# baseline (speedup 1.0000x reference)
; #define NT_LOAD(p) __builtin_nontemporal_load(p)
; __device__ __forceinline__ int opaque_tid() { int t = threadIdx.x; asm volatile("" : "+v"(t)); return t; }
; __device__ __forceinline__ void row_load_bf(const bf16* __restrict__ p, int lane, float (&v)[16]) {
; #pragma unroll
;   for (int i = 0; i < 4; ++i) { u32x2_nt t = NT_LOAD((const u32x2_nt*)p + (lane + 64 * i)); v[i * 4] = bflo(t[0]); v[i * 4 + 1] = bfhi(t[0]); v[i * 4 + 2] = bflo(t[1]); v[i * 4 + 3] = bfhi(t[1]); }
; template <bool WITH_H>
; __device__ void rows_resid(const bf16* __restrict__ Y, const float* __restrict__ xsrc, float* __restrict__ xdst, const float* __restrict__ gpost,
;                            bf16* __restrict__ Hout, const float* __restrict__ gpre, int nrows) {
;   const int tid_ = opaque_tid(); const int lane = tid_ & 63, wid = tid_ >> 6;
;   const int stride = gridDim.x * 8;
;   int r = blockIdx.x * 8 + wid;
;   float y[16], x[16];
;   if (r < nrows) { row_load_bf(Y + (size_t)r * D, lane, y); row_load(xsrc + (size_t)r * D, lane, x); }
;   while (r < nrows) {
;     const int rn = r + stride;
;     float yn[16], xn[16];
;     if (rn < nrows) { row_load_bf(Y + (size_t)rn * D, lane, yn); row_load(xsrc + (size_t)rn * D, lane, xn); }
.LBB0_46:
	s_mov_b32 s100, 0xffff0000
	v_mov_b32_e32 v0, v163
	s_nop 0
	v_ashrrev_i32_e32 v48, 6, v0
	v_add_u32_e32 v64, s88, v48
	v_cmp_gt_i32_e32 vcc, s92, v64
	s_and_saveexec_b64 s[16:17], vcc
	s_cbranch_execz .LBB0_51
	s_load_dwordx2 s[38:39], s[20:21], 0x28
	s_nop 0
	s_load_dwordx2 s[20:21], s[20:21], 0x98
	s_lshl_b32 s40, s2, 12
	v_ashrrev_i32_e32 v65, 31, v64
	v_and_b32_e32 v4, 63, v0
	v_lshlrev_b64 v[0:1], 11, v[64:65]
	s_waitcnt lgkmcnt(0)
	s_add_u32 s22, s20, s40
	s_addc_u32 s23, s21, 0
	s_add_u32 s20, s38, s40
	v_lshlrev_b32_e32 v66, 3, v4
	v_mov_b32_e32 v67, v164
	v_lshl_add_u64 v[68:69], s[18:19], 0, v[0:1]
	s_addc_u32 s21, s39, 0
	v_lshl_add_u64 v[0:1], v[68:69], 0, v[66:67]
	s_mov_b64 s[38:39], 0x9a00000
	v_lshl_add_u64 v[2:3], v[0:1], 0, s[38:39]
	s_mov_b32 s38, 0x9a00000
	v_add_co_u32_e32 v0, vcc, s38, v0
	v_lshlrev_b32_e32 v70, 4, v4
	s_nop 0
	v_addc_co_u32_e32 v1, vcc, 0, v1, vcc
	global_load_dwordx2 v[20:21], v[0:1], off nt
	global_load_dwordx2 v[24:25], v[2:3], off offset:512 nt
	global_load_dwordx2 v[36:37], v[2:3], off offset:1024 nt
	global_load_dwordx2 v[38:39], v[2:3], off offset:1536 nt
	v_lshlrev_b64 v[0:1], 12, v[64:65]
	v_lshl_add_u64 v[0:1], s[4:5], 0, v[0:1]
	v_mov_b32_e32 v71, v164
	v_lshl_add_u64 v[0:1], v[0:1], 0, v[70:71]
	global_load_dwordx4 v[28:31], v[0:1], off nt
	global_load_dwordx4 v[32:35], v[0:1], off offset:1024 nt
	global_load_dwordx4 v[40:43], v[0:1], off offset:2048 nt
	global_load_dwordx4 v[44:47], v[0:1], off offset:3072 nt
	v_lshlrev_b32_e32 v0, 2, v4
	v_xor_b32_e32 v65, 0x80, v0
	v_xor_b32_e32 v110, 64, v0
	v_xor_b32_e32 v111, 32, v0
	v_xor_b32_e32 v112, 16, v0
	v_xor_b32_e32 v113, 8, v0
	v_xor_b32_e32 v114, 4, v0
	global_load_dwordx4 v[0:3], v70, s[22:23]
	global_load_dwordx4 v[4:7], v70, s[22:23] offset:1024
	global_load_dwordx4 v[8:11], v70, s[22:23] offset:2048
	global_load_dwordx4 v[12:15], v70, s[22:23] offset:3072
	global_load_dwordx4 v[16:19], v70, s[20:21]
	s_and_b32 s9, s9, 0xffff
	v_mov_b32_e32 v75, v164
	s_waitcnt vmcnt(12)
	v_lshlrev_b32_e32 v78, 16, v20
	v_and_b32_e32 v79, s100, v20
	v_lshlrev_b32_e32 v84, 16, v21
	s_waitcnt vmcnt(9)
	v_and_b32_e32 v72, s100, v39
	v_lshlrev_b32_e32 v73, 16, v39
	v_and_b32_e32 v85, s100, v21
	v_lshlrev_b32_e32 v80, 16, v24
	v_and_b32_e32 v81, s100, v24
	global_load_dwordx4 v[20:23], v70, s[20:21] offset:1024
	v_lshlrev_b32_e32 v88, 16, v25
	v_and_b32_e32 v89, s100, v25
	v_lshlrev_b32_e32 v86, 16, v36
	v_and_b32_e32 v87, s100, v36
	global_load_dwordx4 v[24:27], v70, s[20:21] offset:2048
	v_lshlrev_b32_e32 v92, 16, v37
	v_and_b32_e32 v93, s100, v37
	v_lshlrev_b32_e32 v90, 16, v38
	v_and_b32_e32 v91, s100, v38
	global_load_dwordx4 v[36:39], v70, s[20:21] offset:3072
	v_readlane_b32 s20, v224, 33
	s_nop 1
	v_lshl_add_u32 v74, v48, 12, s20
	v_readlane_b32 s20, v224, 34
	s_nop 1
	v_add_u32_e32 v48, s20, v48
	v_ashrrev_i32_e32 v49, 31, v48
	v_lshlrev_b64 v[50:51], 11, v[48:49]
	v_lshlrev_b64 v[48:49], 12, v[48:49]
	v_lshl_add_u64 v[76:77], s[18:19], 0, v[50:51]
	v_lshl_add_u64 v[82:83], s[4:5], 0, v[48:49]
	s_mov_b64 s[18:19], 0
	s_branch .LBB0_49

; template <bool WITH_H>
; __device__ void rows_resid(const bf16* __restrict__ Y, const float* __restrict__ xsrc, float* __restrict__ xdst, const float* __restrict__ gpost,
;                            bf16* __restrict__ Hout, const float* __restrict__ gpre, int nrows) {
;     ...
;     const int rn = r + stride;
;     float yn[16], xn[16];
;     if (rn < nrows) { row_load_bf(Y + (size_t)rn * D, lane, yn); row_load(xsrc + (size_t)rn * D, lane, xn); }
.LBB0_49:
	s_mov_b32 s100, 0xffff0000
	v_add_u32_e32 v64, s24, v64
	v_cmp_gt_i32_e32 vcc, s92, v64
	v_cmp_lt_i32_e64 s[4:5], s93, v64
	s_and_saveexec_b64 s[20:21], vcc
	s_cbranch_execz .LBB0_48
	v_lshl_add_u64 v[48:49], v[76:77], 0, v[66:67]
	v_add_co_u32_e32 v48, vcc, 0x9a00000, v48
	v_lshl_add_u64 v[60:61], v[82:83], 0, v[70:71]
	s_nop 0
	v_addc_co_u32_e32 v49, vcc, 0, v49, vcc
	global_load_dwordx2 v[96:97], v[48:49], off nt
	global_load_dwordx2 v[100:101], v[48:49], off offset:512 nt
	global_load_dwordx2 v[102:103], v[48:49], off offset:1024 nt
	global_load_dwordx2 v[116:117], v[48:49], off offset:1536 nt
	s_nop 0
	global_load_dwordx4 v[48:51], v[60:61], off nt
	global_load_dwordx4 v[52:55], v[60:61], off offset:1024 nt
	global_load_dwordx4 v[56:59], v[60:61], off offset:2048 nt
	s_nop 0
	global_load_dwordx4 v[60:63], v[60:61], off offset:3072 nt
	s_waitcnt vmcnt(4)
	v_lshlrev_b32_e32 v108, 16, v116
	v_lshlrev_b32_e32 v94, 16, v96
	v_and_b32_e32 v95, s100, v96
	v_lshlrev_b32_e32 v96, 16, v97
	v_and_b32_e32 v97, s100, v97
	v_lshlrev_b32_e32 v98, 16, v100
	v_and_b32_e32 v99, s100, v100
	v_lshlrev_b32_e32 v100, 16, v101
	v_and_b32_e32 v101, s100, v101
	v_lshlrev_b32_e32 v104, 16, v102
	v_and_b32_e32 v105, s100, v102
	v_lshlrev_b32_e32 v106, 16, v103
	v_and_b32_e32 v107, s100, v103
	v_and_b32_e32 v109, s100, v116
	v_and_b32_e32 v102, s100, v117
	v_lshlrev_b32_e32 v103, 16, v117
	s_branch .LBB0_48

; __device__ __forceinline__ KP opq(KP p) { asm volatile("" : "+s"(p)); return p; }
; __device__ __forceinline__ int opaque_tid() { int t = threadIdx.x; asm volatile("" : "+v"(t)); return t; }
; __device__ __forceinline__ float sigmoidf_(float x) { return __builtin_amdgcn_rcpf(1.f + __expf(-x)); }
; __device__ __forceinline__ void phase4c(KP pp, int l) {
;   KP p = opq(pp);
;   char* ws = p->ws;
;   const h16* LAB = (const h16*)(ws + OFF_LAB);
;   const unsigned char* LA8B = (const unsigned char*)(ws + OFF_LAB);
;   const float* CARRY = (const float*)(ws + OFF_CARRY);
;   const bf16* Z = (const bf16*)(ws + OFF_Z);
;   bf16* MERGED = (bf16*)(ws + OFF_PM);
;   h16x2* hf = (h16x2*)g_shm;
;   const int tid_ = opaque_tid(); const int c2 = tid_ * 2;
;   const float2 lmf = *(const float2*)(p->lru_lambda + (size_t)l * 2048 + c2), lmb = *(const float2*)(p->lru_lambda + (size_t)l * 2048 + 1024 + c2);
;   const float kf0 = -8.f * log1pf(__expf(-lmf.x)) * (1.f / 255.f), kf1 = -8.f * log1pf(__expf(-lmf.y)) * (1.f / 255.f);
;   const float kb0 = -8.f * log1pf(__expf(-lmb.x)) * (1.f / 255.f), kb1 = -8.f * log1pf(__expf(-lmb.y)) * (1.f / 255.f);
.LBB0_53:
	s_mov_b32 s100, 0xbfb8aa3b
	s_mov_b32 s101, 0x3f317218
	s_and_b64 vcc, exec, s[8:9]
	s_cbranch_vccz .LBB0_84
	s_cmp_gt_i32 s25, 5
	s_mov_b64 s[8:9], -1
	s_cbranch_scc0 .LBB0_65
	s_cmp_lt_i32 s25, 7
	s_cbranch_scc0 .LBB0_64
	v_readlane_b32 s4, v225, 2
	v_readlane_b32 s5, v225, 3
	s_mov_b64 s[8:9], s[0:1]
	v_mov_b32_e32 v8, v163
	s_andn2_b64 vcc, exec, s[4:5]
	s_cbranch_vccnz .LBB0_63
	s_load_dwordx2 s[4:5], s[8:9], 0xc0
	v_lshlrev_b32_e32 v0, 1, v8
	s_load_dwordx2 s[8:9], s[8:9], 0x80
	s_lshl_b32 s16, s2, 13
	v_ashrrev_i32_e32 v1, 31, v0
	v_lshlrev_b64 v[2:3], 2, v[0:1]
	s_mov_b32 s17, 0x33800000
	s_waitcnt lgkmcnt(0)
	s_add_u32 s8, s8, s16
	s_addc_u32 s9, s9, 0
	v_lshl_add_u64 v[4:5], s[8:9], 0, v[2:3]
	global_load_dwordx2 v[6:7], v[4:5], off
	v_add_co_u32_e32 v4, vcc, s58, v4
	s_mov_b32 s8, 0x3f2aaaab
	s_nop 0
	v_addc_co_u32_e32 v5, vcc, 0, v5, vcc
	s_mov_b32 s9, 0x3f317218
	s_mov_b32 s16, 0x7f800000
	global_load_dwordx2 v[4:5], v[4:5], off
	v_lshl_add_u64 v[2:3], s[4:5], 0, v[2:3]
	v_lshlrev_b32_e32 v26, 2, v8
	s_waitcnt vmcnt(1)
	v_mul_f32_e32 v6, s100, v6
	v_exp_f32_e32 v6, v6
	s_waitcnt vmcnt(0)
	v_mul_f32_e32 v4, s100, v4
	v_add_f32_e32 v9, 1.0, v6
	v_add_f32_e32 v10, -1.0, v9
	v_sub_f32_e32 v11, v10, v9
	v_add_f32_e32 v11, 1.0, v11
	v_sub_f32_e32 v10, v6, v10
	v_add_f32_e32 v12, v10, v11
	v_frexp_mant_f32_e32 v10, v9
	v_cmp_gt_f32_e32 vcc, s8, v10
	v_cvt_f64_f32_e32 v[10:11], v9
	v_frexp_exp_i32_f64_e32 v10, v[10:11]
	v_subbrev_co_u32_e32 v10, vcc, 0, v10, vcc
	v_sub_u32_e32 v11, 0, v10
	v_ldexp_f32 v9, v9, v11
	v_ldexp_f32 v11, v12, v11
	v_add_f32_e32 v12, -1.0, v9
	v_add_f32_e32 v13, 1.0, v12
	v_sub_f32_e32 v13, v9, v13
	v_add_f32_e32 v13, v11, v13
	v_add_f32_e32 v14, v12, v13
	v_sub_f32_e32 v12, v14, v12
	v_sub_f32_e32 v12, v13, v12
	v_add_f32_e32 v13, 1.0, v9
	v_add_f32_e32 v15, -1.0, v13
	v_sub_f32_e32 v9, v9, v15
	v_add_f32_e32 v9, v11, v9
	v_add_f32_e32 v11, v13, v9
	v_sub_f32_e32 v13, v11, v13
	v_sub_f32_e32 v9, v9, v13
	v_rcp_f32_e32 v13, v11
	v_cvt_f32_i32_e32 v10, v10
	v_cmp_neq_f32_e32 vcc, s16, v6
	v_exp_f32_e32 v4, v4
	v_mul_f32_e32 v15, v14, v13
	v_mul_f32_e32 v16, v11, v15
	v_fma_f32 v17, v15, v11, -v16
	v_fmac_f32_e32 v17, v15, v9
	v_add_f32_e32 v18, v16, v17
	v_sub_f32_e32 v19, v14, v18
	v_sub_f32_e32 v14, v14, v19
	v_sub_f32_e32 v16, v18, v16
	v_sub_f32_e32 v14, v14, v18
	v_add_f32_e32 v12, v12, v14
	v_sub_f32_e32 v14, v16, v17
	v_add_f32_e32 v12, v14, v12
	v_add_f32_e32 v14, v19, v12
	v_mul_f32_e32 v16, v13, v14
	v_mul_f32_e32 v17, v11, v16
	v_fma_f32 v11, v16, v11, -v17
	v_fmac_f32_e32 v11, v16, v9
	v_sub_f32_e32 v9, v19, v14
	v_add_f32_e32 v9, v12, v9
	v_add_f32_e32 v12, v17, v11
	v_sub_f32_e32 v18, v14, v12
	v_sub_f32_e32 v14, v14, v18
	v_sub_f32_e32 v17, v12, v17
	v_sub_f32_e32 v12, v14, v12
	v_add_f32_e32 v9, v9, v12
	v_sub_f32_e32 v11, v17, v11
	v_add_f32_e32 v9, v11, v9
	v_add_f32_e32 v11, v15, v16
	v_add_f32_e32 v9, v18, v9
	v_sub_f32_e32 v12, v11, v15
	v_mul_f32_e32 v9, v13, v9
	v_sub_f32_e32 v12, v16, v12
	v_add_f32_e32 v9, v12, v9
	v_mul_f32_e32 v15, s101, v10
	v_add_f32_e32 v12, v11, v9
	v_fma_f32 v16, v10, s9, -v15
	v_mul_f32_e32 v13, v12, v12
	v_fmac_f32_e32 v16, 0xb102e308, v10
	v_sub_f32_e32 v10, v12, v11
	v_fmamk_f32 v14, v13, 0x3e9b6dac, v185
	v_sub_f32_e32 v9, v9, v10
	v_add_f32_e32 v10, v15, v16
	v_fmaak_f32 v14, v13, v14, 0x3f2aaada
	v_sub_f32_e32 v11, v10, v15
	v_ldexp_f32 v15, v12, 1
	v_mul_f32_e32 v12, v12, v13
	v_mul_f32_e32 v12, v12, v14
	v_add_f32_e32 v13, v15, v12
	v_sub_f32_e32 v14, v13, v15
	v_ldexp_f32 v9, v9, 1
	v_sub_f32_e32 v12, v12, v14
	v_add_f32_e32 v9, v9, v12
	v_add_f32_e32 v12, v13, v9
	v_sub_f32_e32 v13, v12, v13
	v_sub_f32_e32 v9, v9, v13
	v_add_f32_e32 v13, v10, v12
	v_sub_f32_e32 v14, v13, v10
	v_sub_f32_e32 v15, v13, v14
	v_sub_f32_e32 v11, v16, v11
	v_sub_f32_e32 v10, v10, v15
	v_sub_f32_e32 v12, v12, v14
	v_add_f32_e32 v10, v12, v10
	v_add_f32_e32 v12, v11, v9
	v_sub_f32_e32 v14, v12, v11
	v_sub_f32_e32 v15, v12, v14
	v_sub_f32_e32 v11, v11, v15
	v_sub_f32_e32 v9, v9, v14
	v_add_f32_e32 v10, v12, v10
	v_add_f32_e32 v9, v9, v11
	v_add_f32_e32 v11, v13, v10
	v_sub_f32_e32 v12, v11, v13
	v_sub_f32_e32 v10, v10, v12
	v_add_f32_e32 v9, v9, v10
	v_add_f32_e32 v9, v11, v9
	v_cndmask_b32_e32 v9, v187, v9, vcc
	v_cmp_ngt_f32_e32 vcc, -1.0, v6
	s_nop 1
	v_cndmask_b32_e32 v9, v188, v9, vcc
	v_cmp_neq_f32_e32 vcc, -1.0, v6
	s_nop 1
	v_cndmask_b32_e32 v9, v189, v9, vcc
	v_cmp_lt_f32_e64 vcc, |v6|, s17
	s_nop 1
	v_cndmask_b32_e32 v6, v9, v6, vcc
	v_mul_f32_e32 v6, 0xc1000000, v6
	v_mul_f32_e32 v22, 0x3b808081, v6
	v_mul_f32_e32 v6, s100, v7
	v_exp_f32_e32 v6, v6
	s_nop 0
	v_add_f32_e32 v7, 1.0, v6
	v_add_f32_e32 v9, -1.0, v7
	v_sub_f32_e32 v10, v9, v7
	v_add_f32_e32 v10, 1.0, v10
	v_sub_f32_e32 v9, v6, v9
	v_add_f32_e32 v9, v9, v10
	v_frexp_mant_f32_e32 v10, v7
	v_cmp_gt_f32_e32 vcc, s8, v10
	v_cvt_f64_f32_e32 v[10:11], v7
	v_frexp_exp_i32_f64_e32 v10, v[10:11]
	v_subbrev_co_u32_e32 v10, vcc, 0, v10, vcc
	v_sub_u32_e32 v11, 0, v10
	v_ldexp_f32 v7, v7, v11
	v_ldexp_f32 v9, v9, v11
	v_add_f32_e32 v11, -1.0, v7
	v_add_f32_e32 v12, 1.0, v11
	v_sub_f32_e32 v12, v7, v12
	v_add_f32_e32 v12, v9, v12
	v_add_f32_e32 v13, v11, v12
	v_sub_f32_e32 v11, v13, v11
	v_sub_f32_e32 v11, v12, v11
	v_add_f32_e32 v12, 1.0, v7
	v_add_f32_e32 v14, -1.0, v12
	v_sub_f32_e32 v7, v7, v14
	v_add_f32_e32 v7, v9, v7
	v_add_f32_e32 v9, v12, v7
	v_sub_f32_e32 v12, v9, v12
	v_sub_f32_e32 v7, v7, v12
	v_rcp_f32_e32 v12, v9
	v_cvt_f32_i32_e32 v10, v10
	v_cmp_neq_f32_e32 vcc, s16, v6
	v_mul_f32_e32 v14, v13, v12
	v_mul_f32_e32 v15, v9, v14
	v_fma_f32 v16, v14, v9, -v15
	v_fmac_f32_e32 v16, v14, v7
; __device__ __forceinline__ void phase4c(KP pp, int l) {
;     ...
;   const float kf0 = -8.f * log1pf(__expf(-lmf.x)) * (1.f / 255.f), kf1 = -8.f * log1pf(__expf(-lmf.y)) * (1.f / 255.f);
;   const float kb0 = -8.f * log1pf(__expf(-lmb.x)) * (1.f / 255.f), kb1 = -8.f * log1pf(__expf(-lmb.y)) * (1.f / 255.f);
	v_add_f32_e32 v17, v15, v16
	v_sub_f32_e32 v18, v13, v17
	v_sub_f32_e32 v13, v13, v18
	v_sub_f32_e32 v15, v17, v15
	v_sub_f32_e32 v13, v13, v17
	v_add_f32_e32 v11, v11, v13
	v_sub_f32_e32 v13, v15, v16
	v_add_f32_e32 v11, v13, v11
	v_add_f32_e32 v13, v18, v11
	v_mul_f32_e32 v15, v12, v13
	v_mul_f32_e32 v16, v9, v15
	v_fma_f32 v9, v15, v9, -v16
	v_fmac_f32_e32 v9, v15, v7
	v_sub_f32_e32 v7, v18, v13
	v_add_f32_e32 v7, v11, v7
	v_add_f32_e32 v11, v16, v9
	v_sub_f32_e32 v17, v13, v11
	v_sub_f32_e32 v13, v13, v17
	v_sub_f32_e32 v16, v11, v16
	v_sub_f32_e32 v11, v13, v11
	v_add_f32_e32 v7, v7, v11
	v_sub_f32_e32 v9, v16, v9
	v_add_f32_e32 v7, v9, v7
	v_add_f32_e32 v9, v14, v15
	v_add_f32_e32 v7, v17, v7
	v_sub_f32_e32 v11, v9, v14
	v_mul_f32_e32 v7, v12, v7
	v_sub_f32_e32 v11, v15, v11
	v_add_f32_e32 v7, v11, v7
	v_mul_f32_e32 v14, s101, v10
	v_add_f32_e32 v11, v9, v7
	v_fma_f32 v15, v10, s9, -v14
	v_mul_f32_e32 v12, v11, v11
	v_fmac_f32_e32 v15, 0xb102e308, v10
	v_sub_f32_e32 v9, v11, v9
	v_fmamk_f32 v13, v12, 0x3e9b6dac, v185
	v_sub_f32_e32 v7, v7, v9
	v_add_f32_e32 v9, v14, v15
	v_fmaak_f32 v13, v12, v13, 0x3f2aaada
	v_sub_f32_e32 v10, v9, v14
	v_ldexp_f32 v14, v11, 1
	v_mul_f32_e32 v11, v11, v12
	v_mul_f32_e32 v11, v11, v13
	v_add_f32_e32 v12, v14, v11
	v_sub_f32_e32 v13, v12, v14
	v_ldexp_f32 v7, v7, 1
	v_sub_f32_e32 v11, v11, v13
	v_add_f32_e32 v7, v7, v11
	v_add_f32_e32 v11, v12, v7
	v_sub_f32_e32 v12, v11, v12
	v_sub_f32_e32 v7, v7, v12
	v_add_f32_e32 v12, v9, v11
	v_sub_f32_e32 v13, v12, v9
	v_sub_f32_e32 v14, v12, v13
	v_sub_f32_e32 v10, v15, v10
	v_sub_f32_e32 v9, v9, v14
	v_sub_f32_e32 v11, v11, v13
	v_add_f32_e32 v9, v11, v9
	v_add_f32_e32 v11, v10, v7
	v_sub_f32_e32 v13, v11, v10
	v_sub_f32_e32 v14, v11, v13
	v_sub_f32_e32 v10, v10, v14
	v_sub_f32_e32 v7, v7, v13
	v_add_f32_e32 v9, v11, v9
	v_add_f32_e32 v7, v7, v10
	v_add_f32_e32 v10, v12, v9
	v_sub_f32_e32 v11, v10, v12
	v_sub_f32_e32 v9, v9, v11
	v_add_f32_e32 v7, v7, v9
	v_add_f32_e32 v7, v10, v7
	v_cndmask_b32_e32 v7, v187, v7, vcc
	v_cmp_ngt_f32_e32 vcc, -1.0, v6
	v_add_f32_e32 v9, 1.0, v4
	s_nop 0
	v_cndmask_b32_e32 v7, v188, v7, vcc
	v_cmp_neq_f32_e32 vcc, -1.0, v6
	s_nop 1
	v_cndmask_b32_e32 v7, v189, v7, vcc
	v_cmp_lt_f32_e64 vcc, |v6|, s17
	s_nop 1
	v_cndmask_b32_e32 v6, v7, v6, vcc
	v_mul_f32_e32 v6, 0xc1000000, v6
	v_mul_f32_e32 v23, 0x3b808081, v6
	v_add_f32_e32 v6, -1.0, v9
	v_sub_f32_e32 v7, v6, v9
	v_add_f32_e32 v7, 1.0, v7
	v_sub_f32_e32 v6, v4, v6
	v_add_f32_e32 v10, v6, v7
	v_frexp_mant_f32_e32 v6, v9
	v_cmp_gt_f32_e32 vcc, s8, v6
	v_cvt_f64_f32_e32 v[6:7], v9
	v_frexp_exp_i32_f64_e32 v6, v[6:7]
	v_subbrev_co_u32_e32 v6, vcc, 0, v6, vcc
	v_sub_u32_e32 v7, 0, v6
	v_ldexp_f32 v9, v9, v7
	v_ldexp_f32 v7, v10, v7
	v_add_f32_e32 v10, -1.0, v9
	v_add_f32_e32 v11, 1.0, v10
	v_sub_f32_e32 v11, v9, v11
	v_add_f32_e32 v11, v7, v11
	v_add_f32_e32 v12, v10, v11
	v_sub_f32_e32 v10, v12, v10
	v_sub_f32_e32 v10, v11, v10
	v_add_f32_e32 v11, 1.0, v9
	v_add_f32_e32 v13, -1.0, v11
	v_sub_f32_e32 v9, v9, v13
	v_add_f32_e32 v7, v7, v9
	v_add_f32_e32 v9, v11, v7
	v_sub_f32_e32 v11, v9, v11
	v_sub_f32_e32 v7, v7, v11
	v_rcp_f32_e32 v11, v9
	v_cvt_f32_i32_e32 v6, v6
	v_cmp_neq_f32_e32 vcc, s16, v4
	v_mul_f32_e32 v13, v12, v11
	v_mul_f32_e32 v14, v9, v13
	v_fma_f32 v15, v13, v9, -v14
	v_fmac_f32_e32 v15, v13, v7
	v_add_f32_e32 v16, v14, v15
	v_sub_f32_e32 v17, v12, v16
	v_sub_f32_e32 v12, v12, v17
	v_sub_f32_e32 v14, v16, v14
	v_sub_f32_e32 v12, v12, v16
	v_add_f32_e32 v10, v10, v12
	v_sub_f32_e32 v12, v14, v15
	v_add_f32_e32 v10, v12, v10
	v_add_f32_e32 v12, v17, v10
	v_mul_f32_e32 v14, v11, v12
	v_mul_f32_e32 v15, v9, v14
	v_fma_f32 v9, v14, v9, -v15
	v_fmac_f32_e32 v9, v14, v7
	v_sub_f32_e32 v7, v17, v12
	v_add_f32_e32 v7, v10, v7
	v_add_f32_e32 v10, v15, v9
	v_sub_f32_e32 v16, v12, v10
	v_sub_f32_e32 v12, v12, v16
	v_sub_f32_e32 v15, v10, v15
	v_sub_f32_e32 v10, v12, v10
	v_add_f32_e32 v7, v7, v10
	v_sub_f32_e32 v9, v15, v9
	v_add_f32_e32 v7, v9, v7
	v_add_f32_e32 v9, v13, v14
	v_add_f32_e32 v7, v16, v7
	v_sub_f32_e32 v10, v9, v13
	v_mul_f32_e32 v7, v11, v7
	v_sub_f32_e32 v10, v14, v10
	v_add_f32_e32 v7, v10, v7
	v_mul_f32_e32 v13, s101, v6
	v_add_f32_e32 v10, v9, v7
	v_fma_f32 v14, v6, s9, -v13
	v_mul_f32_e32 v11, v10, v10
	v_fmac_f32_e32 v14, 0xb102e308, v6
	v_sub_f32_e32 v6, v10, v9
	v_fmamk_f32 v12, v11, 0x3e9b6dac, v185
	v_sub_f32_e32 v6, v7, v6
	v_add_f32_e32 v7, v13, v14
	v_fmaak_f32 v12, v11, v12, 0x3f2aaada
	v_sub_f32_e32 v9, v7, v13
	v_ldexp_f32 v13, v10, 1
	v_mul_f32_e32 v10, v10, v11
; __device__ __forceinline__ void phase4c(KP pp, int l) {
;     ...
;   const float kb0 = -8.f * log1pf(__expf(-lmb.x)) * (1.f / 255.f), kb1 = -8.f * log1pf(__expf(-lmb.y)) * (1.f / 255.f);
;   for (int seg = blockIdx.x; seg < 256; seg += gridDim.x) {
;     size_t base = (size_t)seg * 64 * D + c2;
;     { const unsigned char* LA = LA8B + base; const h16* Bv = LAB + (size_t)CT * D + base;
;       float2 cr = *(const float2*)(CARRY + (size_t)seg * D + c2); float h0 = cr.x, h1 = cr.y;
	v_mul_f32_e32 v10, v10, v12
	v_add_f32_e32 v11, v13, v10
	v_sub_f32_e32 v12, v11, v13
	v_ldexp_f32 v6, v6, 1
	v_sub_f32_e32 v10, v10, v12
	v_add_f32_e32 v6, v6, v10
	v_add_f32_e32 v10, v11, v6
	v_sub_f32_e32 v11, v10, v11
	v_sub_f32_e32 v6, v6, v11
	v_add_f32_e32 v11, v7, v10
	v_sub_f32_e32 v12, v11, v7
	v_sub_f32_e32 v13, v11, v12
	v_sub_f32_e32 v9, v14, v9
	v_sub_f32_e32 v7, v7, v13
	v_sub_f32_e32 v10, v10, v12
	v_add_f32_e32 v7, v10, v7
	v_add_f32_e32 v10, v9, v6
	v_sub_f32_e32 v12, v10, v9
	v_sub_f32_e32 v13, v10, v12
	v_sub_f32_e32 v9, v9, v13
	v_sub_f32_e32 v6, v6, v12
	v_add_f32_e32 v7, v10, v7
	v_add_f32_e32 v6, v6, v9
	v_add_f32_e32 v9, v11, v7
	v_sub_f32_e32 v10, v9, v11
	v_sub_f32_e32 v7, v7, v10
	v_add_f32_e32 v6, v6, v7
	v_add_f32_e32 v6, v9, v6
	v_cndmask_b32_e32 v6, v187, v6, vcc
	v_cmp_ngt_f32_e32 vcc, -1.0, v4
	s_nop 1
	v_cndmask_b32_e32 v6, v188, v6, vcc
	v_cmp_neq_f32_e32 vcc, -1.0, v4
	s_nop 1
	v_cndmask_b32_e32 v6, v189, v6, vcc
	v_cmp_lt_f32_e64 vcc, |v4|, s17
	s_nop 1
	v_cndmask_b32_e32 v4, v6, v4, vcc
	v_mul_f32_e32 v4, 0xc1000000, v4
	v_mul_f32_e32 v24, 0x3b808081, v4
	v_mul_f32_e32 v4, s100, v5
	v_exp_f32_e32 v6, v4
	s_nop 0
	v_add_f32_e32 v7, 1.0, v6
	v_add_f32_e32 v4, -1.0, v7
	v_sub_f32_e32 v5, v4, v7
	v_add_f32_e32 v5, 1.0, v5
	v_sub_f32_e32 v4, v6, v4
	v_add_f32_e32 v9, v4, v5
	v_frexp_mant_f32_e32 v4, v7
	v_cmp_gt_f32_e32 vcc, s8, v4
	v_cvt_f64_f32_e32 v[4:5], v7
	v_frexp_exp_i32_f64_e32 v4, v[4:5]
	v_subbrev_co_u32_e32 v4, vcc, 0, v4, vcc
	v_sub_u32_e32 v5, 0, v4
	v_ldexp_f32 v7, v7, v5
	v_ldexp_f32 v5, v9, v5
	v_add_f32_e32 v9, -1.0, v7
	v_add_f32_e32 v10, 1.0, v9
	v_sub_f32_e32 v10, v7, v10
	v_add_f32_e32 v10, v5, v10
	v_add_f32_e32 v11, v9, v10
	v_sub_f32_e32 v9, v11, v9
	v_sub_f32_e32 v9, v10, v9
	v_add_f32_e32 v10, 1.0, v7
	v_add_f32_e32 v12, -1.0, v10
	v_sub_f32_e32 v7, v7, v12
	v_add_f32_e32 v5, v5, v7
	v_add_f32_e32 v7, v10, v5
	v_sub_f32_e32 v10, v7, v10
	v_sub_f32_e32 v5, v5, v10
	v_rcp_f32_e32 v10, v7
	v_cvt_f32_i32_e32 v4, v4
	v_cmp_neq_f32_e32 vcc, s16, v6
	v_mul_f32_e32 v12, v11, v10
	v_mul_f32_e32 v13, v7, v12
	v_fma_f32 v14, v12, v7, -v13
	v_fmac_f32_e32 v14, v12, v5
	v_add_f32_e32 v15, v13, v14
	v_sub_f32_e32 v16, v11, v15
	v_sub_f32_e32 v11, v11, v16
	v_sub_f32_e32 v13, v15, v13
	v_sub_f32_e32 v11, v11, v15
	v_add_f32_e32 v9, v9, v11
	v_sub_f32_e32 v11, v13, v14
	v_add_f32_e32 v9, v11, v9
	v_add_f32_e32 v11, v16, v9
	v_mul_f32_e32 v13, v10, v11
	v_mul_f32_e32 v14, v7, v13
	v_fma_f32 v7, v13, v7, -v14
	v_fmac_f32_e32 v7, v13, v5
	v_sub_f32_e32 v5, v16, v11
	v_add_f32_e32 v5, v9, v5
	v_add_f32_e32 v9, v14, v7
	v_sub_f32_e32 v15, v11, v9
	v_sub_f32_e32 v11, v11, v15
	v_sub_f32_e32 v14, v9, v14
	v_sub_f32_e32 v9, v11, v9
	v_add_f32_e32 v5, v5, v9
	v_sub_f32_e32 v7, v14, v7
	v_add_f32_e32 v5, v7, v5
	v_add_f32_e32 v7, v12, v13
	v_add_f32_e32 v5, v15, v5
	v_sub_f32_e32 v9, v7, v12
	v_mul_f32_e32 v5, v10, v5
	v_sub_f32_e32 v9, v13, v9
	v_add_f32_e32 v5, v9, v5
	v_mul_f32_e32 v12, s101, v4
	v_add_f32_e32 v9, v7, v5
	v_fma_f32 v13, v4, s9, -v12
	v_mul_f32_e32 v10, v9, v9
	v_fmac_f32_e32 v13, 0xb102e308, v4
	v_sub_f32_e32 v4, v9, v7
	v_fmamk_f32 v11, v10, 0x3e9b6dac, v185
	v_sub_f32_e32 v4, v5, v4
	v_add_f32_e32 v5, v12, v13
	v_fmaak_f32 v11, v10, v11, 0x3f2aaada
	v_sub_f32_e32 v7, v5, v12
	v_ldexp_f32 v12, v9, 1
	v_mul_f32_e32 v9, v9, v10
	v_mul_f32_e32 v9, v9, v11
	v_add_f32_e32 v10, v12, v9
	v_sub_f32_e32 v11, v10, v12
	v_ldexp_f32 v4, v4, 1
	v_sub_f32_e32 v9, v9, v11
	v_add_f32_e32 v4, v4, v9
	v_add_f32_e32 v9, v10, v4
	v_sub_f32_e32 v10, v9, v10
	v_sub_f32_e32 v4, v4, v10
	v_add_f32_e32 v10, v5, v9
	v_sub_f32_e32 v11, v10, v5
	v_sub_f32_e32 v12, v10, v11
	v_sub_f32_e32 v7, v13, v7
	v_sub_f32_e32 v5, v5, v12
	v_sub_f32_e32 v9, v9, v11
	v_add_f32_e32 v5, v9, v5
	v_add_f32_e32 v9, v7, v4
	v_sub_f32_e32 v11, v9, v7
	v_sub_f32_e32 v12, v9, v11
	v_sub_f32_e32 v7, v7, v12
	v_sub_f32_e32 v4, v4, v11
	v_add_f32_e32 v5, v9, v5
	v_add_f32_e32 v4, v4, v7
	v_add_f32_e32 v7, v10, v5
	v_sub_f32_e32 v9, v7, v10
	v_sub_f32_e32 v5, v5, v9
	v_add_f32_e32 v4, v4, v5
	v_add_f32_e32 v4, v7, v4
	v_cndmask_b32_e32 v4, v187, v4, vcc
	v_cmp_ngt_f32_e32 vcc, -1.0, v6
	s_mov_b64 s[8:9], 0x3800000
	v_lshl_add_u64 v[2:3], v[2:3], 0, s[8:9]
	v_cndmask_b32_e32 v4, v188, v4, vcc
	v_cmp_neq_f32_e32 vcc, -1.0, v6
	s_mov_b32 s8, s94
	s_nop 0
	v_cndmask_b32_e32 v4, v189, v4, vcc
	v_cmp_lt_f32_e64 vcc, |v6|, s17
	s_nop 1
	v_cndmask_b32_e32 v4, v4, v6, vcc
	v_mul_f32_e32 v4, 0xc1000000, v4
	v_mul_f32_e32 v25, 0x3b808081, v4
	v_lshlrev_b64 v[4:5], 1, v[0:1]

; __device__ __forceinline__ KP opq(KP p) { asm volatile("" : "+s"(p)); return p; }
; __device__ __forceinline__ int opaque_tid() { int t = threadIdx.x; asm volatile("" : "+v"(t)); return t; }
; template <int G>
; __device__ __forceinline__ void carry_items(const float* __restrict__ AGGA, const float* __restrict__ AGGH, float* __restrict__ CARRY, int nseq, int tid) {
;   const int sps = 16 * G;
;   float2* ex = (float2*)g_shm;
;   const int chl = tid & 31, grp = tid >> 5;
;   for (int it = blockIdx.x; it < 2 * nseq * 32; it += gridDim.x) {
;     const int slab = it & 31, sq = (it >> 5) % nseq, dir = it / (32 * nseq);
;     const int ch = slab * 32 + chl;
;     float a[G], h[G];
; #pragma unroll
;     for (int i = 0; i < G; ++i) { int pos = grp * G + i; int s = dir ? sps - 1 - pos : pos;
;       size_t o = (size_t)(dir * 256 + sq * sps + s) * D + ch; a[i] = AGGA[o]; h[i] = AGGH[o]; }
; __device__ __forceinline__ void phase4b(KP pp, int c) {
;   KP p = opq(pp);
;   char* ws = p->ws;
;   const float* AGGA = (const float*)(ws + OFF_AGGA); const float* AGGH = (const float*)(ws + OFF_AGGH);
;   float* CARRY = (float*)(ws + OFF_CARRY);
;   const int tid_ = opaque_tid();
;   if (c < 2) carry_items<4>(AGGA, AGGH, CARRY, 4, tid_); else carry_items<16>(AGGA, AGGH, CARRY, 1, tid_);
.LBB0_65:
	s_mov_b32 s100, 0xff
	s_and_b64 vcc, exec, s[8:9]
	s_cbranch_vccz .LBB0_84
	s_mov_b64 s[4:5], s[0:1]
	s_load_dwordx2 s[4:5], s[4:5], 0xc0
	v_mov_b32_e32 v74, v163
	s_waitcnt lgkmcnt(0)
	s_add_u32 s8, s4, 0x3400000
	s_addc_u32 s9, s5, 0
	s_add_u32 s16, s4, 0x3600000
	s_addc_u32 s17, s5, 0
	s_add_u32 s18, s4, 0x3800000
	s_addc_u32 s19, s5, 0
	v_and_b32_e32 v72, 31, v74
	s_cmp_gt_u32 s84, 1
	v_ashrrev_i32_e32 v73, 5, v74
	s_mov_b64 s[4:5], -1
	s_cbranch_scc0 .LBB0_75
	v_readlane_b32 s4, v225, 4
	v_readlane_b32 s5, v225, 5
	s_andn2_b64 vcc, exec, s[4:5]
	s_cbranch_vccnz .LBB0_74
	v_lshlrev_b32_e32 v75, 4, v73
	v_or_b32_e32 v79, 1, v75
	v_or_b32_e32 v81, 2, v75
	v_or_b32_e32 v83, 3, v75
	v_or_b32_e32 v85, 4, v75
	v_or_b32_e32 v87, 5, v75
	v_or_b32_e32 v89, 6, v75
	v_or_b32_e32 v91, 7, v75
	v_or_b32_e32 v93, 8, v75
	v_or_b32_e32 v95, 9, v75
	v_or_b32_e32 v97, 10, v75
	v_or_b32_e32 v99, 11, v75
	v_or_b32_e32 v101, 12, v75
	v_or_b32_e32 v103, 13, v75
	v_or_b32_e32 v105, 14, v75
	v_or_b32_e32 v107, 15, v75
	v_lshlrev_b32_e32 v76, 3, v74
	v_lshlrev_b32_e32 v77, 3, v72
	v_cmp_lt_i32_e32 vcc, 0, v73
	v_sub_u32_e32 v78, s100, v75
	v_sub_u32_e32 v80, s100, v79
	v_sub_u32_e32 v82, s100, v81
	v_sub_u32_e32 v84, s100, v83
	v_sub_u32_e32 v86, s100, v85
	v_sub_u32_e32 v88, s100, v87
	v_sub_u32_e32 v90, s100, v89
	v_sub_u32_e32 v92, s100, v91
	v_sub_u32_e32 v94, s100, v93
	v_sub_u32_e32 v96, s100, v95
	v_sub_u32_e32 v98, s100, v97
	v_sub_u32_e32 v100, s100, v99
	v_sub_u32_e32 v102, s100, v101
	v_sub_u32_e32 v104, s100, v103
	v_sub_u32_e32 v106, s100, v105
	v_sub_u32_e32 v108, s100, v107
	s_mov_b32 s38, s94
	s_branch .LBB0_71

; __device__ __forceinline__ void phase2(KP pp, int l, int c) {
;     ...
;         if (tt > 0) {
;           uint4 ue = *(const uint4*)(lbase + (tl + 8 + h - 1) * RS), ul = *(const uint4*)(lbase + (tl + 8 - h - 1) * RS);
;           s[0] += bflo(ue.x) - bflo(ul.x); s[1] += bfhi(ue.x) - bfhi(ul.x); s[2] += bflo(ue.y) - bflo(ul.y); s[3] += bfhi(ue.y) - bfhi(ul.y);
;           s[4] += bflo(ue.z) - bflo(ul.z); s[5] += bfhi(ue.z) - bfhi(ul.z); s[6] += bflo(ue.w) - bflo(ul.w); s[7] += bfhi(ue.w) - bfhi(ul.w);
;         }
.LBB0_153:
	s_mov_b32 s100, 0xffff0000
	s_cmp_eq_u32 s4, 0
	v_add_u32_e32 v44, v48, v100
	v_add_u32_e32 v51, v49, v100
	s_cbranch_scc1 .LBB0_152
	ds_read_b128 v[52:55], v44
	ds_read_b128 v[56:59], v51
	s_waitcnt lgkmcnt(1)
	v_lshlrev_b32_e32 v61, 16, v52
	s_waitcnt lgkmcnt(0)
	v_lshlrev_b32_e32 v63, 16, v56
	v_and_b32_e32 v60, s100, v52
	v_and_b32_e32 v62, s100, v56
	v_pk_add_f32 v[60:61], v[60:61], v[62:63] neg_lo:[0,1] neg_hi:[0,1]
	v_lshlrev_b32_e32 v63, 16, v57
	v_pk_add_f32 v[42:43], v[42:43], v[60:61]
	v_lshlrev_b32_e32 v61, 16, v53
	v_and_b32_e32 v60, s100, v53
	v_and_b32_e32 v62, s100, v57
	v_pk_add_f32 v[52:53], v[60:61], v[62:63] neg_lo:[0,1] neg_hi:[0,1]
	v_lshlrev_b32_e32 v57, 16, v58
	v_pk_add_f32 v[40:41], v[40:41], v[52:53]
	v_lshlrev_b32_e32 v53, 16, v54
	v_and_b32_e32 v52, s100, v54
	v_and_b32_e32 v56, s100, v58
	v_pk_add_f32 v[52:53], v[52:53], v[56:57] neg_lo:[0,1] neg_hi:[0,1]
	v_lshlrev_b32_e32 v57, 16, v59
	v_pk_add_f32 v[38:39], v[38:39], v[52:53]
	v_lshlrev_b32_e32 v53, 16, v55
	v_and_b32_e32 v52, s100, v55
	v_and_b32_e32 v56, s100, v59
	v_pk_add_f32 v[52:53], v[52:53], v[56:57] neg_lo:[0,1] neg_hi:[0,1]
	s_nop 0
	v_pk_add_f32 v[36:37], v[36:37], v[52:53]
	s_branch .LBB0_152

; __device__ __forceinline__ KP opq(KP p) { asm volatile("" : "+s"(p)); return p; }
; __device__ __forceinline__ int opaque_tid() { int t = threadIdx.x; asm volatile("" : "+v"(t)); return t; }
; template <bool WITH_H>
; __device__ void rows_resid(const bf16* __restrict__ Y, const float* __restrict__ xsrc, float* __restrict__ xdst, const float* __restrict__ gpost,
;                            bf16* __restrict__ Hout, const float* __restrict__ gpre, int nrows) {
;   const int tid_ = opaque_tid(); const int lane = tid_ & 63, wid = tid_ >> 6;
;   const int stride = gridDim.x * 8;
;   int r = blockIdx.x * 8 + wid;
;   float y[16], x[16];
;   if (r < nrows) { row_load_bf(Y + (size_t)r * D, lane, y); row_load(xsrc + (size_t)r * D, lane, x); }
; __device__ __forceinline__ void phase_resid(KP pp, int pl, int pc) {
;   KP p = opq(pp);
;   float* pxo = p->out + (size_t)pc * CT * D;
;   rows_resid<false>((const bf16*)(p->ws + OFF_LAB), pxo, pxo, p->norm_mlp_post + pl * D, nullptr, nullptr, CT);
; }
.LBB0_172:
	s_mov_b32 s100, 0xffff0000
	s_cmp_eq_u32 s25, 0
	s_mov_b64 s[62:63], -1
	s_cbranch_scc0 .LBB0_266
	s_cmp_lt_u32 s7, 40
	s_cselect_b64 s[60:61], -1, 0
	s_and_b64 vcc, exec, s[60:61]
	s_cbranch_vccnz .LBB0_180
	s_mov_b64 s[4:5], s[0:1]
	s_waitcnt vmcnt(0)
	v_mov_b32_e32 v0, v163
	s_nop 0
	v_ashrrev_i32_e32 v32, 6, v0
	v_add_u32_e32 v48, s88, v32
	v_cmp_gt_i32_e32 vcc, s92, v48
	s_and_saveexec_b64 s[22:23], vcc
	s_cbranch_execz .LBB0_179
	s_load_dwordx4 s[16:19], s[4:5], 0xb8
	s_nop 0
	s_load_dwordx2 s[4:5], s[4:5], 0xa0
	v_ashrrev_i32_e32 v49, 31, v48
	v_and_b32_e32 v33, 63, v0
	v_lshlrev_b64 v[0:1], 11, v[48:49]
	s_waitcnt lgkmcnt(0)
	v_lshl_add_u64 v[0:1], s[18:19], 0, v[0:1]
	v_lshlrev_b32_e32 v34, 3, v33
	v_mov_b32_e32 v35, v164
	v_lshl_add_u64 v[0:1], v[0:1], 0, v[34:35]
	s_mov_b64 s[8:9], 0x9a00000
	v_lshl_add_u64 v[2:3], v[0:1], 0, s[8:9]
	s_mov_b32 s8, 0x9a00000
	v_add_co_u32_e32 v0, vcc, s8, v0
	s_lshl_b32 s8, s2, 12
	s_add_u32 s4, s4, s8
	s_addc_u32 s5, s5, 0
	v_addc_co_u32_e32 v1, vcc, 0, v1, vcc
	s_add_u32 s8, s16, 0xc000000
	global_load_dwordx2 v[36:37], v[0:1], off nt
	global_load_dwordx2 v[38:39], v[2:3], off offset:512 nt
	global_load_dwordx2 v[40:41], v[2:3], off offset:1536 nt
	global_load_dwordx2 v[42:43], v[2:3], off offset:1024 nt
	s_addc_u32 s9, s17, 0
	v_lshlrev_b64 v[0:1], 12, v[48:49]
	v_lshl_add_u64 v[0:1], s[8:9], 0, v[0:1]
	v_lshlrev_b32_e32 v50, 4, v33
	v_mov_b32_e32 v51, v164
	v_lshl_add_u64 v[28:29], v[0:1], 0, v[50:51]
	global_load_dwordx4 v[4:7], v[28:29], off nt
	global_load_dwordx4 v[12:15], v[28:29], off offset:1024 nt
	global_load_dwordx4 v[0:3], v50, s[4:5] offset:-4096
	global_load_dwordx4 v[8:11], v50, s[4:5] offset:-3072
	global_load_dwordx4 v[16:19], v50, s[4:5] offset:-2048
	global_load_dwordx4 v[20:23], v50, s[4:5] offset:-1024
	global_load_dwordx4 v[24:27], v[28:29], off offset:2048 nt
	s_nop 0
	global_load_dwordx4 v[28:31], v[28:29], off offset:3072 nt
	v_readlane_b32 s4, v224, 33
	v_lshlrev_b32_e32 v35, 2, v33
	v_mov_b32_e32 v53, v164
	v_lshl_add_u32 v52, v32, 12, s4
	v_readlane_b32 s4, v224, 34
	v_xor_b32_e32 v49, 0x80, v35
	v_xor_b32_e32 v90, 64, v35
	v_add_u32_e32 v32, s4, v32
	v_ashrrev_i32_e32 v33, 31, v32
	v_lshlrev_b64 v[44:45], 12, v[32:33]
	v_lshlrev_b64 v[32:33], 11, v[32:33]
	v_or_b32_e32 v32, v32, v34
	v_lshl_add_u64 v[32:33], s[18:19], 0, v[32:33]
	s_mov_b64 s[4:5], 0x9a00600
	v_xor_b32_e32 v91, 32, v35
	v_xor_b32_e32 v92, 16, v35
	v_xor_b32_e32 v93, 8, v35
	v_xor_b32_e32 v94, 4, v35
	v_lshl_add_u64 v[54:55], s[16:17], 0, v[44:45]
	s_and_b32 s9, s9, 0xffff
	v_lshl_add_u64 v[58:59], v[32:33], 0, s[4:5]
	s_mov_b64 s[16:17], 0
	s_waitcnt vmcnt(11)
	v_lshlrev_b32_e32 v70, 16, v36
	v_and_b32_e32 v71, s100, v36
	s_waitcnt vmcnt(9)
	v_and_b32_e32 v56, s100, v41
	v_lshlrev_b32_e32 v57, 16, v41
	v_lshlrev_b32_e32 v72, 16, v37
	v_and_b32_e32 v73, s100, v37
	v_lshlrev_b32_e32 v66, 16, v38
	v_and_b32_e32 v67, s100, v38
	v_lshlrev_b32_e32 v68, 16, v39
	v_and_b32_e32 v69, s100, v39
	s_waitcnt vmcnt(8)
	v_lshlrev_b32_e32 v62, 16, v42
	v_and_b32_e32 v63, s100, v42
	v_lshlrev_b32_e32 v64, 16, v43
	v_and_b32_e32 v65, s100, v43
	v_lshlrev_b32_e32 v60, 16, v40
	v_and_b32_e32 v61, s100, v40
	s_branch .LBB0_177

; template <bool WITH_H>
; __device__ void rows_resid(const bf16* __restrict__ Y, const float* __restrict__ xsrc, float* __restrict__ xdst, const float* __restrict__ gpost,
;                            bf16* __restrict__ Hout, const float* __restrict__ gpre, int nrows) {
;     ...
;     const int rn = r + stride;
;     float yn[16], xn[16];
;     if (rn < nrows) { row_load_bf(Y + (size_t)rn * D, lane, yn); row_load(xsrc + (size_t)rn * D, lane, xn); }
.LBB0_177:
	s_mov_b32 s100, 0xffff0000
	v_add_u32_e32 v48, s24, v48
	v_cmp_gt_i32_e64 s[4:5], s92, v48
	v_cmp_lt_i32_e32 vcc, s93, v48
	s_and_saveexec_b64 s[18:19], s[4:5]
	s_cbranch_execz .LBB0_176
	v_lshl_add_u64 v[32:33], v[54:55], 0, v[50:51]
	s_brev_b32 s4, 48
	v_add_co_u32_e64 v44, s[4:5], s4, v32
	global_load_dwordx2 v[76:77], v[58:59], off offset:-1536 nt
	global_load_dwordx2 v[80:81], v[58:59], off offset:-1024 nt
	global_load_dwordx2 v[82:83], v[58:59], off offset:-512 nt
	global_load_dwordx2 v[96:97], v[58:59], off nt
	v_addc_co_u32_e64 v45, s[4:5], 0, v33, s[4:5]
	global_load_dwordx4 v[32:35], v[44:45], off nt
	global_load_dwordx4 v[36:39], v[44:45], off offset:1024 nt
	global_load_dwordx4 v[40:43], v[44:45], off offset:2048 nt
	s_nop 0
	global_load_dwordx4 v[44:47], v[44:45], off offset:3072 nt
	s_waitcnt vmcnt(7)
	v_lshlrev_b32_e32 v74, 16, v76
	v_and_b32_e32 v75, s100, v76
	v_lshlrev_b32_e32 v76, 16, v77
	v_and_b32_e32 v77, s100, v77
	s_waitcnt vmcnt(6)
	v_lshlrev_b32_e32 v78, 16, v80
	v_and_b32_e32 v79, s100, v80
	v_lshlrev_b32_e32 v80, 16, v81
	v_and_b32_e32 v81, s100, v81
	s_waitcnt vmcnt(5)
	v_lshlrev_b32_e32 v84, 16, v82
	v_and_b32_e32 v85, s100, v82
	v_lshlrev_b32_e32 v86, 16, v83
	v_and_b32_e32 v87, s100, v83
	s_waitcnt vmcnt(4)
	v_lshlrev_b32_e32 v88, 16, v96
	v_and_b32_e32 v89, s100, v96
	v_and_b32_e32 v82, s100, v97
	v_lshlrev_b32_e32 v83, 16, v97
	s_branch .LBB0_176

; __device__ __forceinline__ KP opq(KP p) { asm volatile("" : "+s"(p)); return p; }
; __device__ __forceinline__ int opaque_tid() { int t = threadIdx.x; asm volatile("" : "+v"(t)); return t; }
; template <bool WITH_H>
; __device__ void rows_resid(const bf16* __restrict__ Y, const float* __restrict__ xsrc, float* __restrict__ xdst, const float* __restrict__ gpost,
;                            bf16* __restrict__ Hout, const float* __restrict__ gpre, int nrows) {
;   const int tid_ = opaque_tid(); const int lane = tid_ & 63, wid = tid_ >> 6;
;   const int stride = gridDim.x * 8;
;   int r = blockIdx.x * 8 + wid;
;   float y[16], x[16];
;   if (r < nrows) { row_load_bf(Y + (size_t)r * D, lane, y); row_load(xsrc + (size_t)r * D, lane, x); }
; __device__ __forceinline__ void phase_resid(KP pp, int pl, int pc) {
;   KP p = opq(pp);
;   float* pxo = p->out + (size_t)pc * CT * D;
;   rows_resid<false>((const bf16*)(p->ws + OFF_LAB), pxo, pxo, p->norm_mlp_post + pl * D, nullptr, nullptr, CT);
; }
.LBB0_321:
	s_mov_b32 s100, 0xffff0000
	s_cmp_lg_u32 s25, 2
	s_cselect_b64 s[4:5], -1, 0
	s_xor_b64 s[8:9], s[36:37], -1
	s_or_b64 s[4:5], s[8:9], s[4:5]
	s_and_b64 vcc, exec, s[4:5]
	s_cbranch_vccnz .LBB0_328
	s_mov_b64 s[4:5], s[0:1]
	s_waitcnt vmcnt(0)
	v_mov_b32_e32 v0, v163
	s_nop 0
	v_ashrrev_i32_e32 v32, 6, v0
	v_add_u32_e32 v48, s88, v32
	v_cmp_gt_i32_e32 vcc, s92, v48
	s_and_saveexec_b64 s[22:23], vcc
	s_cbranch_execz .LBB0_327
	s_load_dwordx2 s[8:9], s[4:5], 0xa0
	s_load_dwordx4 s[16:19], s[4:5], 0xb8
	v_ashrrev_i32_e32 v49, 31, v48
	s_mul_hi_u32 s4, s7, 0xcccccccd
	v_and_b32_e32 v33, 63, v0
	v_lshlrev_b64 v[0:1], 11, v[48:49]
	s_lshl_b32 s4, s4, 23
	s_waitcnt lgkmcnt(0)
	v_lshl_add_u64 v[0:1], s[18:19], 0, v[0:1]
	v_lshlrev_b32_e32 v34, 3, v33
	v_mov_b32_e32 v35, v164
	s_and_b32 s36, s4, 0xc000000
	v_lshl_add_u64 v[0:1], v[0:1], 0, v[34:35]
	s_mov_b64 s[4:5], 0x9a00000
	v_lshl_add_u64 v[2:3], v[0:1], 0, s[4:5]
	s_mov_b32 s4, 0x9a00000
	v_add_co_u32_e32 v0, vcc, s4, v0
	s_lshl_b32 s4, s2, 12
	s_add_u32 s4, s8, s4
	s_addc_u32 s5, s9, 0
	s_lshl_b32 s8, s84, 26
	s_add_u32 s8, s16, s8
	s_addc_u32 s9, s17, 0
	v_addc_co_u32_e32 v1, vcc, 0, v1, vcc
	s_add_u32 s8, s8, 0xfc000000
	global_load_dwordx2 v[36:37], v[0:1], off nt
	global_load_dwordx2 v[38:39], v[2:3], off offset:512 nt
	global_load_dwordx2 v[40:41], v[2:3], off offset:1024 nt
	global_load_dwordx2 v[42:43], v[2:3], off offset:1536 nt
	s_addc_u32 s9, s9, -1
	v_lshlrev_b64 v[0:1], 12, v[48:49]
	v_lshl_add_u64 v[0:1], s[8:9], 0, v[0:1]
	v_lshlrev_b32_e32 v50, 4, v33
	v_mov_b32_e32 v51, v164
	v_lshl_add_u64 v[28:29], v[0:1], 0, v[50:51]
	global_load_dwordx4 v[4:7], v[28:29], off nt
	global_load_dwordx4 v[12:15], v[28:29], off offset:1024 nt
	global_load_dwordx4 v[0:3], v50, s[4:5]
	global_load_dwordx4 v[8:11], v50, s[4:5] offset:1024
	global_load_dwordx4 v[16:19], v50, s[4:5] offset:2048
	global_load_dwordx4 v[20:23], v50, s[4:5] offset:3072
	global_load_dwordx4 v[24:27], v[28:29], off offset:2048 nt
	s_nop 0
	global_load_dwordx4 v[28:31], v[28:29], off offset:3072 nt
	v_readlane_b32 s4, v224, 33
	v_lshlrev_b32_e32 v35, 2, v33
	v_xor_b32_e32 v49, 0x80, v35
	v_lshl_add_u32 v52, v32, 12, s4
	v_readlane_b32 s4, v224, 34
	v_xor_b32_e32 v90, 64, v35
	v_xor_b32_e32 v91, 32, v35
	v_add_u32_e32 v32, s4, v32
	v_ashrrev_i32_e32 v33, 31, v32
	v_lshlrev_b64 v[44:45], 11, v[32:33]
	v_or_b32_e32 v44, v44, v34
	v_xor_b32_e32 v92, 16, v35
	v_xor_b32_e32 v93, 8, v35
	v_xor_b32_e32 v94, 4, v35
	v_lshl_add_u64 v[34:35], s[18:19], 0, v[44:45]
	s_mov_b64 s[4:5], 0x9a00600
	s_and_b32 s9, s9, 0xffff
	v_lshl_add_u64 v[54:55], v[34:35], 0, s[4:5]
	s_add_u32 s4, s16, s36
	v_lshlrev_b64 v[32:33], 12, v[32:33]
	s_addc_u32 s5, s17, 0
	v_lshl_add_u64 v[32:33], s[4:5], 0, v[32:33]
	s_brev_b32 s4, 63
	s_mov_b32 s5, -1
	v_mov_b32_e32 v53, v164
	v_lshl_add_u64 v[72:73], v[32:33], 0, s[4:5]
	s_mov_b64 s[16:17], 0
	s_waitcnt vmcnt(11)
	v_lshlrev_b32_e32 v68, 16, v36
	v_and_b32_e32 v69, s100, v36
	v_lshlrev_b32_e32 v70, 16, v37
	s_waitcnt vmcnt(8)
	v_and_b32_e32 v56, s100, v43
	v_lshlrev_b32_e32 v57, 16, v43
	v_and_b32_e32 v71, s100, v37
	v_lshlrev_b32_e32 v64, 16, v38
	v_and_b32_e32 v65, s100, v38
	v_lshlrev_b32_e32 v66, 16, v39
	v_and_b32_e32 v67, s100, v39
	v_lshlrev_b32_e32 v60, 16, v40
	v_and_b32_e32 v61, s100, v40
	v_lshlrev_b32_e32 v62, 16, v41
	v_and_b32_e32 v63, s100, v41
	v_lshlrev_b32_e32 v58, 16, v42
	v_and_b32_e32 v59, s100, v42
	s_branch .LBB0_325

; template <bool WITH_H>
; __device__ void rows_resid(const bf16* __restrict__ Y, const float* __restrict__ xsrc, float* __restrict__ xdst, const float* __restrict__ gpost,
;                            bf16* __restrict__ Hout, const float* __restrict__ gpre, int nrows) {
;     ...
;     const int rn = r + stride;
;     float yn[16], xn[16];
;     if (rn < nrows) { row_load_bf(Y + (size_t)rn * D, lane, yn); row_load(xsrc + (size_t)rn * D, lane, xn); }
.LBB0_325:
	s_mov_b32 s100, 0xffff0000
	v_add_u32_e32 v48, s24, v48
	v_cmp_gt_i32_e64 s[4:5], s92, v48
	v_cmp_lt_i32_e32 vcc, s93, v48
	s_and_saveexec_b64 s[18:19], s[4:5]
	s_cbranch_execz .LBB0_324
	v_lshl_add_u64 v[44:45], v[72:73], 0, v[50:51]
	global_load_dwordx2 v[76:77], v[54:55], off offset:-1536 nt
	global_load_dwordx2 v[80:81], v[54:55], off offset:-1024 nt
	global_load_dwordx2 v[82:83], v[54:55], off offset:-512 nt
	global_load_dwordx2 v[96:97], v[54:55], off nt
	global_load_dwordx4 v[32:35], v[44:45], off nt
	global_load_dwordx4 v[36:39], v[44:45], off offset:1024 nt
	global_load_dwordx4 v[40:43], v[44:45], off offset:2048 nt
	s_nop 0
	global_load_dwordx4 v[44:47], v[44:45], off offset:3072 nt
	s_waitcnt vmcnt(7)
	v_lshlrev_b32_e32 v74, 16, v76
	v_and_b32_e32 v75, s100, v76
	v_lshlrev_b32_e32 v76, 16, v77
	v_and_b32_e32 v77, s100, v77
	s_waitcnt vmcnt(6)
	v_lshlrev_b32_e32 v78, 16, v80
	v_and_b32_e32 v79, s100, v80
	v_lshlrev_b32_e32 v80, 16, v81
	v_and_b32_e32 v81, s100, v81
	s_waitcnt vmcnt(5)
	v_lshlrev_b32_e32 v84, 16, v82
	v_and_b32_e32 v85, s100, v82
	v_lshlrev_b32_e32 v86, 16, v83
	v_and_b32_e32 v87, s100, v83
	s_waitcnt vmcnt(4)
	v_lshlrev_b32_e32 v88, 16, v96
	v_and_b32_e32 v89, s100, v96
	v_and_b32_e32 v82, s100, v97
	v_lshlrev_b32_e32 v83, 16, v97
	s_branch .LBB0_324

.LBB0_433:
	s_mov_b32 s100, 0x3db8aa3b
	s_or_b64 exec, exec, s[16:17]
	s_waitcnt lgkmcnt(0)
	s_barrier
	ds_read_b128 v[156:159], v144
	ds_read_b128 v[196:199], v144 offset:4096
	s_mov_b32 s18, s10
	s_mov_b32 s19, s11
	s_waitcnt lgkmcnt(0)
	v_max_f32_e32 v146, v159, v159
	v_max_f32_e32 v148, v158, v158
	v_max_f32_e32 v146, v148, v146
	v_max3_f32 v204, v156, v157, v146
	v_mul_f32_e32 v204, s100, v204
	v_add_f32_e32 v146, v196, v197
	v_add_f32_e32 v146, v198, v146
	v_add_f32_e32 v146, v199, v146
	v_div_scale_f32 v148, s[16:17], v146, v146, 1.0
	v_rcp_f32_e32 v150, v148
	ds_read_b128 v[196:199], v144 offset:256
	ds_read_b128 v[206:209], v144 offset:4352
	v_fma_f32 v152, -v148, v150, 1.0
	v_fmac_f32_e32 v150, v152, v150
	v_div_scale_f32 v152, vcc, 1.0, v146, 1.0
	v_mul_f32_e32 v154, v152, v150
	v_fma_f32 v156, -v148, v154, v152
	v_fmac_f32_e32 v154, v156, v150
	v_fma_f32 v148, -v148, v154, v152
	v_div_fmas_f32 v148, v148, v150, v154
	v_div_fixup_f32 v158, v148, v146, 1.0
	s_waitcnt lgkmcnt(0)
	v_max_f32_e32 v146, v199, v199
	v_max_f32_e32 v148, v198, v198
	v_max_f32_e32 v146, v148, v146
	v_max3_f32 v201, v196, v197, v146
	v_mul_f32_e32 v201, s100, v201
	v_add_f32_e32 v146, v206, v207
	v_add_f32_e32 v146, v208, v146
	v_add_f32_e32 v146, v209, v146
	v_div_scale_f32 v148, s[16:17], v146, v146, 1.0
	v_rcp_f32_e32 v150, v148
	ds_read_b128 v[196:199], v144 offset:512
	ds_read_b128 v[206:209], v144 offset:4608
	v_fma_f32 v152, -v148, v150, 1.0
	v_fmac_f32_e32 v150, v152, v150
	v_div_scale_f32 v152, vcc, 1.0, v146, 1.0
	v_mul_f32_e32 v154, v152, v150
	v_fma_f32 v156, -v148, v154, v152
	v_fmac_f32_e32 v154, v156, v150
	v_fma_f32 v148, -v148, v154, v152
	v_div_fmas_f32 v148, v148, v150, v154
	v_div_fixup_f32 v156, v148, v146, 1.0
	s_waitcnt lgkmcnt(0)
	v_max_f32_e32 v146, v199, v199
	v_max_f32_e32 v148, v198, v198
	v_max_f32_e32 v146, v148, v146
	v_max3_f32 v200, v196, v197, v146
	v_mul_f32_e32 v200, s100, v200
	v_add_f32_e32 v146, v206, v207
	v_add_f32_e32 v146, v208, v146
	v_add_f32_e32 v146, v209, v146
	v_div_scale_f32 v148, s[16:17], v146, v146, 1.0
	v_rcp_f32_e32 v150, v148
	ds_read_b128 v[196:199], v144 offset:768
	ds_read_b128 v[206:209], v144 offset:4864
	v_fma_f32 v152, -v148, v150, 1.0
	v_fmac_f32_e32 v150, v152, v150
	v_div_scale_f32 v152, vcc, 1.0, v146, 1.0
	v_mul_f32_e32 v154, v152, v150
	v_fma_f32 v157, -v148, v154, v152
	v_fmac_f32_e32 v154, v157, v150
	v_fma_f32 v148, -v148, v154, v152
	v_div_fmas_f32 v148, v148, v150, v154
	v_div_fixup_f32 v154, v148, v146, 1.0
	s_waitcnt lgkmcnt(0)
	v_max_f32_e32 v146, v199, v199
	v_max_f32_e32 v148, v198, v198
	v_max_f32_e32 v146, v148, v146
	v_max3_f32 v199, v196, v197, v146
	v_mul_f32_e32 v199, s100, v199
	v_add_f32_e32 v146, v206, v207
	v_add_f32_e32 v146, v208, v146
	v_add_f32_e32 v146, v209, v146
	v_div_scale_f32 v148, s[16:17], v146, v146, 1.0
	v_rcp_f32_e32 v150, v148
	ds_read_b128 v[206:209], v144 offset:1024
	ds_read_b128 v[210:213], v144 offset:5120
	v_fma_f32 v152, -v148, v150, 1.0
	v_fmac_f32_e32 v150, v152, v150
	v_div_scale_f32 v152, vcc, 1.0, v146, 1.0
	v_mul_f32_e32 v157, v152, v150
	v_fma_f32 v159, -v148, v157, v152
	v_fmac_f32_e32 v157, v159, v150
	v_fma_f32 v148, -v148, v157, v152
	v_div_fmas_f32 v148, v148, v150, v157
	v_div_fixup_f32 v152, v148, v146, 1.0
	s_waitcnt lgkmcnt(0)
	v_max_f32_e32 v146, v209, v209
	v_max_f32_e32 v148, v208, v208
	v_max_f32_e32 v146, v148, v146
	v_max3_f32 v198, v206, v207, v146
	v_mul_f32_e32 v198, s100, v198
	v_add_f32_e32 v146, v210, v211
	v_add_f32_e32 v146, v212, v146
	v_add_f32_e32 v146, v213, v146
	v_div_scale_f32 v148, s[16:17], v146, v146, 1.0
	v_rcp_f32_e32 v150, v148
	ds_read_b128 v[206:209], v144 offset:1280
	ds_read_b128 v[210:213], v144 offset:5376
	v_fma_f32 v157, -v148, v150, 1.0
	v_fmac_f32_e32 v150, v157, v150
	v_div_scale_f32 v157, vcc, 1.0, v146, 1.0
	v_mul_f32_e32 v159, v157, v150
	v_fma_f32 v160, -v148, v159, v157
	v_fmac_f32_e32 v159, v160, v150
	v_fma_f32 v148, -v148, v159, v157
	v_div_fmas_f32 v148, v148, v150, v159
	v_div_fixup_f32 v150, v148, v146, 1.0
	s_waitcnt lgkmcnt(0)
	v_max_f32_e32 v146, v209, v209
	v_max_f32_e32 v148, v208, v208
	v_max_f32_e32 v146, v148, v146
	v_max3_f32 v160, v206, v207, v146
	v_mul_f32_e32 v160, s100, v160
	v_add_f32_e32 v146, v210, v211
	v_add_f32_e32 v146, v212, v146
	v_add_f32_e32 v146, v213, v146
	v_div_scale_f32 v148, s[16:17], v146, v146, 1.0
	v_rcp_f32_e32 v157, v148
	ds_read_b128 v[206:209], v144 offset:1536
	ds_read_b128 v[210:213], v144 offset:5632
	v_fma_f32 v159, -v148, v157, 1.0
	v_fmac_f32_e32 v157, v159, v157
	v_div_scale_f32 v159, vcc, 1.0, v146, 1.0
	v_mul_f32_e32 v196, v159, v157
	v_fma_f32 v197, -v148, v196, v159
	v_fmac_f32_e32 v196, v197, v157
	v_fma_f32 v148, -v148, v196, v159
	v_div_fmas_f32 v148, v148, v157, v196
	v_div_fixup_f32 v148, v148, v146, 1.0
	s_waitcnt lgkmcnt(0)
	v_max_f32_e32 v146, v209, v209
	v_max_f32_e32 v157, v208, v208
	v_max_f32_e32 v146, v157, v146
	v_max3_f32 v159, v206, v207, v146
	v_mul_f32_e32 v159, s100, v159
	v_add_f32_e32 v146, v210, v211
	v_add_f32_e32 v146, v212, v146
	v_add_f32_e32 v146, v213, v146
	v_div_scale_f32 v157, s[16:17], v146, v146, 1.0
	v_rcp_f32_e32 v196, v157
	ds_read_b128 v[206:209], v144 offset:1792
	ds_read_b128 v[210:213], v144 offset:5888
	v_fma_f32 v197, -v157, v196, 1.0
	v_fmac_f32_e32 v196, v197, v196
	v_div_scale_f32 v197, vcc, 1.0, v146, 1.0
	v_mul_f32_e32 v202, v197, v196
	v_fma_f32 v203, -v157, v202, v197
	v_fmac_f32_e32 v202, v203, v196
	v_fma_f32 v157, -v157, v202, v197
	v_div_fmas_f32 v157, v157, v196, v202
	v_div_fixup_f32 v146, v157, v146, 1.0
	s_waitcnt lgkmcnt(0)
; __device__ __forceinline__ uint2 pk4(const f32x4& v) { uint2 r; r.x = pk2(v[0], v[1]); r.y = pk2(v[2], v[3]); return r; }
; template <class F>
; __device__ __forceinline__ void epi_store_bf16(f32x4 (&acc)[8][4], bf16* C, int ldc, int wr, int wc, int fr, int fq, F f) {
;   char* slab = g_shm + 65536 + (wr * 4 + wc) * 8192;
;   const int lane = (fq << 4) | fr;
;   const int rr = lane >> 3, kk = lane & 7;
;   const unsigned go = (unsigned)((wr * 128 + rr) * ldc + wc * 64 + kk * 8);
;   const __amdgpu_buffer_rsrc_t rsrc = __builtin_amdgcn_make_buffer_rsrc((void*)C, (short)0, 0x7fffffff, 0x27000);
; #pragma unroll
;   for (int half = 0; half < 2; ++half) {
; #pragma unroll
;     for (int mm = 0; mm < 4; ++mm)
; #pragma unroll
;       for (int n = 0; n < 4; ++n)
;         *(uint2*)(slab + (mm * 16 + fr) * 128 + (((n * 4 + fq) ^ (fr & 14)) << 3)) = pk4(f(acc[half * 4 + mm][n], half * 4 + mm, n));
	v_max_f32_e32 v144, v209, v209
	v_max_f32_e32 v157, v208, v208
	v_max_f32_e32 v144, v157, v144
	v_max3_f32 v157, v206, v207, v144
	v_mul_f32_e32 v157, s100, v157
	v_add_f32_e32 v144, v210, v211
	v_add_f32_e32 v144, v212, v144
	v_add_f32_e32 v144, v213, v144
	v_div_scale_f32 v196, s[16:17], v144, v144, 1.0
	v_rcp_f32_e32 v197, v196
	s_and_b32 s17, s13, 0xffff
	s_mov_b32 s16, s12
	v_fma_f32 v202, -v196, v197, 1.0
	v_fmac_f32_e32 v197, v202, v197
	v_div_scale_f32 v202, vcc, 1.0, v144, 1.0
	v_mul_f32_e32 v203, v202, v197
	v_fma_f32 v205, -v196, v203, v202
	v_fmac_f32_e32 v203, v205, v197
	v_fma_f32 v196, -v196, v203, v202
	v_div_fmas_f32 v196, v196, v197, v203
	v_div_fixup_f32 v144, v196, v144, 1.0
	v_lshlrev_b32_e32 v196, 15, v155
	v_lshlrev_b32_e32 v197, 13, v147
	v_add3_u32 v202, v196, v197, s89
	v_ashrrev_i32_e32 v203, 3, v153
	v_lshlrev_b32_e32 v205, 18, v155
	v_lshl_add_u32 v155, v203, 7, v202
	v_xor_b32_e32 v153, v153, v145
	v_and_or_b32 v153, v153, s44, v155
	v_fma_f32 v155, v124, v248, -v204
	v_exp_f32_e32 v196, v155
	v_fma_f32 v155, v125, v248, -v204
	v_exp_f32_e32 v197, v155
	v_fma_f32 v155, v126, v248, -v204
	v_exp_f32_e32 v206, v155
	v_fma_f32 v155, v127, v248, -v204
	v_exp_f32_e32 v207, v155
	v_lshl_add_u32 v210, v149, 7, v202
	v_pk_mul_f32 v[196:197], v[158:159], v[196:197] op_sel_hi:[0,1]
	v_bitop3_b32 v155, v149, v151, 14 bitop3:0x6c
	v_pk_mul_f32 v[206:207], v[158:159], v[206:207] op_sel_hi:[0,1]
	v_cvt_pk_bf16_f32 v196, v196, v197
	v_cvt_pk_bf16_f32 v197, v206, v207
	v_lshl_add_u32 v155, v155, 3, v210
	s_waitcnt vmcnt(0)
	ds_write_b64 v155, v[196:197]
	v_fma_f32 v196, v120, v248, -v204
	v_fma_f32 v197, v121, v248, -v204
	v_exp_f32_e32 v196, v196
	v_exp_f32_e32 v197, v197
	v_fma_f32 v206, v122, v248, -v204
	v_fma_f32 v207, v123, v248, -v204
	v_exp_f32_e32 v206, v206
	v_exp_f32_e32 v207, v207
	v_pk_mul_f32 v[196:197], v[158:159], v[196:197] op_sel_hi:[0,1]
	v_cvt_pk_bf16_f32 v208, v196, v197
	v_fma_f32 v197, v116, v248, -v204
	v_pk_mul_f32 v[206:207], v[158:159], v[206:207] op_sel_hi:[0,1]
	v_cvt_pk_bf16_f32 v209, v206, v207
	v_exp_f32_e32 v206, v197
	v_fma_f32 v197, v117, v248, -v204
	v_add_u32_e32 v196, 4, v151
	v_bitop3_b32 v196, v196, v149, 14 bitop3:0x78
	v_exp_f32_e32 v207, v197
	v_fma_f32 v197, v118, v248, -v204
	v_lshl_add_u32 v196, v196, 3, v210
	ds_write_b64 v196, v[208:209]
	v_exp_f32_e32 v208, v197
	v_fma_f32 v197, v119, v248, -v204
	v_exp_f32_e32 v209, v197
	v_add_u32_e32 v197, 8, v151
	v_pk_mul_f32 v[206:207], v[158:159], v[206:207] op_sel_hi:[0,1]
	v_bitop3_b32 v197, v197, v149, 14 bitop3:0x78
	v_pk_mul_f32 v[208:209], v[158:159], v[208:209] op_sel_hi:[0,1]
	v_cvt_pk_bf16_f32 v206, v206, v207
	v_cvt_pk_bf16_f32 v207, v208, v209
	v_lshl_add_u32 v197, v197, 3, v210
	ds_write_b64 v197, v[206:207]
	v_fma_f32 v206, v112, v248, -v204
	v_fma_f32 v207, v113, v248, -v204
	v_fma_f32 v208, v114, v248, -v204
	v_fma_f32 v204, v115, v248, -v204
	v_exp_f32_e32 v206, v206
	v_exp_f32_e32 v207, v207
	v_exp_f32_e32 v208, v208
	v_exp_f32_e32 v209, v204
	v_add_u32_e32 v151, 12, v151
	v_pk_mul_f32 v[206:207], v[158:159], v[206:207] op_sel_hi:[0,1]
	v_bitop3_b32 v149, v151, v149, 14 bitop3:0x78
	v_pk_mul_f32 v[208:209], v[158:159], v[208:209] op_sel_hi:[0,1]
	v_fma_f32 v151, v108, v248, -v201
	v_cvt_pk_bf16_f32 v206, v206, v207
	v_cvt_pk_bf16_f32 v207, v208, v209
	v_lshl_add_u32 v149, v149, 3, v210
	ds_write_b64 v149, v[206:207]
	v_exp_f32_e32 v206, v151
	v_fma_f32 v151, v109, v248, -v201
	v_exp_f32_e32 v207, v151
	v_fma_f32 v151, v110, v248, -v201
	v_exp_f32_e32 v208, v151
	v_fma_f32 v151, v111, v248, -v201
	v_exp_f32_e32 v209, v151
	v_pk_mul_f32 v[206:207], v[156:157], v[206:207] op_sel_hi:[0,1]
	v_fma_f32 v151, v104, v248, -v201
	v_cvt_pk_bf16_f32 v206, v206, v207
	v_pk_mul_f32 v[208:209], v[156:157], v[208:209] op_sel_hi:[0,1]
	v_cvt_pk_bf16_f32 v207, v208, v209
	ds_write_b64 v155, v[206:207] offset:2048
	v_exp_f32_e32 v206, v151
	v_fma_f32 v151, v105, v248, -v201
	v_exp_f32_e32 v207, v151
	v_fma_f32 v151, v106, v248, -v201
	v_exp_f32_e32 v208, v151
	v_fma_f32 v151, v107, v248, -v201
	v_exp_f32_e32 v209, v151
	v_pk_mul_f32 v[206:207], v[156:157], v[206:207] op_sel_hi:[0,1]
	v_fma_f32 v151, v100, v248, -v201
	v_cvt_pk_bf16_f32 v206, v206, v207
	v_pk_mul_f32 v[208:209], v[156:157], v[208:209] op_sel_hi:[0,1]
	v_cvt_pk_bf16_f32 v207, v208, v209
	ds_write_b64 v196, v[206:207] offset:2048
	v_exp_f32_e32 v206, v151
	v_fma_f32 v151, v101, v248, -v201
	v_exp_f32_e32 v207, v151
	v_fma_f32 v151, v102, v248, -v201
	v_exp_f32_e32 v208, v151
	v_fma_f32 v151, v103, v248, -v201
	v_exp_f32_e32 v209, v151
	v_pk_mul_f32 v[206:207], v[156:157], v[206:207] op_sel_hi:[0,1]
	v_fma_f32 v151, v96, v248, -v201
	v_cvt_pk_bf16_f32 v206, v206, v207
	v_pk_mul_f32 v[208:209], v[156:157], v[208:209] op_sel_hi:[0,1]
	v_cvt_pk_bf16_f32 v207, v208, v209
	ds_write_b64 v197, v[206:207] offset:2048
	v_exp_f32_e32 v206, v151
	v_fma_f32 v151, v97, v248, -v201
	v_exp_f32_e32 v207, v151
	v_fma_f32 v151, v98, v248, -v201
	v_exp_f32_e32 v208, v151
	v_fma_f32 v151, v99, v248, -v201
	v_exp_f32_e32 v209, v151
	v_pk_mul_f32 v[206:207], v[156:157], v[206:207] op_sel_hi:[0,1]
	v_fma_f32 v151, v92, v248, -v200
	v_cvt_pk_bf16_f32 v206, v206, v207
	v_pk_mul_f32 v[208:209], v[156:157], v[208:209] op_sel_hi:[0,1]
	v_cvt_pk_bf16_f32 v207, v208, v209
	ds_write_b64 v149, v[206:207] offset:2048
	v_exp_f32_e32 v206, v151
	v_fma_f32 v151, v93, v248, -v200
	v_exp_f32_e32 v207, v151
	v_fma_f32 v151, v94, v248, -v200
	v_exp_f32_e32 v208, v151
	v_fma_f32 v151, v95, v248, -v200
	v_exp_f32_e32 v209, v151
	v_pk_mul_f32 v[206:207], v[154:155], v[206:207] op_sel_hi:[0,1]
	v_fma_f32 v151, v88, v248, -v200
; __device__ __forceinline__ uint2 pk4(const f32x4& v) { uint2 r; r.x = pk2(v[0], v[1]); r.y = pk2(v[2], v[3]); return r; }
; template <class F>
; __device__ __forceinline__ void epi_store_bf16(f32x4 (&acc)[8][4], bf16* C, int ldc, int wr, int wc, int fr, int fq, F f) {
;   char* slab = g_shm + 65536 + (wr * 4 + wc) * 8192;
;   const int lane = (fq << 4) | fr;
;   const int rr = lane >> 3, kk = lane & 7;
;   const unsigned go = (unsigned)((wr * 128 + rr) * ldc + wc * 64 + kk * 8);
;   const __amdgpu_buffer_rsrc_t rsrc = __builtin_amdgcn_make_buffer_rsrc((void*)C, (short)0, 0x7fffffff, 0x27000);
; #pragma unroll
;   for (int half = 0; half < 2; ++half) {
; #pragma unroll
;     for (int mm = 0; mm < 4; ++mm)
; #pragma unroll
;       for (int n = 0; n < 4; ++n)
;         *(uint2*)(slab + (mm * 16 + fr) * 128 + (((n * 4 + fq) ^ (fr & 14)) << 3)) = pk4(f(acc[half * 4 + mm][n], half * 4 + mm, n));
; #pragma unroll
;     for (int i = 0; i < 8; ++i) {
;       const int r = i * 8 + rr;
;       uint4 w = *(const uint4*)(slab + r * 128 + (((2 * kk) ^ (r & 14)) << 3));
;       { typedef unsigned u32x4 __attribute__((ext_vector_type(4)));
;         u32x4 wv = {w.x, w.y, w.z, w.w};
;         __builtin_amdgcn_raw_buffer_store_b128(wv, rsrc, (int)(((unsigned)((half * 64 + i * 8) * ldc) + go) * 2u), 0, 16  ); } }
	v_cvt_pk_bf16_f32 v206, v206, v207
	v_pk_mul_f32 v[208:209], v[154:155], v[208:209] op_sel_hi:[0,1]
	v_cvt_pk_bf16_f32 v207, v208, v209
	ds_write_b64 v155, v[206:207] offset:4096
	v_exp_f32_e32 v206, v151
	v_fma_f32 v151, v89, v248, -v200
	v_exp_f32_e32 v207, v151
	v_fma_f32 v151, v90, v248, -v200
	v_exp_f32_e32 v208, v151
	v_fma_f32 v151, v91, v248, -v200
	v_exp_f32_e32 v209, v151
	v_pk_mul_f32 v[206:207], v[154:155], v[206:207] op_sel_hi:[0,1]
	v_fma_f32 v151, v84, v248, -v200
	v_cvt_pk_bf16_f32 v206, v206, v207
	v_pk_mul_f32 v[208:209], v[154:155], v[208:209] op_sel_hi:[0,1]
	v_cvt_pk_bf16_f32 v207, v208, v209
	ds_write_b64 v196, v[206:207] offset:4096
	v_exp_f32_e32 v206, v151
	v_fma_f32 v151, v85, v248, -v200
	v_exp_f32_e32 v207, v151
	v_fma_f32 v151, v86, v248, -v200
	v_exp_f32_e32 v208, v151
	v_fma_f32 v151, v87, v248, -v200
	v_exp_f32_e32 v209, v151
	v_pk_mul_f32 v[206:207], v[154:155], v[206:207] op_sel_hi:[0,1]
	v_fma_f32 v151, v80, v248, -v200
	v_cvt_pk_bf16_f32 v206, v206, v207
	v_pk_mul_f32 v[208:209], v[154:155], v[208:209] op_sel_hi:[0,1]
	v_cvt_pk_bf16_f32 v207, v208, v209
	ds_write_b64 v197, v[206:207] offset:4096
	v_exp_f32_e32 v206, v151
	v_fma_f32 v151, v81, v248, -v200
	v_exp_f32_e32 v207, v151
	v_fma_f32 v151, v82, v248, -v200
	v_exp_f32_e32 v208, v151
	v_fma_f32 v151, v83, v248, -v200
	v_exp_f32_e32 v209, v151
	v_fma_f32 v151, v76, v248, -v199
	v_pk_mul_f32 v[206:207], v[154:155], v[206:207] op_sel_hi:[0,1]
	v_pk_mul_f32 v[200:201], v[154:155], v[208:209] op_sel_hi:[0,1]
	v_cvt_pk_bf16_f32 v206, v206, v207
	v_cvt_pk_bf16_f32 v207, v200, v201
	v_exp_f32_e32 v200, v151
	v_fma_f32 v151, v77, v248, -v199
	v_exp_f32_e32 v201, v151
	v_fma_f32 v151, v78, v248, -v199
	ds_write_b64 v149, v[206:207] offset:4096
	v_exp_f32_e32 v206, v151
	v_fma_f32 v151, v79, v248, -v199
	v_exp_f32_e32 v207, v151
	v_pk_mul_f32 v[200:201], v[152:153], v[200:201] op_sel_hi:[0,1]
	v_fma_f32 v151, v72, v248, -v199
	v_cvt_pk_bf16_f32 v200, v200, v201
	v_pk_mul_f32 v[206:207], v[152:153], v[206:207] op_sel_hi:[0,1]
	v_cvt_pk_bf16_f32 v201, v206, v207
	ds_write_b64 v155, v[200:201] offset:6144
	v_exp_f32_e32 v200, v151
	v_fma_f32 v151, v73, v248, -v199
	v_exp_f32_e32 v201, v151
	v_fma_f32 v151, v74, v248, -v199
	v_exp_f32_e32 v206, v151
	v_fma_f32 v151, v75, v248, -v199
	v_exp_f32_e32 v207, v151
	v_pk_mul_f32 v[200:201], v[152:153], v[200:201] op_sel_hi:[0,1]
	v_fma_f32 v151, v68, v248, -v199
	v_cvt_pk_bf16_f32 v200, v200, v201
	v_pk_mul_f32 v[206:207], v[152:153], v[206:207] op_sel_hi:[0,1]
	v_cvt_pk_bf16_f32 v201, v206, v207
	ds_write_b64 v196, v[200:201] offset:6144
	v_exp_f32_e32 v200, v151
	v_fma_f32 v151, v69, v248, -v199
	v_exp_f32_e32 v201, v151
	v_fma_f32 v151, v70, v248, -v199
	v_exp_f32_e32 v206, v151
	v_fma_f32 v151, v71, v248, -v199
	v_exp_f32_e32 v207, v151
	v_pk_mul_f32 v[200:201], v[152:153], v[200:201] op_sel_hi:[0,1]
	v_fma_f32 v151, v64, v248, -v199
	v_cvt_pk_bf16_f32 v200, v200, v201
	v_pk_mul_f32 v[206:207], v[152:153], v[206:207] op_sel_hi:[0,1]
	v_cvt_pk_bf16_f32 v201, v206, v207
	ds_write_b64 v197, v[200:201] offset:6144
	v_exp_f32_e32 v200, v151
	v_fma_f32 v151, v65, v248, -v199
	v_exp_f32_e32 v201, v151
	v_fma_f32 v151, v66, v248, -v199
	v_exp_f32_e32 v206, v151
	v_fma_f32 v151, v67, v248, -v199
	v_exp_f32_e32 v207, v151
	v_pk_mul_f32 v[200:201], v[152:153], v[200:201] op_sel_hi:[0,1]
	v_cvt_pk_bf16_f32 v200, v200, v201
	v_add_u32_e32 v151, 8, v203
	v_pk_mul_f32 v[206:207], v[152:153], v[206:207] op_sel_hi:[0,1]
	v_cvt_pk_bf16_f32 v201, v206, v207
	ds_write_b64 v149, v[200:201] offset:6144
	ds_read_b128 v[206:209], v153
	v_lshl_add_u32 v147, v147, 7, v205
	v_lshl_add_u32 v152, v151, 7, v202
	v_lshlrev_b32_e32 v151, 3, v151
	v_and_or_b32 v147, v145, s44, v147
	v_xor_b32_e32 v151, v151, v145
	v_lshl_add_u32 v147, v203, 11, v147
	v_and_or_b32 v151, v151, s44, v152
	s_waitcnt lgkmcnt(0)
	buffer_store_dwordx4 v[206:209], v147, s[16:19], 0 offen sc1
	ds_read_b128 v[204:207], v151
	v_add_u32_e32 v152, 0x4000, v147
	s_waitcnt lgkmcnt(0)
	buffer_store_dwordx4 v[204:207], v152, s[16:19], 0 offen sc1
	ds_read_b128 v[204:207], v153 offset:2048
	v_add_u32_e32 v152, 0x8000, v147
	s_waitcnt lgkmcnt(0)
	buffer_store_dwordx4 v[204:207], v152, s[16:19], 0 offen sc1
	v_add_u32_e32 v152, 24, v203
	v_lshl_add_u32 v154, v152, 7, v202
	v_lshlrev_b32_e32 v152, 3, v152
	v_xor_b32_e32 v152, v152, v145
	v_and_or_b32 v152, v152, s44, v154
	ds_read_b128 v[204:207], v152
	v_add_u32_e32 v154, 0xc000, v147
	s_waitcnt lgkmcnt(0)
	buffer_store_dwordx4 v[204:207], v154, s[16:19], 0 offen sc1
	ds_read_b128 v[204:207], v153 offset:4096
	v_add_u32_e32 v154, 0x10000, v147
	s_waitcnt lgkmcnt(0)
	buffer_store_dwordx4 v[204:207], v154, s[16:19], 0 offen sc1
	v_add_u32_e32 v154, 40, v203
	v_lshl_add_u32 v156, v154, 7, v202
	v_lshlrev_b32_e32 v154, 3, v154
	v_xor_b32_e32 v154, v154, v145
	v_and_or_b32 v154, v154, s44, v156
	ds_read_b128 v[204:207], v154
	v_add_u32_e32 v156, 0x14000, v147
	s_waitcnt lgkmcnt(0)
	buffer_store_dwordx4 v[204:207], v156, s[16:19], 0 offen sc1
	ds_read_b128 v[204:207], v153 offset:6144
	v_add_u32_e32 v156, 0x18000, v147
	s_waitcnt lgkmcnt(0)
	buffer_store_dwordx4 v[204:207], v156, s[16:19], 0 offen sc1
	v_add_u32_e32 v156, 56, v203
	v_lshl_add_u32 v158, v156, 7, v202
	v_lshlrev_b32_e32 v156, 3, v156
	v_xor_b32_e32 v145, v156, v145
	v_and_or_b32 v145, v145, s44, v158
	ds_read_b128 v[200:203], v145
	v_add_u32_e32 v156, 0x1c000, v147
	s_waitcnt lgkmcnt(0)
; __device__ __forceinline__ uint2 pk4(const f32x4& v) { uint2 r; r.x = pk2(v[0], v[1]); r.y = pk2(v[2], v[3]); return r; }
; template <class F>
; __device__ __forceinline__ void epi_store_bf16(f32x4 (&acc)[8][4], bf16* C, int ldc, int wr, int wc, int fr, int fq, F f) {
;     ...
;     for (int mm = 0; mm < 4; ++mm)
; #pragma unroll
;       for (int n = 0; n < 4; ++n)
;         *(uint2*)(slab + (mm * 16 + fr) * 128 + (((n * 4 + fq) ^ (fr & 14)) << 3)) = pk4(f(acc[half * 4 + mm][n], half * 4 + mm, n));
	buffer_store_dwordx4 v[200:203], v156, s[16:19], 0 offen sc1
	v_fma_f32 v156, v60, v248, -v198
	v_exp_f32_e32 v200, v156
	v_fma_f32 v156, v61, v248, -v198
	v_exp_f32_e32 v201, v156
	v_fma_f32 v156, v62, v248, -v198
	v_exp_f32_e32 v202, v156
	v_fma_f32 v156, v63, v248, -v198
	v_exp_f32_e32 v203, v156
	v_pk_mul_f32 v[200:201], v[150:151], v[200:201] op_sel_hi:[0,1]
	v_fma_f32 v156, v56, v248, -v198
	v_cvt_pk_bf16_f32 v200, v200, v201
	v_pk_mul_f32 v[202:203], v[150:151], v[202:203] op_sel_hi:[0,1]
	v_cvt_pk_bf16_f32 v201, v202, v203
	ds_write_b64 v155, v[200:201]
	v_exp_f32_e32 v200, v156
	v_fma_f32 v156, v57, v248, -v198
	v_exp_f32_e32 v201, v156
	v_fma_f32 v156, v58, v248, -v198
	v_exp_f32_e32 v202, v156
	v_fma_f32 v156, v59, v248, -v198
	v_exp_f32_e32 v203, v156
	v_pk_mul_f32 v[200:201], v[150:151], v[200:201] op_sel_hi:[0,1]
	v_fma_f32 v156, v52, v248, -v198
	v_cvt_pk_bf16_f32 v200, v200, v201
	v_pk_mul_f32 v[202:203], v[150:151], v[202:203] op_sel_hi:[0,1]
	v_cvt_pk_bf16_f32 v201, v202, v203
	ds_write_b64 v196, v[200:201]
	v_exp_f32_e32 v200, v156
	v_fma_f32 v156, v53, v248, -v198
	v_exp_f32_e32 v201, v156
	v_fma_f32 v156, v54, v248, -v198
	v_exp_f32_e32 v202, v156
	v_fma_f32 v156, v55, v248, -v198
	v_exp_f32_e32 v203, v156
	v_pk_mul_f32 v[200:201], v[150:151], v[200:201] op_sel_hi:[0,1]
	v_fma_f32 v156, v48, v248, -v198
	v_cvt_pk_bf16_f32 v200, v200, v201
	v_pk_mul_f32 v[202:203], v[150:151], v[202:203] op_sel_hi:[0,1]
	v_cvt_pk_bf16_f32 v201, v202, v203
	ds_write_b64 v197, v[200:201]
	v_exp_f32_e32 v200, v156
	v_fma_f32 v156, v49, v248, -v198
	v_exp_f32_e32 v201, v156
	v_fma_f32 v156, v50, v248, -v198
	v_exp_f32_e32 v202, v156
	v_fma_f32 v156, v51, v248, -v198
	v_exp_f32_e32 v203, v156
	v_pk_mul_f32 v[200:201], v[150:151], v[200:201] op_sel_hi:[0,1]
	v_cvt_pk_bf16_f32 v200, v200, v201
	v_pk_mul_f32 v[198:199], v[150:151], v[202:203] op_sel_hi:[0,1]
	v_fma_f32 v150, v44, v248, -v160
	v_cvt_pk_bf16_f32 v201, v198, v199
	v_exp_f32_e32 v198, v150
	v_fma_f32 v150, v45, v248, -v160
	v_exp_f32_e32 v199, v150
	v_fma_f32 v150, v46, v248, -v160
	ds_write_b64 v149, v[200:201]
	v_exp_f32_e32 v200, v150
	v_fma_f32 v150, v47, v248, -v160
	v_exp_f32_e32 v201, v150
	v_pk_mul_f32 v[198:199], v[148:149], v[198:199] op_sel_hi:[0,1]
	v_fma_f32 v150, v40, v248, -v160
	v_cvt_pk_bf16_f32 v198, v198, v199
	v_pk_mul_f32 v[200:201], v[148:149], v[200:201] op_sel_hi:[0,1]
	v_cvt_pk_bf16_f32 v199, v200, v201
	ds_write_b64 v155, v[198:199] offset:2048
	v_exp_f32_e32 v198, v150
	v_fma_f32 v150, v41, v248, -v160
	v_exp_f32_e32 v199, v150
	v_fma_f32 v150, v42, v248, -v160
	v_exp_f32_e32 v200, v150
	v_fma_f32 v150, v43, v248, -v160
	v_exp_f32_e32 v201, v150
	v_pk_mul_f32 v[198:199], v[148:149], v[198:199] op_sel_hi:[0,1]
	v_fma_f32 v150, v36, v248, -v160
	v_cvt_pk_bf16_f32 v198, v198, v199
	v_pk_mul_f32 v[200:201], v[148:149], v[200:201] op_sel_hi:[0,1]
	v_cvt_pk_bf16_f32 v199, v200, v201
	ds_write_b64 v196, v[198:199] offset:2048
	v_exp_f32_e32 v198, v150
	v_fma_f32 v150, v37, v248, -v160
	v_exp_f32_e32 v199, v150
	v_fma_f32 v150, v38, v248, -v160
	v_exp_f32_e32 v200, v150
	v_fma_f32 v150, v39, v248, -v160
	v_exp_f32_e32 v201, v150
	v_pk_mul_f32 v[198:199], v[148:149], v[198:199] op_sel_hi:[0,1]
	v_fma_f32 v150, v32, v248, -v160
	v_cvt_pk_bf16_f32 v198, v198, v199
	v_pk_mul_f32 v[200:201], v[148:149], v[200:201] op_sel_hi:[0,1]
	v_cvt_pk_bf16_f32 v199, v200, v201
	ds_write_b64 v197, v[198:199] offset:2048
	v_exp_f32_e32 v198, v150
	v_fma_f32 v150, v33, v248, -v160
	v_exp_f32_e32 v199, v150
	v_fma_f32 v150, v34, v248, -v160
	v_exp_f32_e32 v200, v150
	v_fma_f32 v150, v35, v248, -v160
	v_exp_f32_e32 v201, v150
	v_pk_mul_f32 v[198:199], v[148:149], v[198:199] op_sel_hi:[0,1]
	v_cvt_pk_bf16_f32 v198, v198, v199
	v_pk_mul_f32 v[200:201], v[148:149], v[200:201] op_sel_hi:[0,1]
	v_fma_f32 v148, v28, v248, -v159
	v_cvt_pk_bf16_f32 v199, v200, v201
	ds_write_b64 v149, v[198:199] offset:2048
	v_exp_f32_e32 v198, v148
	v_fma_f32 v148, v29, v248, -v159
	v_exp_f32_e32 v199, v148
	v_fma_f32 v148, v30, v248, -v159
	v_exp_f32_e32 v200, v148
	v_fma_f32 v148, v31, v248, -v159
	v_exp_f32_e32 v201, v148
	v_pk_mul_f32 v[198:199], v[146:147], v[198:199] op_sel_hi:[0,1]
	v_fma_f32 v148, v24, v248, -v159
	v_cvt_pk_bf16_f32 v198, v198, v199
	v_pk_mul_f32 v[200:201], v[146:147], v[200:201] op_sel_hi:[0,1]
	v_cvt_pk_bf16_f32 v199, v200, v201
	ds_write_b64 v155, v[198:199] offset:4096
	v_exp_f32_e32 v198, v148
	v_fma_f32 v148, v25, v248, -v159
	v_exp_f32_e32 v199, v148
; #define RAW_BARRIER() do { asm volatile("s_waitcnt lgkmcnt(0)" ::: "memory"); __builtin_amdgcn_s_barrier(); } while (0)
; __device__ __forceinline__ uint2 pk4(const f32x4& v) { uint2 r; r.x = pk2(v[0], v[1]); r.y = pk2(v[2], v[3]); return r; }
; template <class F>
; __device__ __forceinline__ void epi_store_bf16(f32x4 (&acc)[8][4], bf16* C, int ldc, int wr, int wc, int fr, int fq, F f) {
;     ...
;     for (int mm = 0; mm < 4; ++mm)
; #pragma unroll
;       for (int n = 0; n < 4; ++n)
;         *(uint2*)(slab + (mm * 16 + fr) * 128 + (((n * 4 + fq) ^ (fr & 14)) << 3)) = pk4(f(acc[half * 4 + mm][n], half * 4 + mm, n));
; #pragma unroll
;     for (int i = 0; i < 8; ++i) {
;       const int r = i * 8 + rr;
;       uint4 w = *(const uint4*)(slab + r * 128 + (((2 * kk) ^ (r & 14)) << 3));
;       { typedef unsigned u32x4 __attribute__((ext_vector_type(4)));
;         u32x4 wv = {w.x, w.y, w.z, w.w};
;         __builtin_amdgcn_raw_buffer_store_b128(wv, rsrc, (int)(((unsigned)((half * 64 + i * 8) * ldc) + go) * 2u), 0, 16  ); } }
;   }
;   RAW_BARRIER();
	v_fma_f32 v148, v26, v248, -v159
	v_exp_f32_e32 v200, v148
	v_fma_f32 v148, v27, v248, -v159
	v_exp_f32_e32 v201, v148
	v_pk_mul_f32 v[198:199], v[146:147], v[198:199] op_sel_hi:[0,1]
	v_fma_f32 v148, v20, v248, -v159
	v_cvt_pk_bf16_f32 v198, v198, v199
	v_pk_mul_f32 v[200:201], v[146:147], v[200:201] op_sel_hi:[0,1]
	v_cvt_pk_bf16_f32 v199, v200, v201
	ds_write_b64 v196, v[198:199] offset:4096
	v_exp_f32_e32 v198, v148
	v_fma_f32 v148, v21, v248, -v159
	v_exp_f32_e32 v199, v148
	v_fma_f32 v148, v22, v248, -v159
	v_exp_f32_e32 v200, v148
	v_fma_f32 v148, v23, v248, -v159
	v_exp_f32_e32 v201, v148
	v_pk_mul_f32 v[198:199], v[146:147], v[198:199] op_sel_hi:[0,1]
	v_fma_f32 v148, v16, v248, -v159
	v_cvt_pk_bf16_f32 v198, v198, v199
	v_pk_mul_f32 v[200:201], v[146:147], v[200:201] op_sel_hi:[0,1]
	v_cvt_pk_bf16_f32 v199, v200, v201
	ds_write_b64 v197, v[198:199] offset:4096
	v_exp_f32_e32 v198, v148
	v_fma_f32 v148, v17, v248, -v159
	v_exp_f32_e32 v199, v148
	v_fma_f32 v148, v18, v248, -v159
	v_exp_f32_e32 v158, v148
	v_fma_f32 v148, v19, v248, -v159
	v_exp_f32_e32 v159, v148
	v_pk_mul_f32 v[198:199], v[146:147], v[198:199] op_sel_hi:[0,1]
	v_cvt_pk_bf16_f32 v198, v198, v199
	v_pk_mul_f32 v[158:159], v[146:147], v[158:159] op_sel_hi:[0,1]
	v_fma_f32 v146, v12, v248, -v157
	v_cvt_pk_bf16_f32 v199, v158, v159
	v_exp_f32_e32 v158, v146
	v_fma_f32 v146, v13, v248, -v157
	v_exp_f32_e32 v159, v146
	v_fma_f32 v146, v14, v248, -v157
	ds_write_b64 v149, v[198:199] offset:4096
	v_exp_f32_e32 v198, v146
	v_fma_f32 v146, v15, v248, -v157
	v_exp_f32_e32 v199, v146
	v_pk_mul_f32 v[158:159], v[144:145], v[158:159] op_sel_hi:[0,1]
	v_fma_f32 v146, v8, v248, -v157
	v_cvt_pk_bf16_f32 v158, v158, v159
	v_pk_mul_f32 v[198:199], v[144:145], v[198:199] op_sel_hi:[0,1]
	v_cvt_pk_bf16_f32 v159, v198, v199
	ds_write_b64 v155, v[158:159] offset:6144
	v_exp_f32_e32 v158, v146
	v_fma_f32 v146, v9, v248, -v157
	v_exp_f32_e32 v159, v146
	v_fma_f32 v146, v10, v248, -v157
	v_exp_f32_e32 v198, v146
	v_fma_f32 v146, v11, v248, -v157
	v_exp_f32_e32 v199, v146
	v_pk_mul_f32 v[158:159], v[144:145], v[158:159] op_sel_hi:[0,1]
	v_fma_f32 v146, v4, v248, -v157
	v_cvt_pk_bf16_f32 v158, v158, v159
	v_pk_mul_f32 v[198:199], v[144:145], v[198:199] op_sel_hi:[0,1]
	v_cvt_pk_bf16_f32 v159, v198, v199
	ds_write_b64 v196, v[158:159] offset:6144
	v_exp_f32_e32 v158, v146
	v_fma_f32 v146, v5, v248, -v157
	v_exp_f32_e32 v159, v146
	v_fma_f32 v146, v6, v248, -v157
	v_exp_f32_e32 v198, v146
	v_fma_f32 v146, v7, v248, -v157
	v_exp_f32_e32 v199, v146
	v_pk_mul_f32 v[158:159], v[144:145], v[158:159] op_sel_hi:[0,1]
	v_fma_f32 v146, v0, v248, -v157
	v_cvt_pk_bf16_f32 v158, v158, v159
	v_pk_mul_f32 v[198:199], v[144:145], v[198:199] op_sel_hi:[0,1]
	v_cvt_pk_bf16_f32 v159, v198, v199
	ds_write_b64 v197, v[158:159] offset:6144
	v_exp_f32_e32 v158, v146
	v_fma_f32 v146, v1, v248, -v157
	v_exp_f32_e32 v159, v146
	v_fma_f32 v146, v2, v248, -v157
	v_exp_f32_e32 v156, v146
	v_fma_f32 v146, v3, v248, -v157
	v_exp_f32_e32 v157, v146
	v_pk_mul_f32 v[158:159], v[144:145], v[158:159] op_sel_hi:[0,1]
	v_cvt_pk_bf16_f32 v158, v158, v159
	v_pk_mul_f32 v[156:157], v[144:145], v[156:157] op_sel_hi:[0,1]
	v_cvt_pk_bf16_f32 v159, v156, v157
	ds_write_b64 v149, v[158:159] offset:6144
	ds_read_b128 v[156:159], v153
	ds_read_b128 v[148:151], v151
	v_add_u32_e32 v144, 0x20000, v147
	s_waitcnt lgkmcnt(1)
	buffer_store_dwordx4 v[156:159], v144, s[16:19], 0 offen sc1
	v_add_u32_e32 v144, 0x24000, v147
	s_waitcnt lgkmcnt(0)
	buffer_store_dwordx4 v[148:151], v144, s[16:19], 0 offen sc1
	ds_read_b128 v[148:151], v153 offset:2048
	v_add_u32_e32 v144, 0x28000, v147
	s_waitcnt lgkmcnt(0)
	buffer_store_dwordx4 v[148:151], v144, s[16:19], 0 offen sc1
	ds_read_b128 v[148:151], v152
	v_add_u32_e32 v144, 0x2c000, v147
	s_waitcnt lgkmcnt(0)
	buffer_store_dwordx4 v[148:151], v144, s[16:19], 0 offen sc1
	ds_read_b128 v[148:151], v153 offset:4096
	v_add_u32_e32 v144, 0x30000, v147
	s_waitcnt lgkmcnt(0)
	buffer_store_dwordx4 v[148:151], v144, s[16:19], 0 offen sc1
	ds_read_b128 v[148:151], v154
	v_add_u32_e32 v144, 0x34000, v147
	s_waitcnt lgkmcnt(0)
	buffer_store_dwordx4 v[148:151], v144, s[16:19], 0 offen sc1
	ds_read_b128 v[148:151], v153 offset:6144
	v_add_u32_e32 v144, 0x38000, v147
	s_waitcnt lgkmcnt(0)
	buffer_store_dwordx4 v[148:151], v144, s[16:19], 0 offen sc1
	ds_read_b128 v[148:151], v145
	v_add_u32_e32 v144, 0x3c000, v147
	s_waitcnt lgkmcnt(0)
	buffer_store_dwordx4 v[148:151], v144, s[16:19], 0 offen sc1
	s_waitcnt lgkmcnt(0)
	s_barrier

.LBB0_457:
	s_mov_b32 s34, 0xffff0000
	s_mov_b32 s100, 0xbfb8aa3b
	s_mov_b32 s101, 0x437f0000
	v_mov_b32_e32 v156, v194
	v_mov_b32_e32 v157, v165
	v_mov_b32_e32 v158, v195
	v_mov_b32_e32 v159, v193
	v_lshlrev_b32_e32 v202, 16, v142
	v_lshlrev_b32_e32 v144, 4, v158
	v_lshl_add_u32 v144, v159, 2, v144
	v_ashrrev_i32_e32 v145, 31, v144
	v_lshlrev_b64 v[148:149], 2, v[144:145]
	v_lshl_add_u64 v[152:153], s[66:67], 0, v[148:149]
	v_lshl_add_u64 v[154:155], s[64:65], 0, v[148:149]
	global_load_dwordx4 v[144:147], v[152:153], off
	global_load_dwordx4 v[148:151], v[154:155], off
	v_and_b32_e32 v246, 63, v163
	v_lshlrev_b32_e32 v246, 2, v246
	global_load_dword v247, v246, s[68:69] offset:256
	global_load_dword v246, v246, s[68:69]
	v_and_b32_e32 v203, s34, v142
	v_lshlrev_b32_e32 v142, 6, v158
	v_lshl_add_u32 v158, v158, 2, v159
	v_lshlrev_b32_e32 v160, 15, v156
	v_lshl_add_u32 v142, v156, 8, v142
	v_xor_b32_e32 v156, v158, v157
	v_lshl_or_b32 v201, v159, 4, v142
	v_lshlrev_b32_e32 v142, 4, v156
	v_lshlrev_b32_e32 v198, 8, v157
	v_add3_u32 v142, v142, v160, s89
	v_add_u32_e32 v158, v142, v198
	v_lshlrev_b32_e32 v196, 16, v140
	v_and_b32_e32 v197, s34, v140
	v_lshlrev_b32_e32 v140, 16, v141
	v_and_b32_e32 v141, s34, v141
	v_or_b32_e32 v156, v201, v157
	s_movk_i32 s4, 0x100
	v_add_u32_e32 v200, 0x100, v156
	v_cmp_gt_i32_e64 s[4:5], s4, v156
	s_and_b32 s9, s9, 0xffff
	v_cmp_lt_i32_e32 vcc, s81, v156
	s_waitcnt vmcnt(0)
	v_add_f32_e32 v142, v124, v144
	v_add_f32_e32 v159, v120, v148
	v_add_f32_e32 v160, v125, v145
	v_add_f32_e32 v198, v121, v149
	v_add_f32_e32 v199, v126, v146
	v_add_f32_e32 v204, v122, v150
	v_add_f32_e32 v205, v127, v147
	v_add_f32_e32 v206, v123, v151
	v_med3_f32 v142, v142, s6, v191
	v_med3_f32 v159, v159, s6, v191
	v_med3_f32 v160, v160, s6, v191
	v_med3_f32 v198, v198, s6, v191
	v_med3_f32 v199, v199, s6, v191
	v_med3_f32 v204, v204, s6, v191
	v_med3_f32 v205, v205, s6, v191
	v_med3_f32 v206, v206, s6, v191
	v_mul_f32_e32 v142, s100, v142
	v_mul_f32_e32 v159, s100, v159
	v_mul_f32_e32 v160, s100, v160
	v_mul_f32_e32 v207, s100, v198
	v_mul_f32_e32 v208, s100, v199
	v_mul_f32_e32 v209, s100, v204
	v_mul_f32_e32 v205, s100, v205
	v_mul_f32_e32 v206, s100, v206
	v_exp_f32_e32 v198, v142
	v_exp_f32_e32 v142, v159
	v_exp_f32_e32 v199, v160
	v_exp_f32_e32 v159, v207
	v_exp_f32_e32 v204, v208
	v_exp_f32_e32 v160, v209
	v_exp_f32_e32 v205, v205
	v_exp_f32_e32 v206, v206
	v_add_f32_e32 v142, 1.0, v142
	v_add_f32_e32 v159, 1.0, v159
	v_pk_add_f32 v[198:199], v[198:199], 1.0 op_sel_hi:[1,0]
	v_add_f32_e32 v160, 1.0, v160
	v_add_f32_e32 v211, 1.0, v206
	v_pk_add_f32 v[204:205], v[204:205], 1.0 op_sel_hi:[1,0]
	v_mul_f32_e32 v206, v198, v142
	v_mul_f32_e32 v207, v199, v159
	v_mul_f32_e32 v208, v204, v160
	v_mul_f32_e32 v209, v205, v211
	v_rcp_f32_e32 v206, v206
	v_rcp_f32_e32 v207, v207
	v_rcp_f32_e32 v208, v208
	v_rcp_f32_e32 v209, v209
	v_mul_f32_e32 v142, v142, v206
	v_pk_mul_f32 v[198:199], v[198:199], v[206:207]
	v_mul_f32_e32 v160, v160, v208
	v_pk_mul_f32 v[204:205], v[204:205], v[208:209]
	v_mul_f32_e32 v206, v211, v209
	v_pk_mul_f32 v[196:197], v[198:199], v[196:197]
	v_mul_f32_e32 v160, s101, v160
	v_pk_mul_f32 v[140:141], v[204:205], v[140:141]
	v_mul_f32_e32 v198, s101, v206
	v_rndne_f32_e32 v160, v160
	v_cvt_pk_f16_f32 v140, v140, v141
	v_rndne_f32_e32 v141, v198
	v_cvt_f16_f32_e32 v141, v141
	v_cvt_f16_f32_e32 v160, v160
	v_mul_f32_e32 v159, v159, v207
	v_mul_f32_e32 v159, s101, v159
	v_bfi_b32 v199, s98, v141, v140
	v_pack_b32_f16 v198, v160, v140
	v_add_f32_e32 v140, v104, v148
	v_rndne_f32_e32 v159, v159
	v_med3_f32 v140, v140, s6, v191
	v_mul_f32_e32 v140, s100, v140
	v_cvt_f16_f32_e32 v159, v159
	v_exp_f32_e32 v141, v140
	v_mul_f32_e32 v142, s101, v142
	v_rndne_f32_e32 v142, v142
	v_cvt_pk_f16_f32 v196, v196, v197
	v_add_f32_e32 v210, v108, v144
	v_bfi_b32 v197, s98, v159, v196
	v_add_f32_e32 v159, 1.0, v141
	v_add_f32_e32 v141, v109, v145
	v_cvt_f16_f32_e32 v142, v142
	v_med3_f32 v140, v210, s6, v191
	v_med3_f32 v141, v141, s6, v191
	v_mul_f32_e32 v140, s100, v140
	v_mul_f32_e32 v141, s100, v141
	v_exp_f32_e32 v140, v140
	v_exp_f32_e32 v141, v141
	v_pack_b32_f16 v196, v142, v196
	v_add_f32_e32 v142, v105, v149
	v_med3_f32 v142, v142, s6, v191
	v_mul_f32_e32 v142, s100, v142
	v_pk_add_f32 v[140:141], v[140:141], 1.0 op_sel_hi:[1,0]
	v_exp_f32_e32 v160, v142
	v_mul_f32_e32 v142, v140, v159
	v_rcp_f32_e32 v142, v142
	ds_write_b128 v158, v[196:199]
	v_lshlrev_b32_e32 v196, 16, v143
	v_and_b32_e32 v197, s34, v143
	v_add_f32_e32 v160, 1.0, v160
	v_mul_f32_e32 v143, v159, v142
	v_mul_f32_e32 v159, s101, v143
	v_mul_f32_e32 v143, v141, v160
	v_rcp_f32_e32 v143, v143
	v_rndne_f32_e32 v159, v159
	v_cvt_f16_f32_e32 v159, v159
	v_pk_mul_f32 v[140:141], v[140:141], v[142:143]
	v_add_f32_e32 v142, v107, v151
	v_pk_mul_f32 v[140:141], v[140:141], v[202:203]
	v_med3_f32 v142, v142, s6, v191
	v_cvt_pk_f16_f32 v198, v140, v141
	v_add_f32_e32 v141, v106, v150
	v_med3_f32 v141, v141, s6, v191
	v_mul_f32_e32 v141, s100, v141
	v_exp_f32_e32 v141, v141
	v_mul_f32_e32 v140, v160, v143
	v_mul_f32_e32 v140, s101, v140
	v_rndne_f32_e32 v143, v140
	v_add_f32_e32 v140, v110, v146
	v_add_f32_e32 v160, 1.0, v141
	v_add_f32_e32 v141, v111, v147
	v_med3_f32 v140, v140, s6, v191
	v_med3_f32 v141, v141, s6, v191
	v_mul_f32_e32 v140, s100, v140
	v_mul_f32_e32 v141, s100, v141
	v_exp_f32_e32 v140, v140
	v_exp_f32_e32 v141, v141
	v_mul_f32_e32 v142, s100, v142
	v_exp_f32_e32 v199, v142
	v_pk_add_f32 v[140:141], v[140:141], 1.0 op_sel_hi:[1,0]
	v_cvt_f16_f32_e32 v202, v143
	v_mul_f32_e32 v142, v140, v160
	v_rcp_f32_e32 v142, v142
	v_add_f32_e32 v199, 1.0, v199
	v_mul_f32_e32 v143, v160, v142
	v_mul_f32_e32 v160, s101, v143
	v_mul_f32_e32 v143, v141, v199
	v_rcp_f32_e32 v143, v143
	v_rndne_f32_e32 v160, v160
	v_cvt_f16_f32_e32 v160, v160
	v_mul_f32_e32 v199, v199, v143
	v_mul_f32_e32 v199, s101, v199
	v_rndne_f32_e32 v199, v199
	v_cvt_f16_f32_e32 v199, v199
	v_pk_mul_f32 v[140:141], v[140:141], v[142:143]
	s_nop 0
	v_pk_mul_f32 v[140:141], v[140:141], v[196:197]
	v_lshlrev_b32_e32 v196, 16, v137
	v_cvt_pk_f16_f32 v140, v140, v141
	v_bfi_b32 v143, s98, v199, v140
	v_bfi_b32 v141, s98, v202, v198
	v_pack_b32_f16 v142, v160, v140
	v_pack_b32_f16 v140, v159, v198
	ds_write_b128 v158, v[140:143] offset:4096
	v_add_f32_e32 v142, v88, v148
	v_lshlrev_b32_e32 v140, 16, v136
	v_and_b32_e32 v141, s34, v136
	v_add_f32_e32 v136, v92, v144
	v_med3_f32 v142, v142, s6, v191
	v_mul_f32_e32 v142, s100, v142
	v_med3_f32 v136, v136, s6, v191
	v_exp_f32_e32 v143, v142
	v_mul_f32_e32 v136, s100, v136
	v_exp_f32_e32 v142, v136
	v_add_f32_e32 v136, v93, v145
	v_med3_f32 v136, v136, s6, v191
	v_mul_f32_e32 v136, s100, v136
	v_add_f32_e32 v159, 1.0, v143
	v_exp_f32_e32 v143, v136
	v_add_f32_e32 v160, v89, v149
	v_med3_f32 v136, v160, s6, v191
	v_mul_f32_e32 v136, s100, v136
	v_pk_add_f32 v[142:143], v[142:143], 1.0 op_sel_hi:[1,0]
	v_exp_f32_e32 v160, v136
	v_mul_f32_e32 v136, v142, v159
	v_rcp_f32_e32 v136, v136
	v_and_b32_e32 v197, s34, v137
	v_add_f32_e32 v160, 1.0, v160
	v_mul_f32_e32 v137, v159, v136
	v_mul_f32_e32 v159, s101, v137
	v_mul_f32_e32 v137, v143, v160
	v_rcp_f32_e32 v137, v137
	v_rndne_f32_e32 v159, v159
	v_cvt_f16_f32_e32 v159, v159
	v_pk_mul_f32 v[142:143], v[142:143], v[136:137]
	v_mul_f32_e32 v136, v160, v137
	v_add_f32_e32 v137, v90, v150
	v_med3_f32 v137, v137, s6, v191
	v_mul_f32_e32 v137, s100, v137
	v_exp_f32_e32 v137, v137
	v_pk_mul_f32 v[140:141], v[142:143], v[140:141]
	v_mul_f32_e32 v136, s101, v136
	v_cvt_pk_f16_f32 v198, v140, v141
	v_rndne_f32_e32 v141, v136
	v_add_f32_e32 v136, v94, v146
	v_add_f32_e32 v142, 1.0, v137
	v_add_f32_e32 v137, v95, v147
	v_med3_f32 v136, v136, s6, v191
	v_med3_f32 v137, v137, s6, v191
	v_mul_f32_e32 v136, s100, v136
	v_mul_f32_e32 v137, s100, v137
	v_exp_f32_e32 v136, v136
	v_exp_f32_e32 v137, v137
	v_add_f32_e32 v140, v91, v151
	v_med3_f32 v140, v140, s6, v191
	v_mul_f32_e32 v140, s100, v140
	v_pk_add_f32 v[136:137], v[136:137], 1.0 op_sel_hi:[1,0]
	v_exp_f32_e32 v143, v140
	v_mul_f32_e32 v140, v136, v142
	v_rcp_f32_e32 v140, v140
	v_cvt_f16_f32_e32 v160, v141
	v_add_f32_e32 v143, 1.0, v143
	v_mul_f32_e32 v141, v142, v140
	v_mul_f32_e32 v142, s101, v141
	v_mul_f32_e32 v141, v137, v143
	v_rcp_f32_e32 v141, v141
	v_rndne_f32_e32 v142, v142
	v_cvt_f16_f32_e32 v142, v142
	v_mul_f32_e32 v143, v143, v141
	v_mul_f32_e32 v143, s101, v143
	v_rndne_f32_e32 v143, v143
	v_cvt_f16_f32_e32 v143, v143
	v_pk_mul_f32 v[136:137], v[136:137], v[140:141]
	v_bfi_b32 v141, s98, v160, v198
	v_pk_mul_f32 v[136:137], v[136:137], v[196:197]
	v_pack_b32_f16 v140, v159, v198
	v_cvt_pk_f16_f32 v136, v136, v137
	v_bfi_b32 v143, s98, v143, v136
	v_pack_b32_f16 v142, v142, v136
	ds_write_b128 v158, v[140:143] offset:8192
	v_add_f32_e32 v140, v72, v148
	v_lshlrev_b32_e32 v136, 16, v138
	v_and_b32_e32 v137, s34, v138
	v_add_f32_e32 v138, v76, v144
	v_med3_f32 v140, v140, s6, v191
	v_mul_f32_e32 v140, s100, v140
	v_med3_f32 v138, v138, s6, v191
	v_exp_f32_e32 v141, v140
	v_mul_f32_e32 v138, s100, v138
	v_exp_f32_e32 v140, v138
	v_add_f32_e32 v138, v77, v145
	v_med3_f32 v138, v138, s6, v191
	v_mul_f32_e32 v138, s100, v138
	v_add_f32_e32 v159, 1.0, v141
	v_exp_f32_e32 v141, v138
	v_add_f32_e32 v142, v73, v149
	v_med3_f32 v138, v142, s6, v191
	v_mul_f32_e32 v138, s100, v138
	v_pk_add_f32 v[140:141], v[140:141], 1.0 op_sel_hi:[1,0]
	v_exp_f32_e32 v160, v138
	v_mul_f32_e32 v138, v140, v159
	v_rcp_f32_e32 v138, v138
	v_lshlrev_b32_e32 v142, 16, v139
	v_and_b32_e32 v143, s34, v139
	v_add_f32_e32 v160, 1.0, v160
	v_mul_f32_e32 v139, v159, v138
	v_mul_f32_e32 v159, s101, v139
	v_mul_f32_e32 v139, v141, v160
	v_rcp_f32_e32 v139, v139
	v_rndne_f32_e32 v159, v159
	v_cvt_f16_f32_e32 v159, v159
	v_pk_mul_f32 v[140:141], v[140:141], v[138:139]
	v_add_f32_e32 v138, v75, v151
	v_pk_mul_f32 v[136:137], v[140:141], v[136:137]
	v_med3_f32 v138, v138, s6, v191
	v_cvt_pk_f16_f32 v140, v136, v137
	v_add_f32_e32 v137, v74, v150
	v_med3_f32 v137, v137, s6, v191
	v_mul_f32_e32 v137, s100, v137
	v_exp_f32_e32 v137, v137
	v_mul_f32_e32 v136, v160, v139
	v_mul_f32_e32 v136, s101, v136
	v_rndne_f32_e32 v139, v136
	v_add_f32_e32 v136, v78, v146
	v_add_f32_e32 v141, 1.0, v137
	v_add_f32_e32 v137, v79, v147
	v_med3_f32 v136, v136, s6, v191
	v_med3_f32 v137, v137, s6, v191
	v_mul_f32_e32 v136, s100, v136
	v_mul_f32_e32 v137, s100, v137
	v_exp_f32_e32 v136, v136
	v_exp_f32_e32 v137, v137
	v_mul_f32_e32 v138, s100, v138
	v_exp_f32_e32 v160, v138
	v_pk_add_f32 v[136:137], v[136:137], 1.0 op_sel_hi:[1,0]
	v_cvt_f16_f32_e32 v196, v139
	v_mul_f32_e32 v138, v136, v141
	v_rcp_f32_e32 v138, v138
	v_add_f32_e32 v160, 1.0, v160
	v_mul_f32_e32 v139, v141, v138
	v_mul_f32_e32 v141, s101, v139
	v_mul_f32_e32 v139, v137, v160
	v_rcp_f32_e32 v139, v139
	v_rndne_f32_e32 v141, v141
	v_cvt_f16_f32_e32 v141, v141
	v_mul_f32_e32 v160, v160, v139
	v_mul_f32_e32 v160, s101, v160
	v_rndne_f32_e32 v160, v160
	v_cvt_f16_f32_e32 v160, v160
	v_pk_mul_f32 v[136:137], v[136:137], v[138:139]
	s_nop 0
	v_pk_mul_f32 v[136:137], v[136:137], v[142:143]
	s_nop 0
	v_cvt_pk_f16_f32 v136, v136, v137
	v_bfi_b32 v139, s98, v160, v136
	v_bfi_b32 v137, s98, v196, v140
	v_pack_b32_f16 v138, v141, v136
	v_pack_b32_f16 v136, v159, v140
	ds_write_b128 v158, v[136:139] offset:12288
	v_add_f32_e32 v138, v56, v148
	v_lshlrev_b32_e32 v136, 16, v132
	v_and_b32_e32 v137, s34, v132
	v_add_f32_e32 v132, v60, v144
	v_med3_f32 v138, v138, s6, v191
	v_mul_f32_e32 v138, s100, v138
	v_med3_f32 v132, v132, s6, v191
	v_exp_f32_e32 v139, v138
	v_mul_f32_e32 v132, s100, v132
	v_exp_f32_e32 v138, v132
	v_add_f32_e32 v132, v61, v145
	v_med3_f32 v132, v132, s6, v191
	v_mul_f32_e32 v132, s100, v132
	v_add_f32_e32 v142, 1.0, v139
	v_exp_f32_e32 v139, v132
	v_add_f32_e32 v140, v57, v149
	v_med3_f32 v132, v140, s6, v191
	v_mul_f32_e32 v132, s100, v132
	v_pk_add_f32 v[138:139], v[138:139], 1.0 op_sel_hi:[1,0]
	v_exp_f32_e32 v143, v132
	v_mul_f32_e32 v132, v138, v142
	v_rcp_f32_e32 v132, v132
	v_lshlrev_b32_e32 v140, 16, v133
	v_and_b32_e32 v141, s34, v133
	v_add_f32_e32 v143, 1.0, v143
	v_mul_f32_e32 v133, v142, v132
	v_mul_f32_e32 v142, s101, v133
	v_mul_f32_e32 v133, v139, v143
	v_rcp_f32_e32 v133, v133
	v_rndne_f32_e32 v142, v142
	v_cvt_f16_f32_e32 v142, v142
	v_pk_mul_f32 v[138:139], v[138:139], v[132:133]
	v_mul_f32_e32 v132, v143, v133
	v_add_f32_e32 v133, v58, v150
	v_med3_f32 v133, v133, s6, v191
	v_mul_f32_e32 v133, s100, v133
	v_exp_f32_e32 v133, v133
	v_pk_mul_f32 v[136:137], v[138:139], v[136:137]
	v_mul_f32_e32 v132, s101, v132
	v_cvt_pk_f16_f32 v159, v136, v137
	v_rndne_f32_e32 v137, v132
	v_add_f32_e32 v132, v62, v146
	v_add_f32_e32 v138, 1.0, v133
	v_add_f32_e32 v133, v63, v147
	v_med3_f32 v132, v132, s6, v191
	v_med3_f32 v133, v133, s6, v191
	v_mul_f32_e32 v132, s100, v132
	v_mul_f32_e32 v133, s100, v133
	v_exp_f32_e32 v132, v132
	v_exp_f32_e32 v133, v133
	v_add_f32_e32 v136, v59, v151
	v_med3_f32 v136, v136, s6, v191
	v_mul_f32_e32 v136, s100, v136
	v_pk_add_f32 v[132:133], v[132:133], 1.0 op_sel_hi:[1,0]
	v_exp_f32_e32 v139, v136
	v_mul_f32_e32 v136, v132, v138
	v_rcp_f32_e32 v136, v136
	v_cvt_f16_f32_e32 v143, v137
	v_add_f32_e32 v139, 1.0, v139
	v_mul_f32_e32 v137, v138, v136
	v_mul_f32_e32 v138, s101, v137
	v_mul_f32_e32 v137, v133, v139
	v_rcp_f32_e32 v137, v137
	v_rndne_f32_e32 v138, v138
	v_cvt_f16_f32_e32 v138, v138
	v_mul_f32_e32 v139, v139, v137
	v_mul_f32_e32 v139, s101, v139
	v_rndne_f32_e32 v139, v139
	v_cvt_f16_f32_e32 v139, v139
	v_pk_mul_f32 v[132:133], v[132:133], v[136:137]
	v_bfi_b32 v137, s98, v143, v159
	v_pk_mul_f32 v[132:133], v[132:133], v[140:141]
	v_pack_b32_f16 v136, v142, v159
	v_cvt_pk_f16_f32 v132, v132, v133
	v_bfi_b32 v139, s98, v139, v132
	v_pack_b32_f16 v138, v138, v132
	ds_write_b128 v158, v[136:139] offset:16384
	v_add_f32_e32 v136, v40, v148
	v_lshlrev_b32_e32 v132, 16, v134
	v_and_b32_e32 v133, s34, v134
	v_add_f32_e32 v134, v44, v144
	v_med3_f32 v136, v136, s6, v191
	v_mul_f32_e32 v136, s100, v136
	v_med3_f32 v134, v134, s6, v191
	v_exp_f32_e32 v137, v136
	v_mul_f32_e32 v134, s100, v134
	v_exp_f32_e32 v136, v134
	v_add_f32_e32 v134, v45, v145
	v_med3_f32 v134, v134, s6, v191
	v_mul_f32_e32 v134, s100, v134
	v_add_f32_e32 v140, 1.0, v137
	v_exp_f32_e32 v137, v134
	v_add_f32_e32 v138, v41, v149
	v_med3_f32 v134, v138, s6, v191
	v_mul_f32_e32 v134, s100, v134
	v_pk_add_f32 v[136:137], v[136:137], 1.0 op_sel_hi:[1,0]
	v_exp_f32_e32 v141, v134
	v_mul_f32_e32 v134, v136, v140
	v_rcp_f32_e32 v134, v134
	v_lshlrev_b32_e32 v138, 16, v135
	v_and_b32_e32 v139, s34, v135
	v_add_f32_e32 v141, 1.0, v141
	v_mul_f32_e32 v135, v140, v134
	v_mul_f32_e32 v140, s101, v135
	v_mul_f32_e32 v135, v137, v141
	v_rcp_f32_e32 v135, v135
	v_rndne_f32_e32 v140, v140
	v_cvt_f16_f32_e32 v140, v140
	v_pk_mul_f32 v[136:137], v[136:137], v[134:135]
	v_add_f32_e32 v134, v43, v151
	v_pk_mul_f32 v[132:133], v[136:137], v[132:133]
	v_med3_f32 v134, v134, s6, v191
	v_cvt_pk_f16_f32 v136, v132, v133
	v_add_f32_e32 v133, v42, v150
	v_med3_f32 v133, v133, s6, v191
	v_mul_f32_e32 v133, s100, v133
	v_exp_f32_e32 v133, v133
	v_mul_f32_e32 v132, v141, v135
	v_mul_f32_e32 v132, s101, v132
	v_rndne_f32_e32 v135, v132
	v_add_f32_e32 v132, v46, v146
	v_add_f32_e32 v137, 1.0, v133
	v_add_f32_e32 v133, v47, v147
	v_med3_f32 v132, v132, s6, v191
	v_med3_f32 v133, v133, s6, v191
	v_mul_f32_e32 v132, s100, v132
	v_mul_f32_e32 v133, s100, v133
	v_exp_f32_e32 v132, v132
	v_exp_f32_e32 v133, v133
	v_mul_f32_e32 v134, s100, v134
	v_exp_f32_e32 v141, v134
	v_pk_add_f32 v[132:133], v[132:133], 1.0 op_sel_hi:[1,0]
	v_cvt_f16_f32_e32 v142, v135
	v_mul_f32_e32 v134, v132, v137
	v_rcp_f32_e32 v134, v134
	v_add_f32_e32 v141, 1.0, v141
	v_mul_f32_e32 v135, v137, v134
	v_mul_f32_e32 v137, s101, v135
	v_mul_f32_e32 v135, v133, v141
	v_rcp_f32_e32 v135, v135
	v_rndne_f32_e32 v137, v137
	v_cvt_f16_f32_e32 v137, v137
	v_mul_f32_e32 v141, v141, v135
	v_mul_f32_e32 v141, s101, v141
	v_rndne_f32_e32 v141, v141
	v_cvt_f16_f32_e32 v141, v141
	v_pk_mul_f32 v[132:133], v[132:133], v[134:135]
	s_nop 0
	v_pk_mul_f32 v[132:133], v[132:133], v[138:139]
	s_nop 0
	v_cvt_pk_f16_f32 v132, v132, v133
	v_bfi_b32 v135, s98, v141, v132
	v_bfi_b32 v133, s98, v142, v136
	v_pack_b32_f16 v134, v137, v132
	v_pack_b32_f16 v132, v140, v136
	ds_write_b128 v158, v[132:135] offset:20480
	v_add_f32_e32 v134, v24, v148
	v_lshlrev_b32_e32 v132, 16, v128
	v_and_b32_e32 v133, s34, v128
	v_add_f32_e32 v128, v28, v144
	v_med3_f32 v134, v134, s6, v191
	v_mul_f32_e32 v134, s100, v134
	v_med3_f32 v128, v128, s6, v191
	v_exp_f32_e32 v135, v134
	v_mul_f32_e32 v128, s100, v128
	v_exp_f32_e32 v134, v128
	v_add_f32_e32 v128, v29, v145
	v_med3_f32 v128, v128, s6, v191
	v_mul_f32_e32 v128, s100, v128
	v_add_f32_e32 v138, 1.0, v135
	v_exp_f32_e32 v135, v128
	v_add_f32_e32 v136, v25, v149
	v_med3_f32 v128, v136, s6, v191
	v_mul_f32_e32 v128, s100, v128
	v_pk_add_f32 v[134:135], v[134:135], 1.0 op_sel_hi:[1,0]
	v_exp_f32_e32 v139, v128
	v_mul_f32_e32 v128, v134, v138
	v_rcp_f32_e32 v128, v128
	v_lshlrev_b32_e32 v136, 16, v129
	v_and_b32_e32 v137, s34, v129
	v_add_f32_e32 v139, 1.0, v139
	v_mul_f32_e32 v129, v138, v128
	v_mul_f32_e32 v138, s101, v129
	v_mul_f32_e32 v129, v135, v139
	v_rcp_f32_e32 v129, v129
	v_rndne_f32_e32 v138, v138
	v_cvt_f16_f32_e32 v138, v138
	v_pk_mul_f32 v[134:135], v[134:135], v[128:129]
	v_mul_f32_e32 v128, v139, v129
	v_add_f32_e32 v129, v26, v150
	v_med3_f32 v129, v129, s6, v191
	v_mul_f32_e32 v129, s100, v129
	v_exp_f32_e32 v129, v129
	v_pk_mul_f32 v[132:133], v[134:135], v[132:133]
	v_mul_f32_e32 v128, s101, v128
	v_cvt_pk_f16_f32 v140, v132, v133
	v_rndne_f32_e32 v133, v128
	v_add_f32_e32 v128, v30, v146
	v_add_f32_e32 v134, 1.0, v129
	v_add_f32_e32 v129, v31, v147
	v_med3_f32 v128, v128, s6, v191
	v_med3_f32 v129, v129, s6, v191
	v_mul_f32_e32 v128, s100, v128
	v_mul_f32_e32 v129, s100, v129
	v_exp_f32_e32 v128, v128
	v_exp_f32_e32 v129, v129
	v_add_f32_e32 v132, v27, v151
	v_med3_f32 v132, v132, s6, v191
	v_mul_f32_e32 v132, s100, v132
	v_pk_add_f32 v[128:129], v[128:129], 1.0 op_sel_hi:[1,0]
	v_exp_f32_e32 v135, v132
	v_mul_f32_e32 v132, v128, v134
	v_rcp_f32_e32 v132, v132
	v_cvt_f16_f32_e32 v139, v133
	v_add_f32_e32 v135, 1.0, v135
	v_mul_f32_e32 v133, v134, v132
	v_mul_f32_e32 v134, s101, v133
	v_mul_f32_e32 v133, v129, v135
	v_rcp_f32_e32 v133, v133
	v_rndne_f32_e32 v134, v134
	v_cvt_f16_f32_e32 v134, v134
	v_mul_f32_e32 v135, v135, v133
	v_mul_f32_e32 v135, s101, v135
	v_rndne_f32_e32 v135, v135
	v_cvt_f16_f32_e32 v135, v135
	v_pk_mul_f32 v[128:129], v[128:129], v[132:133]
	v_bfi_b32 v133, s98, v139, v140
	v_pk_mul_f32 v[128:129], v[128:129], v[136:137]
	v_pack_b32_f16 v132, v138, v140
	v_cvt_pk_f16_f32 v128, v128, v129
	v_bfi_b32 v135, s98, v135, v128
	v_pack_b32_f16 v134, v134, v128
	ds_write_b128 v158, v[132:135] offset:24576
	v_add_f32_e32 v132, v8, v148
	v_lshlrev_b32_e32 v128, 16, v130
	v_and_b32_e32 v129, s34, v130
	v_add_f32_e32 v130, v12, v144
	v_med3_f32 v132, v132, s6, v191
	v_mul_f32_e32 v132, s100, v132
	v_med3_f32 v130, v130, s6, v191
	v_exp_f32_e32 v133, v132
	v_mul_f32_e32 v130, s100, v130
	v_exp_f32_e32 v132, v130
	v_add_f32_e32 v130, v13, v145
	v_med3_f32 v130, v130, s6, v191
	v_mul_f32_e32 v130, s100, v130
	v_add_f32_e32 v136, 1.0, v133
	v_exp_f32_e32 v133, v130
	v_add_f32_e32 v134, v9, v149
	v_med3_f32 v130, v134, s6, v191
	v_mul_f32_e32 v130, s100, v130
	v_pk_add_f32 v[132:133], v[132:133], 1.0 op_sel_hi:[1,0]
	v_exp_f32_e32 v137, v130
	v_mul_f32_e32 v130, v132, v136
	v_rcp_f32_e32 v130, v130
	v_lshlrev_b32_e32 v134, 16, v131
	v_and_b32_e32 v135, s34, v131
	v_add_f32_e32 v137, 1.0, v137
	v_mul_f32_e32 v131, v136, v130
	v_mul_f32_e32 v136, s101, v131
	v_mul_f32_e32 v131, v133, v137
	v_rcp_f32_e32 v131, v131
	v_rndne_f32_e32 v136, v136
	v_cvt_f16_f32_e32 v136, v136
	v_pk_mul_f32 v[132:133], v[132:133], v[130:131]
	v_add_f32_e32 v130, v11, v151
	v_pk_mul_f32 v[128:129], v[132:133], v[128:129]
	v_med3_f32 v130, v130, s6, v191
	v_cvt_pk_f16_f32 v132, v128, v129
	v_add_f32_e32 v129, v10, v150
	v_med3_f32 v129, v129, s6, v191
	v_mul_f32_e32 v129, s100, v129
	v_exp_f32_e32 v129, v129
	v_mul_f32_e32 v128, v137, v131
	v_mul_f32_e32 v128, s101, v128
	v_rndne_f32_e32 v131, v128
	v_add_f32_e32 v128, v14, v146
	v_add_f32_e32 v133, 1.0, v129
	v_add_f32_e32 v129, v15, v147
	v_med3_f32 v128, v128, s6, v191
	v_med3_f32 v129, v129, s6, v191
	v_mul_f32_e32 v128, s100, v128
	v_mul_f32_e32 v129, s100, v129
	v_exp_f32_e32 v128, v128
	v_exp_f32_e32 v129, v129
	v_mul_f32_e32 v130, s100, v130
	v_exp_f32_e32 v137, v130
	v_pk_add_f32 v[128:129], v[128:129], 1.0 op_sel_hi:[1,0]
	v_cvt_f16_f32_e32 v138, v131
	v_mul_f32_e32 v130, v128, v133
	v_rcp_f32_e32 v130, v130
	v_add_f32_e32 v137, 1.0, v137
	v_mul_f32_e32 v131, v133, v130
	v_mul_f32_e32 v133, s101, v131
	v_mul_f32_e32 v131, v129, v137
	v_rcp_f32_e32 v131, v131
	v_rndne_f32_e32 v133, v133
	v_cvt_f16_f32_e32 v133, v133
	v_mul_f32_e32 v137, v137, v131
	v_mul_f32_e32 v137, s101, v137
	v_rndne_f32_e32 v137, v137
	v_cvt_f16_f32_e32 v137, v137
	v_pk_mul_f32 v[128:129], v[128:129], v[130:131]
	s_nop 0
	v_pk_mul_f32 v[128:129], v[128:129], v[134:135]
	s_nop 0
	v_cvt_pk_f16_f32 v128, v128, v129
	v_bfi_b32 v131, s98, v137, v128
	v_bfi_b32 v129, s98, v138, v132
	v_pack_b32_f16 v130, v133, v128
	v_pack_b32_f16 v128, v136, v132
	ds_write_b128 v158, v[128:131] offset:28672
	v_cndmask_b32_e64 v128, v200, v156, s[4:5]
	v_and_b32_e32 v140, 7, v128
	v_ashrrev_i32_e32 v136, 3, v128
	v_lshlrev_b32_e32 v133, 1, v140
	v_lshl_add_u32 v132, v136, 8, v192
	v_bitop3_b32 v128, v133, v136, 15 bitop3:0x78
	v_lshl_or_b32 v128, v128, 4, v132
	s_waitcnt lgkmcnt(0)
	s_barrier
	ds_read_b128 v[128:131], v128
	v_and_b32_e32 v134, 15, v136
	v_bitop3_b32 v133, v133, v134, 1 bitop3:0x36
	v_lshl_or_b32 v132, v133, 4, v132
	ds_read_b128 v[132:135], v132
	s_waitcnt lgkmcnt(0)
	v_cvt_f32_f16_e32 v137, v128
	v_cvt_f32_f16_e32 v138, v129
	v_cvt_f32_f16_e32 v139, v130
	v_cvt_f32_f16_e32 v141, v131
	v_cvt_u32_f32_e32 v137, v137
	v_cvt_u32_f32_e32 v138, v138
	v_cvt_u32_f32_sdwa v139, v139 dst_sel:WORD_1 dst_unused:UNUSED_PAD src0_sel:DWORD
	v_cvt_u32_f32_sdwa v141, v141 dst_sel:BYTE_3 dst_unused:UNUSED_PAD src0_sel:DWORD
	v_and_b32_e32 v131, s34, v131
	v_and_b32_e32 v142, s34, v129
	v_lshl_or_b32 v129, v138, 8, v137
	v_or3_b32 v138, v129, v139, v141
	v_or_b32_sdwa v129, v131, v130 dst_sel:DWORD dst_unused:UNUSED_PAD src0_sel:DWORD src1_sel:WORD_1
	v_cvt_f32_f16_e32 v130, v132
	v_cvt_f32_f16_e32 v131, v133
	v_cvt_f32_f16_e32 v137, v134
	v_cvt_f32_f16_e32 v139, v135
	v_cvt_u32_f32_e32 v130, v130
	v_cvt_u32_f32_e32 v131, v131
	v_cvt_u32_f32_sdwa v137, v137 dst_sel:WORD_1 dst_unused:UNUSED_PAD src0_sel:DWORD
	v_cvt_u32_f32_sdwa v139, v139 dst_sel:BYTE_3 dst_unused:UNUSED_PAD src0_sel:DWORD
	v_and_b32_e32 v133, s34, v133
	v_lshl_or_b32 v130, v131, 8, v130
	v_and_b32_e32 v135, s34, v135
	v_or3_b32 v139, v130, v137, v139
	v_ashrrev_i32_e32 v137, 31, v136
	v_or_b32_sdwa v130, v133, v132 dst_sel:DWORD dst_unused:UNUSED_PAD src0_sel:DWORD src1_sel:WORD_1
	v_lshlrev_b64 v[132:133], 10, v[136:137]
	v_or_b32_sdwa v131, v135, v134 dst_sel:DWORD dst_unused:UNUSED_PAD src0_sel:DWORD src1_sel:WORD_1
	v_lshl_add_u64 v[132:133], s[12:13], 0, v[132:133]
	v_lshlrev_b32_e32 v134, 3, v140
	v_mov_b32_e32 v135, v164
	v_lshl_add_u64 v[132:133], v[132:133], 0, v[134:135]
	global_store_dwordx2 v[132:133], v[138:139], off
	v_lshlrev_b32_e32 v132, 4, v140
	v_or_b32_sdwa v128, v142, v128 dst_sel:DWORD dst_unused:UNUSED_PAD src0_sel:DWORD src1_sel:WORD_1
	v_lshl_or_b32 v132, v136, 11, v132
	buffer_store_dwordx4 v[128:131], v132, s[8:11], 0 offen sc1
	s_nop 1
	v_add_u32_e32 v128, 0x200, v156
	v_cndmask_b32_e64 v128, v128, v200, s[4:5]
	v_and_b32_e32 v140, 7, v128
	v_ashrrev_i32_e32 v136, 3, v128
	v_lshlrev_b32_e32 v132, 1, v140
	v_bitop3_b32 v128, v132, v136, 15 bitop3:0x78
	v_lshl_add_u32 v197, v136, 8, v192
	v_lshlrev_b32_e32 v199, 4, v128
	v_or_b32_e32 v128, v197, v199
	ds_read_b128 v[128:131], v128
	v_and_b32_e32 v133, 15, v136
	v_bitop3_b32 v132, v132, v133, 1 bitop3:0x36
	v_lshlrev_b32_e32 v198, 4, v132
	v_or_b32_e32 v132, v197, v198
	ds_read_b128 v[132:135], v132
	s_waitcnt lgkmcnt(1)
	v_cvt_f32_f16_e32 v137, v128
	v_cvt_f32_f16_e32 v138, v129
	v_cvt_f32_f16_e32 v139, v130
	v_cvt_f32_f16_e32 v141, v131
	v_cvt_u32_f32_e32 v137, v137
	v_cvt_u32_f32_e32 v138, v138
	v_cvt_u32_f32_sdwa v139, v139 dst_sel:WORD_1 dst_unused:UNUSED_PAD src0_sel:DWORD
	v_cvt_u32_f32_sdwa v141, v141 dst_sel:BYTE_3 dst_unused:UNUSED_PAD src0_sel:DWORD
	v_and_b32_e32 v131, s34, v131
	v_and_b32_e32 v142, s34, v129
	v_lshl_or_b32 v129, v138, 8, v137
	v_or3_b32 v138, v129, v139, v141
	v_or_b32_sdwa v129, v131, v130 dst_sel:DWORD dst_unused:UNUSED_PAD src0_sel:DWORD src1_sel:WORD_1
	s_waitcnt lgkmcnt(0)
	v_cvt_f32_f16_e32 v130, v132
	v_cvt_f32_f16_e32 v131, v133
	v_cvt_f32_f16_e32 v137, v134
	v_cvt_f32_f16_e32 v139, v135
	v_cvt_u32_f32_e32 v130, v130
	v_cvt_u32_f32_e32 v131, v131
	v_cvt_u32_f32_sdwa v137, v137 dst_sel:WORD_1 dst_unused:UNUSED_PAD src0_sel:DWORD
	v_cvt_u32_f32_sdwa v139, v139 dst_sel:BYTE_3 dst_unused:UNUSED_PAD src0_sel:DWORD
	v_and_b32_e32 v133, s34, v133
	v_lshl_or_b32 v130, v131, 8, v130
	v_and_b32_e32 v135, s34, v135
	v_or3_b32 v139, v130, v137, v139
	v_ashrrev_i32_e32 v137, 31, v136
	v_or_b32_sdwa v130, v133, v132 dst_sel:DWORD dst_unused:UNUSED_PAD src0_sel:DWORD src1_sel:WORD_1
	v_lshlrev_b64 v[132:133], 10, v[136:137]
	v_or_b32_sdwa v131, v135, v134 dst_sel:DWORD dst_unused:UNUSED_PAD src0_sel:DWORD src1_sel:WORD_1
	v_lshl_add_u64 v[132:133], s[12:13], 0, v[132:133]
	v_lshlrev_b32_e32 v134, 3, v140
	v_mov_b32_e32 v135, v164
	v_lshl_add_u64 v[150:151], v[132:133], 0, v[134:135]
	v_lshlrev_b32_e32 v132, 4, v140
	v_or_b32_sdwa v128, v142, v128 dst_sel:DWORD dst_unused:UNUSED_PAD src0_sel:DWORD src1_sel:WORD_1
	v_lshl_or_b32 v196, v136, 11, v132
	global_store_dwordx2 v[150:151], v[138:139], off
	buffer_store_dwordx4 v[128:131], v196, s[8:11], 0 offen sc1
	v_add_u32_e32 v132, 0x600, v156
	v_ashrrev_i32_e32 v142, 3, v132
	v_add_u32_e32 v128, 0x300, v156
	v_and_b32_e32 v129, 7, v157
	v_add_u32_e32 v130, 0x400, v156
	v_add_u32_e32 v131, 0x500, v156
	v_ashrrev_i32_e32 v148, 3, v128
	v_lshlrev_b32_e32 v160, 1, v129
	v_lshlrev_b32_e32 v140, 3, v129
	v_lshlrev_b32_e32 v159, 4, v129
	v_ashrrev_i32_e32 v146, 3, v130
	v_ashrrev_i32_e32 v144, 3, v131
	s_and_saveexec_b64 s[4:5], vcc
	s_xor_b64 s[4:5], exec, s[4:5]
	s_cbranch_execz .LBB0_459
	v_lshl_add_u32 v129, v148, 8, v192
	v_bitop3_b32 v128, v148, v160, 15 bitop3:0x6c
	v_lshl_or_b32 v130, v128, 4, v129
	v_or_b32_e32 v128, 1, v160
	v_bitop3_b32 v131, v148, v128, 15 bitop3:0x6c
	v_lshl_or_b32 v129, v131, 4, v129
	ds_read_b128 v[130:133], v130
	v_ashrrev_i32_e32 v149, 31, v148
	v_mov_b32_e32 v141, v164
	v_ashrrev_i32_e32 v147, 31, v146
	v_ashrrev_i32_e32 v145, 31, v144
	s_waitcnt lgkmcnt(0)
	v_and_b32_e32 v135, s34, v131
	v_cvt_f32_f16_e32 v136, v130
	v_cvt_f32_f16_e32 v131, v131
	v_and_b32_e32 v134, s34, v133
	v_cvt_f32_f16_e32 v137, v132
	v_cvt_f32_f16_e32 v133, v133
	v_cvt_u32_f32_e32 v136, v136
	v_cvt_u32_f32_e32 v131, v131
	v_cvt_u32_f32_sdwa v137, v137 dst_sel:WORD_1 dst_unused:UNUSED_PAD src0_sel:DWORD
	v_cvt_u32_f32_sdwa v133, v133 dst_sel:BYTE_3 dst_unused:UNUSED_PAD src0_sel:DWORD
	v_or_b32_sdwa v130, v135, v130 dst_sel:DWORD dst_unused:UNUSED_PAD src0_sel:DWORD src1_sel:WORD_1
	v_lshl_or_b32 v131, v131, 8, v136
	v_ashrrev_i32_e32 v143, 31, v142
	v_or3_b32 v136, v131, v137, v133
	v_or_b32_sdwa v131, v134, v132 dst_sel:DWORD dst_unused:UNUSED_PAD src0_sel:DWORD src1_sel:WORD_1
	ds_read_b128 v[132:135], v129
	s_waitcnt lgkmcnt(0)
	v_and_b32_e32 v138, s34, v133
	v_cvt_f32_f16_e32 v137, v132
	v_cvt_f32_f16_e32 v133, v133
	v_and_b32_e32 v129, s34, v135
	v_cvt_f32_f16_e32 v139, v134
	v_cvt_f32_f16_e32 v135, v135
	v_cvt_u32_f32_e32 v137, v137
	v_cvt_u32_f32_e32 v133, v133
	v_cvt_u32_f32_sdwa v139, v139 dst_sel:WORD_1 dst_unused:UNUSED_PAD src0_sel:DWORD
	v_cvt_u32_f32_sdwa v135, v135 dst_sel:BYTE_3 dst_unused:UNUSED_PAD src0_sel:DWORD
	v_or_b32_sdwa v132, v138, v132 dst_sel:DWORD dst_unused:UNUSED_PAD src0_sel:DWORD src1_sel:WORD_1
	v_lshl_or_b32 v133, v133, 8, v137
	v_or3_b32 v137, v133, v139, v135
	v_or_b32_sdwa v133, v129, v134 dst_sel:DWORD dst_unused:UNUSED_PAD src0_sel:DWORD src1_sel:WORD_1
	v_lshlrev_b64 v[134:135], 10, v[148:149]
	v_lshl_add_u64 v[134:135], s[12:13], 0, v[134:135]
	v_lshl_add_u64 v[134:135], v[134:135], 0, v[140:141]
	v_lshl_or_b32 v129, v148, 11, v159
	global_store_dwordx2 v[134:135], v[136:137], off
	buffer_store_dwordx4 v[130:133], v129, s[8:11], 0 offen sc1
	v_lshl_add_u32 v129, v146, 8, v192
	s_nop 0
	v_bitop3_b32 v130, v146, v160, 15 bitop3:0x6c
	v_lshl_or_b32 v130, v130, 4, v129
	v_bitop3_b32 v131, v146, v128, 15 bitop3:0x6c
	v_lshl_or_b32 v129, v131, 4, v129
	ds_read_b128 v[130:133], v130
	s_waitcnt lgkmcnt(0)
	v_and_b32_e32 v135, s34, v131
	v_cvt_f32_f16_e32 v136, v130
	v_cvt_f32_f16_e32 v131, v131
	v_and_b32_e32 v134, s34, v133
	v_cvt_f32_f16_e32 v137, v132
	v_cvt_f32_f16_e32 v133, v133
	v_cvt_u32_f32_e32 v136, v136
	v_cvt_u32_f32_e32 v131, v131
	v_cvt_u32_f32_sdwa v137, v137 dst_sel:WORD_1 dst_unused:UNUSED_PAD src0_sel:DWORD
	v_cvt_u32_f32_sdwa v133, v133 dst_sel:BYTE_3 dst_unused:UNUSED_PAD src0_sel:DWORD
	v_or_b32_sdwa v130, v135, v130 dst_sel:DWORD dst_unused:UNUSED_PAD src0_sel:DWORD src1_sel:WORD_1
	v_lshl_or_b32 v131, v131, 8, v136
	v_or3_b32 v136, v131, v137, v133
	v_or_b32_sdwa v131, v134, v132 dst_sel:DWORD dst_unused:UNUSED_PAD src0_sel:DWORD src1_sel:WORD_1
	ds_read_b128 v[132:135], v129
	s_waitcnt lgkmcnt(0)
	v_and_b32_e32 v138, s34, v133
	v_cvt_f32_f16_e32 v137, v132
	v_cvt_f32_f16_e32 v133, v133
	v_and_b32_e32 v129, s34, v135
	v_cvt_f32_f16_e32 v139, v134
	v_cvt_f32_f16_e32 v135, v135
	v_cvt_u32_f32_e32 v137, v137
	v_cvt_u32_f32_e32 v133, v133
	v_cvt_u32_f32_sdwa v139, v139 dst_sel:WORD_1 dst_unused:UNUSED_PAD src0_sel:DWORD
	v_cvt_u32_f32_sdwa v135, v135 dst_sel:BYTE_3 dst_unused:UNUSED_PAD src0_sel:DWORD
	v_or_b32_sdwa v132, v138, v132 dst_sel:DWORD dst_unused:UNUSED_PAD src0_sel:DWORD src1_sel:WORD_1
	v_lshl_or_b32 v133, v133, 8, v137
	v_or3_b32 v137, v133, v139, v135
	v_or_b32_sdwa v133, v129, v134 dst_sel:DWORD dst_unused:UNUSED_PAD src0_sel:DWORD src1_sel:WORD_1
	v_lshlrev_b64 v[134:135], 10, v[146:147]
	v_lshl_add_u64 v[134:135], s[12:13], 0, v[134:135]
	v_lshl_add_u64 v[134:135], v[134:135], 0, v[140:141]
	v_lshl_or_b32 v129, v146, 11, v159
	global_store_dwordx2 v[134:135], v[136:137], off
	buffer_store_dwordx4 v[130:133], v129, s[8:11], 0 offen sc1
	v_lshl_add_u32 v129, v144, 8, v192
	s_nop 0
	v_bitop3_b32 v130, v144, v160, 15 bitop3:0x6c
	v_lshl_or_b32 v130, v130, 4, v129
	v_bitop3_b32 v131, v144, v128, 15 bitop3:0x6c
	v_lshl_or_b32 v129, v131, 4, v129
	ds_read_b128 v[130:133], v130
	v_bitop3_b32 v128, v142, v128, 15 bitop3:0x6c
	s_waitcnt lgkmcnt(0)
	v_and_b32_e32 v135, s34, v131
	v_cvt_f32_f16_e32 v136, v130
	v_cvt_f32_f16_e32 v131, v131
	v_and_b32_e32 v134, s34, v133
	v_cvt_f32_f16_e32 v137, v132
	v_cvt_f32_f16_e32 v133, v133
	v_cvt_u32_f32_e32 v136, v136
	v_cvt_u32_f32_e32 v131, v131
	v_cvt_u32_f32_sdwa v137, v137 dst_sel:WORD_1 dst_unused:UNUSED_PAD src0_sel:DWORD
	v_cvt_u32_f32_sdwa v133, v133 dst_sel:BYTE_3 dst_unused:UNUSED_PAD src0_sel:DWORD
	v_or_b32_sdwa v130, v135, v130 dst_sel:DWORD dst_unused:UNUSED_PAD src0_sel:DWORD src1_sel:WORD_1
	v_lshl_or_b32 v131, v131, 8, v136
	v_or3_b32 v136, v131, v137, v133
	v_or_b32_sdwa v131, v134, v132 dst_sel:DWORD dst_unused:UNUSED_PAD src0_sel:DWORD src1_sel:WORD_1
	ds_read_b128 v[132:135], v129
	s_waitcnt lgkmcnt(0)
	v_and_b32_e32 v138, s34, v133
	v_cvt_f32_f16_e32 v137, v132
	v_cvt_f32_f16_e32 v133, v133
	v_and_b32_e32 v129, s34, v135
	v_cvt_f32_f16_e32 v139, v134
	v_cvt_f32_f16_e32 v135, v135
	v_cvt_u32_f32_e32 v137, v137
	v_cvt_u32_f32_e32 v133, v133
	v_cvt_u32_f32_sdwa v139, v139 dst_sel:WORD_1 dst_unused:UNUSED_PAD src0_sel:DWORD
	v_cvt_u32_f32_sdwa v135, v135 dst_sel:BYTE_3 dst_unused:UNUSED_PAD src0_sel:DWORD
	v_or_b32_sdwa v132, v138, v132 dst_sel:DWORD dst_unused:UNUSED_PAD src0_sel:DWORD src1_sel:WORD_1
	v_lshl_or_b32 v133, v133, 8, v137
	v_or3_b32 v137, v133, v139, v135
	v_or_b32_sdwa v133, v129, v134 dst_sel:DWORD dst_unused:UNUSED_PAD src0_sel:DWORD src1_sel:WORD_1
	v_lshlrev_b64 v[134:135], 10, v[144:145]
	v_lshl_add_u64 v[134:135], s[12:13], 0, v[134:135]
	v_lshl_add_u64 v[134:135], v[134:135], 0, v[140:141]
	v_lshl_or_b32 v129, v144, 11, v159
	global_store_dwordx2 v[134:135], v[136:137], off
	buffer_store_dwordx4 v[130:133], v129, s[8:11], 0 offen sc1
	v_lshl_add_u32 v129, v142, 8, v192
	s_nop 0
	v_bitop3_b32 v130, v142, v160, 15 bitop3:0x6c
	v_lshl_or_b32 v130, v130, 4, v129
	v_lshl_or_b32 v132, v128, 4, v129
	ds_read_b128 v[128:131], v130
	s_waitcnt lgkmcnt(0)
	v_and_b32_e32 v135, s34, v129
	v_cvt_f32_f16_e32 v134, v128
	v_cvt_f32_f16_e32 v129, v129
	v_and_b32_e32 v133, s34, v131
	v_cvt_f32_f16_e32 v136, v130
	v_cvt_f32_f16_e32 v131, v131
	v_cvt_u32_f32_e32 v134, v134
	v_cvt_u32_f32_e32 v129, v129
	v_cvt_u32_f32_sdwa v136, v136 dst_sel:WORD_1 dst_unused:UNUSED_PAD src0_sel:DWORD
	v_cvt_u32_f32_sdwa v131, v131 dst_sel:BYTE_3 dst_unused:UNUSED_PAD src0_sel:DWORD
	v_or_b32_sdwa v128, v135, v128 dst_sel:DWORD dst_unused:UNUSED_PAD src0_sel:DWORD src1_sel:WORD_1
	v_lshl_or_b32 v129, v129, 8, v134
	v_or3_b32 v134, v129, v136, v131
	v_or_b32_sdwa v129, v133, v130 dst_sel:DWORD dst_unused:UNUSED_PAD src0_sel:DWORD src1_sel:WORD_1
	ds_read_b128 v[130:133], v132
	s_waitcnt lgkmcnt(0)
	v_and_b32_e32 v137, s34, v131
	v_cvt_f32_f16_e32 v135, v130
	v_cvt_f32_f16_e32 v131, v131
	v_and_b32_e32 v136, s34, v133
	v_cvt_f32_f16_e32 v138, v132
	v_cvt_f32_f16_e32 v133, v133
	v_cvt_u32_f32_e32 v135, v135
	v_cvt_u32_f32_e32 v131, v131
	v_cvt_u32_f32_sdwa v138, v138 dst_sel:WORD_1 dst_unused:UNUSED_PAD src0_sel:DWORD
	v_cvt_u32_f32_sdwa v133, v133 dst_sel:BYTE_3 dst_unused:UNUSED_PAD src0_sel:DWORD
	v_or_b32_sdwa v130, v137, v130 dst_sel:DWORD dst_unused:UNUSED_PAD src0_sel:DWORD src1_sel:WORD_1
	v_lshl_or_b32 v131, v131, 8, v135
	v_or3_b32 v135, v131, v138, v133
	v_or_b32_sdwa v131, v136, v132 dst_sel:DWORD dst_unused:UNUSED_PAD src0_sel:DWORD src1_sel:WORD_1
	v_lshlrev_b64 v[132:133], 10, v[142:143]
	v_lshl_add_u64 v[132:133], s[12:13], 0, v[132:133]
	v_lshl_add_u64 v[132:133], v[132:133], 0, v[140:141]
	global_store_dwordx2 v[132:133], v[134:135], off
	v_lshl_or_b32 v132, v142, 11, v159
	buffer_store_dwordx4 v[128:131], v132, s[8:11], 0 offen sc1

.LBB0_463:
	s_mov_b32 s34, 0xffff0000
	s_mov_b32 s100, 0xbfb8aa3b
	s_mov_b32 s101, 0x437f0000
	s_or_b64 exec, exec, s[16:17]
	s_waitcnt lgkmcnt(0)
	s_barrier
	global_load_dwordx4 v[132:135], v[152:153], off offset:256
	global_load_dwordx4 v[128:131], v[154:155], off offset:256
	v_lshlrev_b32_e32 v152, 16, v180
	v_and_b32_e32 v153, s34, v180
	v_lshlrev_b32_e32 v154, 16, v181
	v_and_b32_e32 v155, s34, v181
	s_waitcnt vmcnt(1)
	v_add_f32_e32 v147, v116, v132
	v_med3_f32 v147, v147, s6, v191
	s_waitcnt vmcnt(0)
	v_add_f32_e32 v149, v112, v128
	v_med3_f32 v149, v149, s6, v191
	v_mul_f32_e32 v147, s100, v147
	v_exp_f32_e32 v156, v147
	v_mul_f32_e32 v147, s100, v149
	v_add_f32_e32 v149, v117, v133
	v_med3_f32 v149, v149, s6, v191
	v_add_f32_e32 v157, v113, v129
	v_med3_f32 v180, v157, s6, v191
	v_mul_f32_e32 v149, s100, v149
	v_exp_f32_e32 v157, v149
	v_mul_f32_e32 v149, s100, v180
	v_exp_f32_e32 v147, v147
	v_exp_f32_e32 v149, v149
	v_pk_add_f32 v[156:157], v[156:157], 1.0 op_sel_hi:[1,0]
	v_add_f32_e32 v147, 1.0, v147
	v_add_f32_e32 v149, 1.0, v149
	v_mul_f32_e32 v180, v156, v147
	v_mul_f32_e32 v181, v157, v149
	v_rcp_f32_e32 v180, v180
	v_rcp_f32_e32 v181, v181
	v_mul_f32_e32 v147, v147, v180
	v_pk_mul_f32 v[156:157], v[156:157], v[180:181]
	v_mul_f32_e32 v149, v149, v181
	v_pk_mul_f32 v[152:153], v[156:157], v[152:153]
	v_add_f32_e32 v156, v115, v131
	v_cvt_pk_f16_f32 v180, v152, v153
	v_add_f32_e32 v153, v114, v130
	v_med3_f32 v153, v153, s6, v191
	v_mul_f32_e32 v153, s100, v153
	v_exp_f32_e32 v153, v153
	v_add_f32_e32 v152, v118, v134
	v_med3_f32 v152, v152, s6, v191
	v_mul_f32_e32 v152, s100, v152
	v_add_f32_e32 v157, 1.0, v153
	v_add_f32_e32 v153, v119, v135
	v_med3_f32 v153, v153, s6, v191
	v_med3_f32 v156, v156, s6, v191
	v_mul_f32_e32 v153, s100, v153
	v_exp_f32_e32 v152, v152
	v_exp_f32_e32 v153, v153
	v_mul_f32_e32 v156, s100, v156
	v_exp_f32_e32 v156, v156
	v_mul_f32_e32 v147, s101, v147
	v_pk_add_f32 v[152:153], v[152:153], 1.0 op_sel_hi:[1,0]
	v_rndne_f32_e32 v147, v147
	v_add_f32_e32 v181, 1.0, v156
	v_mul_f32_e32 v156, v152, v157
	v_rcp_f32_e32 v156, v156
	v_mul_f32_e32 v149, s101, v149
	v_rndne_f32_e32 v149, v149
	v_mul_f32_e32 v157, v157, v156
	v_mul_f32_e32 v157, s101, v157
	v_rndne_f32_e32 v157, v157
	v_cvt_f16_f32_e32 v201, v157
	v_mul_f32_e32 v157, v153, v181
	v_rcp_f32_e32 v157, v157
	v_cvt_f16_f32_e32 v147, v147
	v_cvt_f16_f32_e32 v149, v149
	v_pk_mul_f32 v[152:153], v[152:153], v[156:157]
	s_nop 0
	v_pk_mul_f32 v[152:153], v[152:153], v[154:155]
	s_nop 0
	v_cvt_pk_f16_f32 v152, v152, v153
	v_mul_f32_e32 v153, v181, v157
	v_mul_f32_e32 v153, s101, v153
	v_rndne_f32_e32 v153, v153
	v_cvt_f16_f32_e32 v153, v153
	v_pack_b32_f16 v154, v201, v152
	v_add_f32_e32 v157, v97, v129
	v_bfi_b32 v155, s98, v153, v152
	v_pack_b32_f16 v152, v147, v180
	v_add_f32_e32 v147, v100, v132
	v_bfi_b32 v153, s98, v149, v180
	v_med3_f32 v147, v147, s6, v191
	v_add_f32_e32 v149, v96, v128
	v_med3_f32 v149, v149, s6, v191
	v_mul_f32_e32 v147, s100, v147
	v_exp_f32_e32 v156, v147
	v_mul_f32_e32 v147, s100, v149
	v_add_f32_e32 v149, v101, v133
	v_med3_f32 v149, v149, s6, v191
	ds_write_b128 v158, v[152:155]
	v_lshlrev_b32_e32 v154, 16, v178
	v_and_b32_e32 v155, s34, v178
	v_med3_f32 v178, v157, s6, v191
	v_mul_f32_e32 v149, s100, v149
	v_exp_f32_e32 v157, v149
	v_mul_f32_e32 v149, s100, v178
	v_exp_f32_e32 v147, v147
	v_exp_f32_e32 v149, v149
	v_pk_add_f32 v[156:157], v[156:157], 1.0 op_sel_hi:[1,0]
	v_lshlrev_b32_e32 v152, 16, v179
	v_add_f32_e32 v147, 1.0, v147
	v_add_f32_e32 v149, 1.0, v149
	v_and_b32_e32 v153, s34, v179
	v_mul_f32_e32 v178, v156, v147
	v_mul_f32_e32 v179, v157, v149
	v_rcp_f32_e32 v178, v178
	v_rcp_f32_e32 v179, v179
	v_mul_f32_e32 v147, v147, v178
	v_pk_mul_f32 v[156:157], v[156:157], v[178:179]
	v_mul_f32_e32 v149, v149, v179
	v_pk_mul_f32 v[154:155], v[156:157], v[154:155]
	v_add_f32_e32 v156, v99, v131
	v_cvt_pk_f16_f32 v178, v154, v155
	v_add_f32_e32 v155, v98, v130
	v_med3_f32 v155, v155, s6, v191
	v_mul_f32_e32 v155, s100, v155
	v_exp_f32_e32 v155, v155
	v_add_f32_e32 v154, v102, v134
	v_med3_f32 v154, v154, s6, v191
	v_mul_f32_e32 v154, s100, v154
	v_add_f32_e32 v157, 1.0, v155
	v_add_f32_e32 v155, v103, v135
	v_med3_f32 v155, v155, s6, v191
	v_med3_f32 v156, v156, s6, v191
	v_mul_f32_e32 v155, s100, v155
	v_exp_f32_e32 v154, v154
	v_exp_f32_e32 v155, v155
	v_mul_f32_e32 v156, s100, v156
	v_exp_f32_e32 v156, v156
	v_mul_f32_e32 v147, s101, v147
	v_pk_add_f32 v[154:155], v[154:155], 1.0 op_sel_hi:[1,0]
	v_rndne_f32_e32 v147, v147
	v_add_f32_e32 v179, 1.0, v156
	v_mul_f32_e32 v156, v154, v157
	v_rcp_f32_e32 v156, v156
	v_mul_f32_e32 v149, s101, v149
	v_rndne_f32_e32 v149, v149
	v_mul_f32_e32 v157, v157, v156
	v_mul_f32_e32 v157, s101, v157
	v_rndne_f32_e32 v157, v157
	v_cvt_f16_f32_e32 v180, v157
	v_mul_f32_e32 v157, v155, v179
	v_rcp_f32_e32 v157, v157
	v_cvt_f16_f32_e32 v147, v147
	v_cvt_f16_f32_e32 v149, v149
	v_pk_mul_f32 v[154:155], v[154:155], v[156:157]
	s_nop 0
	v_pk_mul_f32 v[152:153], v[154:155], v[152:153]
	s_nop 0
	v_cvt_pk_f16_f32 v152, v152, v153
	v_mul_f32_e32 v153, v179, v157
	v_mul_f32_e32 v153, s101, v153
	v_rndne_f32_e32 v153, v153
	v_cvt_f16_f32_e32 v153, v153
	v_pack_b32_f16 v154, v180, v152
	v_add_f32_e32 v157, v81, v129
	v_bfi_b32 v155, s98, v153, v152
	v_pack_b32_f16 v152, v147, v178
	v_add_f32_e32 v147, v84, v132
	v_bfi_b32 v153, s98, v149, v178
	v_med3_f32 v147, v147, s6, v191
	v_add_f32_e32 v149, v80, v128
	v_med3_f32 v149, v149, s6, v191
	v_mul_f32_e32 v147, s100, v147
	v_exp_f32_e32 v156, v147
	v_mul_f32_e32 v147, s100, v149
	v_add_f32_e32 v149, v85, v133
	v_med3_f32 v149, v149, s6, v191
	ds_write_b128 v158, v[152:155] offset:4096
	v_lshlrev_b32_e32 v152, 16, v176
	v_and_b32_e32 v153, s34, v176
	v_med3_f32 v176, v157, s6, v191
	v_mul_f32_e32 v149, s100, v149
	v_exp_f32_e32 v157, v149
	v_mul_f32_e32 v149, s100, v176
	v_exp_f32_e32 v147, v147
	v_exp_f32_e32 v149, v149
	v_pk_add_f32 v[156:157], v[156:157], 1.0 op_sel_hi:[1,0]
	v_lshlrev_b32_e32 v154, 16, v177
	v_add_f32_e32 v147, 1.0, v147
	v_add_f32_e32 v149, 1.0, v149
	v_and_b32_e32 v155, s34, v177
	v_mul_f32_e32 v176, v156, v147
	v_mul_f32_e32 v177, v157, v149
	v_rcp_f32_e32 v176, v176
	v_rcp_f32_e32 v177, v177
	v_mul_f32_e32 v147, v147, v176
	v_pk_mul_f32 v[156:157], v[156:157], v[176:177]
	v_mul_f32_e32 v149, v149, v177
	v_pk_mul_f32 v[152:153], v[156:157], v[152:153]
	v_add_f32_e32 v156, v83, v131
	v_cvt_pk_f16_f32 v176, v152, v153
	v_add_f32_e32 v153, v82, v130
	v_med3_f32 v153, v153, s6, v191
	v_mul_f32_e32 v153, s100, v153
	v_exp_f32_e32 v153, v153
	v_add_f32_e32 v152, v86, v134
	v_med3_f32 v152, v152, s6, v191
	v_mul_f32_e32 v152, s100, v152
	v_add_f32_e32 v157, 1.0, v153
	v_add_f32_e32 v153, v87, v135
	v_med3_f32 v153, v153, s6, v191
	v_med3_f32 v156, v156, s6, v191
	v_mul_f32_e32 v153, s100, v153
	v_exp_f32_e32 v152, v152
	v_exp_f32_e32 v153, v153
	v_mul_f32_e32 v156, s100, v156
	v_exp_f32_e32 v156, v156
	v_mul_f32_e32 v147, s101, v147
	v_pk_add_f32 v[152:153], v[152:153], 1.0 op_sel_hi:[1,0]
	v_rndne_f32_e32 v147, v147
	v_add_f32_e32 v177, 1.0, v156
	v_mul_f32_e32 v156, v152, v157
	v_rcp_f32_e32 v156, v156
	v_mul_f32_e32 v149, s101, v149
	v_rndne_f32_e32 v149, v149
	v_mul_f32_e32 v157, v157, v156
	v_mul_f32_e32 v157, s101, v157
	v_rndne_f32_e32 v157, v157
	v_cvt_f16_f32_e32 v178, v157
	v_mul_f32_e32 v157, v153, v177
	v_rcp_f32_e32 v157, v157
	v_cvt_f16_f32_e32 v147, v147
	v_cvt_f16_f32_e32 v149, v149
	v_pk_mul_f32 v[152:153], v[152:153], v[156:157]
	s_nop 0
	v_pk_mul_f32 v[152:153], v[152:153], v[154:155]
	s_nop 0
	v_cvt_pk_f16_f32 v152, v152, v153
	v_mul_f32_e32 v153, v177, v157
	v_mul_f32_e32 v153, s101, v153
	v_rndne_f32_e32 v153, v153
	v_cvt_f16_f32_e32 v153, v153
	v_pack_b32_f16 v154, v178, v152
	v_add_f32_e32 v157, v65, v129
	v_bfi_b32 v155, s98, v153, v152
	v_pack_b32_f16 v152, v147, v176
	v_add_f32_e32 v147, v68, v132
	v_bfi_b32 v153, s98, v149, v176
	v_med3_f32 v147, v147, s6, v191
	v_add_f32_e32 v149, v64, v128
	v_med3_f32 v149, v149, s6, v191
	v_mul_f32_e32 v147, s100, v147
	v_exp_f32_e32 v156, v147
	v_mul_f32_e32 v147, s100, v149
	v_add_f32_e32 v149, v69, v133
	v_med3_f32 v149, v149, s6, v191
	ds_write_b128 v158, v[152:155] offset:8192
	v_lshlrev_b32_e32 v152, 16, v174
	v_and_b32_e32 v153, s34, v174
	v_med3_f32 v174, v157, s6, v191
	v_mul_f32_e32 v149, s100, v149
	v_exp_f32_e32 v157, v149
	v_mul_f32_e32 v149, s100, v174
	v_exp_f32_e32 v147, v147
	v_exp_f32_e32 v149, v149
	v_pk_add_f32 v[156:157], v[156:157], 1.0 op_sel_hi:[1,0]
	v_lshlrev_b32_e32 v154, 16, v175
	v_add_f32_e32 v147, 1.0, v147
	v_add_f32_e32 v149, 1.0, v149
	v_and_b32_e32 v155, s34, v175
	v_mul_f32_e32 v174, v156, v147
	v_mul_f32_e32 v175, v157, v149
	v_rcp_f32_e32 v174, v174
	v_rcp_f32_e32 v175, v175
	v_mul_f32_e32 v147, v147, v174
	v_pk_mul_f32 v[156:157], v[156:157], v[174:175]
	v_mul_f32_e32 v149, v149, v175
	v_pk_mul_f32 v[152:153], v[156:157], v[152:153]
	v_add_f32_e32 v156, v67, v131
	v_cvt_pk_f16_f32 v174, v152, v153
	v_add_f32_e32 v153, v66, v130
	v_med3_f32 v153, v153, s6, v191
	v_mul_f32_e32 v153, s100, v153
	v_exp_f32_e32 v153, v153
	v_add_f32_e32 v152, v70, v134
	v_med3_f32 v152, v152, s6, v191
	v_mul_f32_e32 v152, s100, v152
	v_add_f32_e32 v157, 1.0, v153
	v_add_f32_e32 v153, v71, v135
	v_med3_f32 v153, v153, s6, v191
	v_med3_f32 v156, v156, s6, v191
	v_mul_f32_e32 v153, s100, v153
	v_exp_f32_e32 v152, v152
	v_exp_f32_e32 v153, v153
	v_mul_f32_e32 v156, s100, v156
	v_exp_f32_e32 v156, v156
	v_mul_f32_e32 v147, s101, v147
	v_pk_add_f32 v[152:153], v[152:153], 1.0 op_sel_hi:[1,0]
	v_rndne_f32_e32 v147, v147
	v_add_f32_e32 v175, 1.0, v156
	v_mul_f32_e32 v156, v152, v157
	v_rcp_f32_e32 v156, v156
	v_mul_f32_e32 v149, s101, v149
	v_rndne_f32_e32 v149, v149
	v_mul_f32_e32 v157, v157, v156
	v_mul_f32_e32 v157, s101, v157
	v_rndne_f32_e32 v157, v157
	v_cvt_f16_f32_e32 v176, v157
	v_mul_f32_e32 v157, v153, v175
	v_rcp_f32_e32 v157, v157
	v_cvt_f16_f32_e32 v147, v147
	v_cvt_f16_f32_e32 v149, v149
	v_pk_mul_f32 v[152:153], v[152:153], v[156:157]
	s_nop 0
	v_pk_mul_f32 v[152:153], v[152:153], v[154:155]
	s_nop 0
	v_cvt_pk_f16_f32 v152, v152, v153
	v_mul_f32_e32 v153, v175, v157
	v_mul_f32_e32 v153, s101, v153
	v_rndne_f32_e32 v153, v153
	v_cvt_f16_f32_e32 v153, v153
	v_pack_b32_f16 v154, v176, v152
	v_add_f32_e32 v157, v49, v129
	v_bfi_b32 v155, s98, v153, v152
	v_pack_b32_f16 v152, v147, v174
	v_add_f32_e32 v147, v52, v132
	v_bfi_b32 v153, s98, v149, v174
	v_med3_f32 v147, v147, s6, v191
	v_add_f32_e32 v149, v48, v128
	v_med3_f32 v149, v149, s6, v191
	v_mul_f32_e32 v147, s100, v147
	v_exp_f32_e32 v156, v147
	v_mul_f32_e32 v147, s100, v149
	v_add_f32_e32 v149, v53, v133
	v_med3_f32 v149, v149, s6, v191
	ds_write_b128 v158, v[152:155] offset:12288
	v_lshlrev_b32_e32 v152, 16, v172
	v_and_b32_e32 v153, s34, v172
	v_med3_f32 v172, v157, s6, v191
	v_mul_f32_e32 v149, s100, v149
	v_exp_f32_e32 v157, v149
	v_mul_f32_e32 v149, s100, v172
	v_exp_f32_e32 v147, v147
	v_exp_f32_e32 v149, v149
	v_pk_add_f32 v[156:157], v[156:157], 1.0 op_sel_hi:[1,0]
	v_lshlrev_b32_e32 v154, 16, v173
	v_add_f32_e32 v147, 1.0, v147
	v_add_f32_e32 v149, 1.0, v149
	v_and_b32_e32 v155, s34, v173
	v_mul_f32_e32 v172, v156, v147
	v_mul_f32_e32 v173, v157, v149
	v_rcp_f32_e32 v172, v172
	v_rcp_f32_e32 v173, v173
	v_mul_f32_e32 v147, v147, v172
	v_pk_mul_f32 v[156:157], v[156:157], v[172:173]
	v_mul_f32_e32 v149, v149, v173
	v_pk_mul_f32 v[152:153], v[156:157], v[152:153]
	v_add_f32_e32 v156, v51, v131
	v_cvt_pk_f16_f32 v172, v152, v153
	v_add_f32_e32 v153, v50, v130
	v_med3_f32 v153, v153, s6, v191
	v_mul_f32_e32 v153, s100, v153
	v_exp_f32_e32 v153, v153
	v_add_f32_e32 v152, v54, v134
	v_med3_f32 v152, v152, s6, v191
	v_mul_f32_e32 v152, s100, v152
	v_add_f32_e32 v157, 1.0, v153
	v_add_f32_e32 v153, v55, v135
	v_med3_f32 v153, v153, s6, v191
	v_med3_f32 v156, v156, s6, v191
	v_mul_f32_e32 v153, s100, v153
	v_exp_f32_e32 v152, v152
	v_exp_f32_e32 v153, v153
	v_mul_f32_e32 v156, s100, v156
	v_exp_f32_e32 v156, v156
	v_mul_f32_e32 v147, s101, v147
	v_pk_add_f32 v[152:153], v[152:153], 1.0 op_sel_hi:[1,0]
	v_rndne_f32_e32 v147, v147
	v_add_f32_e32 v173, 1.0, v156
	v_mul_f32_e32 v156, v152, v157
	v_rcp_f32_e32 v156, v156
	v_mul_f32_e32 v149, s101, v149
	v_rndne_f32_e32 v149, v149
	v_mul_f32_e32 v157, v157, v156
	v_mul_f32_e32 v157, s101, v157
	v_rndne_f32_e32 v157, v157
	v_cvt_f16_f32_e32 v174, v157
	v_mul_f32_e32 v157, v153, v173
	v_rcp_f32_e32 v157, v157
	v_cvt_f16_f32_e32 v147, v147
	v_cvt_f16_f32_e32 v149, v149
	v_pk_mul_f32 v[152:153], v[152:153], v[156:157]
	s_nop 0
	v_pk_mul_f32 v[152:153], v[152:153], v[154:155]
	s_nop 0
	v_cvt_pk_f16_f32 v152, v152, v153
	v_mul_f32_e32 v153, v173, v157
	v_mul_f32_e32 v153, s101, v153
	v_rndne_f32_e32 v153, v153
	v_cvt_f16_f32_e32 v153, v153
	v_pack_b32_f16 v154, v174, v152
	v_add_f32_e32 v157, v33, v129
	v_bfi_b32 v155, s98, v153, v152
	v_pack_b32_f16 v152, v147, v172
	v_add_f32_e32 v147, v36, v132
	v_bfi_b32 v153, s98, v149, v172
	v_med3_f32 v147, v147, s6, v191
	v_add_f32_e32 v149, v32, v128
	v_med3_f32 v149, v149, s6, v191
	v_mul_f32_e32 v147, s100, v147
	v_exp_f32_e32 v156, v147
	v_mul_f32_e32 v147, s100, v149
	v_add_f32_e32 v149, v37, v133
	v_med3_f32 v149, v149, s6, v191
	ds_write_b128 v158, v[152:155] offset:16384
	v_lshlrev_b32_e32 v152, 16, v170
	v_and_b32_e32 v153, s34, v170
	v_med3_f32 v170, v157, s6, v191
	v_mul_f32_e32 v149, s100, v149
	v_exp_f32_e32 v157, v149
	v_mul_f32_e32 v149, s100, v170
	v_exp_f32_e32 v147, v147
	v_exp_f32_e32 v149, v149
	v_pk_add_f32 v[156:157], v[156:157], 1.0 op_sel_hi:[1,0]
	v_lshlrev_b32_e32 v154, 16, v171
	v_add_f32_e32 v147, 1.0, v147
	v_add_f32_e32 v149, 1.0, v149
	v_and_b32_e32 v155, s34, v171
	v_mul_f32_e32 v170, v156, v147
	v_mul_f32_e32 v171, v157, v149
	v_rcp_f32_e32 v170, v170
	v_rcp_f32_e32 v171, v171
	v_mul_f32_e32 v147, v147, v170
	v_pk_mul_f32 v[156:157], v[156:157], v[170:171]
	v_mul_f32_e32 v149, v149, v171
	v_pk_mul_f32 v[152:153], v[156:157], v[152:153]
	v_add_f32_e32 v156, v35, v131
	v_cvt_pk_f16_f32 v170, v152, v153
	v_add_f32_e32 v153, v34, v130
	v_med3_f32 v153, v153, s6, v191
	v_mul_f32_e32 v153, s100, v153
	v_exp_f32_e32 v153, v153
	v_add_f32_e32 v152, v38, v134
	v_med3_f32 v152, v152, s6, v191
	v_mul_f32_e32 v152, s100, v152
	v_add_f32_e32 v157, 1.0, v153
	v_add_f32_e32 v153, v39, v135
	v_med3_f32 v153, v153, s6, v191
	v_med3_f32 v156, v156, s6, v191
	v_mul_f32_e32 v153, s100, v153
	v_exp_f32_e32 v152, v152
	v_exp_f32_e32 v153, v153
	v_mul_f32_e32 v156, s100, v156
	v_exp_f32_e32 v156, v156
	v_mul_f32_e32 v147, s101, v147
	v_pk_add_f32 v[152:153], v[152:153], 1.0 op_sel_hi:[1,0]
	v_rndne_f32_e32 v147, v147
	v_add_f32_e32 v171, 1.0, v156
	v_mul_f32_e32 v156, v152, v157
	v_rcp_f32_e32 v156, v156
	v_mul_f32_e32 v149, s101, v149
	v_rndne_f32_e32 v149, v149
	v_mul_f32_e32 v157, v157, v156
	v_mul_f32_e32 v157, s101, v157
	v_rndne_f32_e32 v157, v157
	v_cvt_f16_f32_e32 v172, v157
	v_mul_f32_e32 v157, v153, v171
	v_rcp_f32_e32 v157, v157
	v_cvt_f16_f32_e32 v147, v147
	v_cvt_f16_f32_e32 v149, v149
	v_pk_mul_f32 v[152:153], v[152:153], v[156:157]
	s_nop 0
	v_pk_mul_f32 v[152:153], v[152:153], v[154:155]
	s_nop 0
	v_cvt_pk_f16_f32 v152, v152, v153
	v_mul_f32_e32 v153, v171, v157
	v_mul_f32_e32 v153, s101, v153
	v_rndne_f32_e32 v153, v153
	v_cvt_f16_f32_e32 v153, v153
	v_pack_b32_f16 v154, v172, v152
	v_add_f32_e32 v157, v17, v129
	v_add_f32_e32 v129, v1, v129
	v_bfi_b32 v155, s98, v153, v152
	v_pack_b32_f16 v152, v147, v170
	v_add_f32_e32 v147, v20, v132
	v_bfi_b32 v153, s98, v149, v170
	v_med3_f32 v147, v147, s6, v191
	v_add_f32_e32 v149, v16, v128
	v_med3_f32 v149, v149, s6, v191
	v_mul_f32_e32 v147, s100, v147
	v_exp_f32_e32 v156, v147
	v_mul_f32_e32 v147, s100, v149
	v_add_f32_e32 v149, v21, v133
	v_med3_f32 v149, v149, s6, v191
	ds_write_b128 v158, v[152:155] offset:20480
	v_lshlrev_b32_e32 v152, 16, v168
	v_and_b32_e32 v153, s34, v168
	v_med3_f32 v168, v157, s6, v191
	v_mul_f32_e32 v149, s100, v149
	v_exp_f32_e32 v157, v149
	v_mul_f32_e32 v149, s100, v168
	v_exp_f32_e32 v147, v147
	v_exp_f32_e32 v149, v149
	v_pk_add_f32 v[156:157], v[156:157], 1.0 op_sel_hi:[1,0]
	v_lshlrev_b32_e32 v154, 16, v169
	v_add_f32_e32 v147, 1.0, v147
	v_add_f32_e32 v149, 1.0, v149
	v_and_b32_e32 v155, s34, v169
	v_mul_f32_e32 v168, v156, v147
	v_mul_f32_e32 v169, v157, v149
	v_rcp_f32_e32 v168, v168
	v_rcp_f32_e32 v169, v169
	v_add_f32_e32 v132, v4, v132
	v_add_f32_e32 v128, v0, v128
	v_mul_f32_e32 v147, v147, v168
	v_pk_mul_f32 v[156:157], v[156:157], v[168:169]
	v_mul_f32_e32 v149, v149, v169
	v_pk_mul_f32 v[152:153], v[156:157], v[152:153]
	v_add_f32_e32 v156, v19, v131
	v_cvt_pk_f16_f32 v168, v152, v153
	v_add_f32_e32 v153, v18, v130
	v_med3_f32 v153, v153, s6, v191
	v_mul_f32_e32 v153, s100, v153
	v_exp_f32_e32 v153, v153
	v_add_f32_e32 v152, v22, v134
	v_med3_f32 v152, v152, s6, v191
	v_mul_f32_e32 v152, s100, v152
	v_add_f32_e32 v157, 1.0, v153
	v_add_f32_e32 v153, v23, v135
	v_med3_f32 v153, v153, s6, v191
	v_med3_f32 v156, v156, s6, v191
	v_mul_f32_e32 v153, s100, v153
	v_exp_f32_e32 v152, v152
	v_exp_f32_e32 v153, v153
	v_mul_f32_e32 v156, s100, v156
	v_exp_f32_e32 v156, v156
	v_mul_f32_e32 v147, s101, v147
	v_pk_add_f32 v[152:153], v[152:153], 1.0 op_sel_hi:[1,0]
	v_rndne_f32_e32 v147, v147
	v_add_f32_e32 v169, 1.0, v156
	v_mul_f32_e32 v156, v152, v157
	v_rcp_f32_e32 v156, v156
	v_cvt_f16_f32_e32 v147, v147
	v_med3_f32 v132, v132, s6, v191
	v_mul_f32_e32 v157, v157, v156
	v_mul_f32_e32 v157, s101, v157
	v_rndne_f32_e32 v157, v157
	v_cvt_f16_f32_e32 v170, v157
	v_mul_f32_e32 v157, v153, v169
	v_rcp_f32_e32 v157, v157
	v_mul_f32_e32 v149, s101, v149
	v_rndne_f32_e32 v149, v149
	v_pk_mul_f32 v[152:153], v[152:153], v[156:157]
	v_cvt_f16_f32_e32 v149, v149
	v_pk_mul_f32 v[152:153], v[152:153], v[154:155]
	s_nop 0
	v_cvt_pk_f16_f32 v152, v152, v153
	v_mul_f32_e32 v153, v169, v157
	v_mul_f32_e32 v153, s101, v153
	v_rndne_f32_e32 v153, v153
	v_cvt_f16_f32_e32 v153, v153
	v_pack_b32_f16 v154, v170, v152
	v_bfi_b32 v155, s98, v153, v152
	v_pack_b32_f16 v152, v147, v168
	v_med3_f32 v147, v128, s6, v191
	v_mul_f32_e32 v128, s100, v132
	v_mul_f32_e32 v132, s100, v147
	v_exp_f32_e32 v132, v132
	v_exp_f32_e32 v128, v128
	v_bfi_b32 v153, s98, v149, v168
	ds_write_b128 v158, v[152:155] offset:24576
	v_add_f32_e32 v147, 1.0, v132
	v_add_f32_e32 v132, v5, v133
	v_med3_f32 v132, v132, s6, v191
	v_med3_f32 v133, v129, s6, v191
	v_mul_f32_e32 v129, s100, v132
	v_exp_f32_e32 v129, v129
	v_mul_f32_e32 v132, s100, v133
	v_exp_f32_e32 v132, v132
	v_lshlrev_b32_e32 v152, 16, v166
	v_pk_add_f32 v[128:129], v[128:129], 1.0 op_sel_hi:[1,0]
	v_and_b32_e32 v153, s34, v166
	v_add_f32_e32 v149, 1.0, v132
	v_mul_f32_e32 v132, v128, v147
	v_rcp_f32_e32 v132, v132
	v_lshlrev_b32_e32 v154, 16, v167
	v_and_b32_e32 v155, s34, v167
	v_mul_f32_e32 v133, v147, v132
	v_mul_f32_e32 v133, s101, v133
	v_rndne_f32_e32 v133, v133
	v_cvt_f16_f32_e32 v147, v133
	v_mul_f32_e32 v133, v129, v149
	v_rcp_f32_e32 v133, v133
	s_nop 0
	v_pk_mul_f32 v[128:129], v[128:129], v[132:133]
	s_nop 0
	v_pk_mul_f32 v[128:129], v[128:129], v[152:153]
	s_nop 0
	v_cvt_pk_f16_f32 v132, v128, v129
	v_add_f32_e32 v129, v2, v130
	v_med3_f32 v129, v129, s6, v191
	v_mul_f32_e32 v129, s100, v129
	v_mul_f32_e32 v128, v149, v133
	v_exp_f32_e32 v129, v129
	v_mul_f32_e32 v128, s101, v128
	v_rndne_f32_e32 v128, v128
	v_cvt_f16_f32_e32 v133, v128
	v_add_f32_e32 v128, v6, v134
	v_add_f32_e32 v134, 1.0, v129
	v_add_f32_e32 v129, v7, v135
	v_med3_f32 v128, v128, s6, v191
	v_med3_f32 v129, v129, s6, v191
	v_add_f32_e32 v130, v3, v131
	v_mul_f32_e32 v128, s100, v128
	v_med3_f32 v130, v130, s6, v191
	v_mul_f32_e32 v129, s100, v129
	v_exp_f32_e32 v128, v128
	v_exp_f32_e32 v129, v129
	v_mul_f32_e32 v130, s100, v130
	v_exp_f32_e32 v130, v130
	v_pk_add_f32 v[128:129], v[128:129], 1.0 op_sel_hi:[1,0]
	v_add_f32_e32 v135, 1.0, v130
	v_mul_f32_e32 v130, v128, v134
	v_rcp_f32_e32 v130, v130
	s_nop 0
	v_mul_f32_e32 v131, v134, v130
	v_mul_f32_e32 v131, s101, v131
	v_rndne_f32_e32 v131, v131
	v_cvt_f16_f32_e32 v134, v131
	v_mul_f32_e32 v131, v129, v135
	v_rcp_f32_e32 v131, v131
	s_nop 0
	v_pk_mul_f32 v[128:129], v[128:129], v[130:131]
	s_nop 0
	v_pk_mul_f32 v[128:129], v[128:129], v[154:155]
	v_mov_b32_e32 v155, v164
	v_cvt_pk_f16_f32 v128, v128, v129
	v_mul_f32_e32 v129, v135, v131
	v_mul_f32_e32 v129, s101, v129
	v_rndne_f32_e32 v129, v129
	v_cvt_f16_f32_e32 v129, v129
	v_pack_b32_f16 v130, v134, v128
	v_ashrrev_i32_e32 v134, 3, v200
	v_bfi_b32 v131, s98, v129, v128
	v_bfi_b32 v129, s98, v133, v132
	v_pack_b32_f16 v128, v147, v132
	v_and_b32_e32 v147, 7, v200
	ds_write_b128 v158, v[128:131] offset:28672
	v_lshlrev_b32_e32 v129, 1, v147
	v_lshl_add_u32 v128, v134, 8, v192
	v_and_b32_e32 v130, 15, v134
	v_bitop3_b32 v131, v129, v134, 15 bitop3:0x78
	v_lshl_or_b32 v131, v131, 4, v128
	v_bitop3_b32 v129, v129, v130, 1 bitop3:0x36
	s_waitcnt lgkmcnt(0)
	s_barrier
	v_lshl_or_b32 v132, v129, 4, v128
	ds_read_b128 v[128:131], v131
	s_waitcnt lgkmcnt(0)
	v_and_b32_e32 v135, s34, v129
	v_cvt_f32_f16_e32 v149, v128
	v_cvt_f32_f16_e32 v129, v129
	v_and_b32_e32 v133, s34, v131
	v_cvt_f32_f16_e32 v152, v130
	v_cvt_f32_f16_e32 v131, v131
	v_cvt_u32_f32_e32 v149, v149
	v_cvt_u32_f32_e32 v129, v129
	v_cvt_u32_f32_sdwa v152, v152 dst_sel:WORD_1 dst_unused:UNUSED_PAD src0_sel:DWORD
	v_cvt_u32_f32_sdwa v131, v131 dst_sel:BYTE_3 dst_unused:UNUSED_PAD src0_sel:DWORD
	v_or_b32_sdwa v128, v135, v128 dst_sel:DWORD dst_unused:UNUSED_PAD src0_sel:DWORD src1_sel:WORD_1
	v_lshl_or_b32 v129, v129, 8, v149
	v_or3_b32 v152, v129, v152, v131
	v_or_b32_sdwa v129, v133, v130 dst_sel:DWORD dst_unused:UNUSED_PAD src0_sel:DWORD src1_sel:WORD_1
	ds_read_b128 v[130:133], v132
	s_waitcnt lgkmcnt(0)
	v_and_b32_e32 v149, s34, v131
	v_cvt_f32_f16_e32 v153, v130
	v_cvt_f32_f16_e32 v131, v131
	v_and_b32_e32 v135, s34, v133
	v_cvt_f32_f16_e32 v154, v132
	v_cvt_f32_f16_e32 v133, v133
	v_cvt_u32_f32_e32 v153, v153
	v_cvt_u32_f32_e32 v131, v131
	v_cvt_u32_f32_sdwa v154, v154 dst_sel:WORD_1 dst_unused:UNUSED_PAD src0_sel:DWORD
	v_cvt_u32_f32_sdwa v133, v133 dst_sel:BYTE_3 dst_unused:UNUSED_PAD src0_sel:DWORD
	v_or_b32_sdwa v130, v149, v130 dst_sel:DWORD dst_unused:UNUSED_PAD src0_sel:DWORD src1_sel:WORD_1
	v_lshl_or_b32 v131, v131, 8, v153
	v_or3_b32 v153, v131, v154, v133
	v_or_b32_sdwa v131, v135, v132 dst_sel:DWORD dst_unused:UNUSED_PAD src0_sel:DWORD src1_sel:WORD_1
	v_ashrrev_i32_e32 v135, 31, v134
	v_lshlrev_b64 v[132:133], 10, v[134:135]
	v_lshl_add_u64 v[132:133], s[12:13], 0, v[132:133]
	v_lshlrev_b32_e32 v154, 3, v147
	v_lshl_add_u64 v[132:133], v[132:133], 0, v[154:155]
	global_store_dwordx2 v[132:133], v[152:153], off offset:64
	v_lshlrev_b32_e32 v132, 4, v147
	v_lshl_or_b32 v132, v134, 11, v132
	buffer_store_dwordx4 v[128:131], v132, s[8:11], 0 offen offset:128 sc1
	s_nop 1
	v_add_u32_e32 v128, v197, v199
	ds_read_b128 v[128:131], v128
	s_waitcnt lgkmcnt(0)
	v_and_b32_e32 v133, s34, v129
	v_cvt_f32_f16_e32 v134, v128
	v_cvt_f32_f16_e32 v129, v129
	v_and_b32_e32 v132, s34, v131
	v_cvt_f32_f16_e32 v135, v130
	v_cvt_f32_f16_e32 v131, v131
	v_cvt_u32_f32_e32 v134, v134
	v_cvt_u32_f32_e32 v129, v129
	v_cvt_u32_f32_sdwa v135, v135 dst_sel:WORD_1 dst_unused:UNUSED_PAD src0_sel:DWORD
	v_cvt_u32_f32_sdwa v131, v131 dst_sel:BYTE_3 dst_unused:UNUSED_PAD src0_sel:DWORD
	v_or_b32_sdwa v128, v133, v128 dst_sel:DWORD dst_unused:UNUSED_PAD src0_sel:DWORD src1_sel:WORD_1
	v_lshl_or_b32 v129, v129, 8, v134
	v_or3_b32 v134, v129, v135, v131
	v_or_b32_sdwa v129, v132, v130 dst_sel:DWORD dst_unused:UNUSED_PAD src0_sel:DWORD src1_sel:WORD_1
	v_add_u32_e32 v130, v197, v198
	ds_read_b128 v[130:133], v130
	s_waitcnt lgkmcnt(0)
	v_and_b32_e32 v149, s34, v131
	v_cvt_f32_f16_e32 v135, v130
	v_cvt_f32_f16_e32 v131, v131
	v_and_b32_e32 v147, s34, v133
	v_cvt_f32_f16_e32 v152, v132
	v_cvt_f32_f16_e32 v133, v133
	v_cvt_u32_f32_e32 v135, v135
	v_cvt_u32_f32_e32 v131, v131
	v_cvt_u32_f32_sdwa v152, v152 dst_sel:WORD_1 dst_unused:UNUSED_PAD src0_sel:DWORD
	v_cvt_u32_f32_sdwa v133, v133 dst_sel:BYTE_3 dst_unused:UNUSED_PAD src0_sel:DWORD
	v_or_b32_sdwa v130, v149, v130 dst_sel:DWORD dst_unused:UNUSED_PAD src0_sel:DWORD src1_sel:WORD_1
	v_lshl_or_b32 v131, v131, 8, v135
	v_or3_b32 v135, v131, v152, v133
	v_or_b32_sdwa v131, v147, v132 dst_sel:DWORD dst_unused:UNUSED_PAD src0_sel:DWORD src1_sel:WORD_1
	global_store_dwordx2 v[150:151], v[134:135], off offset:64
	buffer_store_dwordx4 v[128:131], v196, s[8:11], 0 offen offset:128 sc1
	s_and_saveexec_b64 s[4:5], vcc
	s_xor_b64 s[4:5], exec, s[4:5]
	s_cbranch_execz .LBB0_465
	v_lshl_add_u32 v129, v148, 8, v192
	v_bitop3_b32 v128, v148, v160, 15 bitop3:0x6c
	v_lshl_or_b32 v130, v128, 4, v129
	v_or_b32_e32 v128, 1, v160
	v_bitop3_b32 v131, v148, v128, 15 bitop3:0x6c
	v_lshl_or_b32 v129, v131, 4, v129
	ds_read_b128 v[130:133], v130
	v_ashrrev_i32_e32 v149, 31, v148
	v_mov_b32_e32 v141, v164
	v_ashrrev_i32_e32 v147, 31, v146
	v_ashrrev_i32_e32 v145, 31, v144
	s_waitcnt lgkmcnt(0)
	v_and_b32_e32 v135, s34, v131
	v_cvt_f32_f16_e32 v136, v130
	v_cvt_f32_f16_e32 v131, v131
	v_and_b32_e32 v134, s34, v133
	v_cvt_f32_f16_e32 v137, v132
	v_cvt_f32_f16_e32 v133, v133
	v_cvt_u32_f32_e32 v136, v136
	v_cvt_u32_f32_e32 v131, v131
	v_cvt_u32_f32_sdwa v137, v137 dst_sel:WORD_1 dst_unused:UNUSED_PAD src0_sel:DWORD
	v_cvt_u32_f32_sdwa v133, v133 dst_sel:BYTE_3 dst_unused:UNUSED_PAD src0_sel:DWORD
	v_or_b32_sdwa v130, v135, v130 dst_sel:DWORD dst_unused:UNUSED_PAD src0_sel:DWORD src1_sel:WORD_1
	v_lshl_or_b32 v131, v131, 8, v136
	v_ashrrev_i32_e32 v143, 31, v142
	v_or3_b32 v136, v131, v137, v133
	v_or_b32_sdwa v131, v134, v132 dst_sel:DWORD dst_unused:UNUSED_PAD src0_sel:DWORD src1_sel:WORD_1
	ds_read_b128 v[132:135], v129
	s_waitcnt lgkmcnt(0)
	v_and_b32_e32 v138, s34, v133
	v_cvt_f32_f16_e32 v137, v132
	v_cvt_f32_f16_e32 v133, v133
	v_and_b32_e32 v129, s34, v135
	v_cvt_f32_f16_e32 v139, v134
	v_cvt_f32_f16_e32 v135, v135
	v_cvt_u32_f32_e32 v137, v137
	v_cvt_u32_f32_e32 v133, v133
	v_cvt_u32_f32_sdwa v139, v139 dst_sel:WORD_1 dst_unused:UNUSED_PAD src0_sel:DWORD
	v_cvt_u32_f32_sdwa v135, v135 dst_sel:BYTE_3 dst_unused:UNUSED_PAD src0_sel:DWORD
	v_or_b32_sdwa v132, v138, v132 dst_sel:DWORD dst_unused:UNUSED_PAD src0_sel:DWORD src1_sel:WORD_1
	v_lshl_or_b32 v133, v133, 8, v137
	v_or3_b32 v137, v133, v139, v135
	v_or_b32_sdwa v133, v129, v134 dst_sel:DWORD dst_unused:UNUSED_PAD src0_sel:DWORD src1_sel:WORD_1
	v_lshlrev_b64 v[134:135], 10, v[148:149]
	v_lshl_add_u64 v[134:135], s[12:13], 0, v[134:135]
	v_lshl_add_u64 v[134:135], v[134:135], 0, v[140:141]
	v_lshl_or_b32 v129, v148, 11, v159
	global_store_dwordx2 v[134:135], v[136:137], off offset:64
	buffer_store_dwordx4 v[130:133], v129, s[8:11], 0 offen offset:128 sc1
	v_lshl_add_u32 v129, v146, 8, v192
	s_nop 0
	v_bitop3_b32 v130, v146, v160, 15 bitop3:0x6c
	v_lshl_or_b32 v130, v130, 4, v129
	v_bitop3_b32 v131, v146, v128, 15 bitop3:0x6c
	v_lshl_or_b32 v129, v131, 4, v129
	ds_read_b128 v[130:133], v130
	s_waitcnt lgkmcnt(0)
	v_and_b32_e32 v135, s34, v131
	v_cvt_f32_f16_e32 v136, v130
	v_cvt_f32_f16_e32 v131, v131
	v_and_b32_e32 v134, s34, v133
	v_cvt_f32_f16_e32 v137, v132
	v_cvt_f32_f16_e32 v133, v133
	v_cvt_u32_f32_e32 v136, v136
	v_cvt_u32_f32_e32 v131, v131
	v_cvt_u32_f32_sdwa v137, v137 dst_sel:WORD_1 dst_unused:UNUSED_PAD src0_sel:DWORD
	v_cvt_u32_f32_sdwa v133, v133 dst_sel:BYTE_3 dst_unused:UNUSED_PAD src0_sel:DWORD
	v_or_b32_sdwa v130, v135, v130 dst_sel:DWORD dst_unused:UNUSED_PAD src0_sel:DWORD src1_sel:WORD_1
	v_lshl_or_b32 v131, v131, 8, v136
	v_or3_b32 v136, v131, v137, v133
	v_or_b32_sdwa v131, v134, v132 dst_sel:DWORD dst_unused:UNUSED_PAD src0_sel:DWORD src1_sel:WORD_1
	ds_read_b128 v[132:135], v129
	s_waitcnt lgkmcnt(0)
	v_and_b32_e32 v138, s34, v133
	v_cvt_f32_f16_e32 v137, v132
	v_cvt_f32_f16_e32 v133, v133
	v_and_b32_e32 v129, s34, v135
	v_cvt_f32_f16_e32 v139, v134
	v_cvt_f32_f16_e32 v135, v135
	v_cvt_u32_f32_e32 v137, v137
	v_cvt_u32_f32_e32 v133, v133
	v_cvt_u32_f32_sdwa v139, v139 dst_sel:WORD_1 dst_unused:UNUSED_PAD src0_sel:DWORD
	v_cvt_u32_f32_sdwa v135, v135 dst_sel:BYTE_3 dst_unused:UNUSED_PAD src0_sel:DWORD
	v_or_b32_sdwa v132, v138, v132 dst_sel:DWORD dst_unused:UNUSED_PAD src0_sel:DWORD src1_sel:WORD_1
	v_lshl_or_b32 v133, v133, 8, v137
	v_or3_b32 v137, v133, v139, v135
	v_or_b32_sdwa v133, v129, v134 dst_sel:DWORD dst_unused:UNUSED_PAD src0_sel:DWORD src1_sel:WORD_1
	v_lshlrev_b64 v[134:135], 10, v[146:147]
	v_lshl_add_u64 v[134:135], s[12:13], 0, v[134:135]
	v_lshl_add_u64 v[134:135], v[134:135], 0, v[140:141]
	v_lshl_or_b32 v129, v146, 11, v159
	global_store_dwordx2 v[134:135], v[136:137], off offset:64
	buffer_store_dwordx4 v[130:133], v129, s[8:11], 0 offen offset:128 sc1
	v_lshl_add_u32 v129, v144, 8, v192
	s_nop 0
	v_bitop3_b32 v130, v144, v160, 15 bitop3:0x6c
	v_lshl_or_b32 v130, v130, 4, v129
	v_bitop3_b32 v131, v144, v128, 15 bitop3:0x6c
	v_lshl_or_b32 v129, v131, 4, v129
	ds_read_b128 v[130:133], v130
	v_bitop3_b32 v128, v142, v128, 15 bitop3:0x6c
	s_waitcnt lgkmcnt(0)
	v_and_b32_e32 v135, s34, v131
	v_cvt_f32_f16_e32 v136, v130
	v_cvt_f32_f16_e32 v131, v131
	v_and_b32_e32 v134, s34, v133
	v_cvt_f32_f16_e32 v137, v132
	v_cvt_f32_f16_e32 v133, v133
	v_cvt_u32_f32_e32 v136, v136
	v_cvt_u32_f32_e32 v131, v131
	v_cvt_u32_f32_sdwa v137, v137 dst_sel:WORD_1 dst_unused:UNUSED_PAD src0_sel:DWORD
	v_cvt_u32_f32_sdwa v133, v133 dst_sel:BYTE_3 dst_unused:UNUSED_PAD src0_sel:DWORD
	v_or_b32_sdwa v130, v135, v130 dst_sel:DWORD dst_unused:UNUSED_PAD src0_sel:DWORD src1_sel:WORD_1
	v_lshl_or_b32 v131, v131, 8, v136
	v_or3_b32 v136, v131, v137, v133
	v_or_b32_sdwa v131, v134, v132 dst_sel:DWORD dst_unused:UNUSED_PAD src0_sel:DWORD src1_sel:WORD_1
	ds_read_b128 v[132:135], v129
	s_waitcnt lgkmcnt(0)
	v_and_b32_e32 v138, s34, v133
	v_cvt_f32_f16_e32 v137, v132
	v_cvt_f32_f16_e32 v133, v133
	v_and_b32_e32 v129, s34, v135
	v_cvt_f32_f16_e32 v139, v134
	v_cvt_f32_f16_e32 v135, v135
	v_cvt_u32_f32_e32 v137, v137
	v_cvt_u32_f32_e32 v133, v133
	v_cvt_u32_f32_sdwa v139, v139 dst_sel:WORD_1 dst_unused:UNUSED_PAD src0_sel:DWORD
	v_cvt_u32_f32_sdwa v135, v135 dst_sel:BYTE_3 dst_unused:UNUSED_PAD src0_sel:DWORD
	v_or_b32_sdwa v132, v138, v132 dst_sel:DWORD dst_unused:UNUSED_PAD src0_sel:DWORD src1_sel:WORD_1
	v_lshl_or_b32 v133, v133, 8, v137
	v_or3_b32 v137, v133, v139, v135
	v_or_b32_sdwa v133, v129, v134 dst_sel:DWORD dst_unused:UNUSED_PAD src0_sel:DWORD src1_sel:WORD_1
	v_lshlrev_b64 v[134:135], 10, v[144:145]
	v_lshl_add_u64 v[134:135], s[12:13], 0, v[134:135]
	v_lshl_add_u64 v[134:135], v[134:135], 0, v[140:141]
	v_lshl_or_b32 v129, v144, 11, v159
	global_store_dwordx2 v[134:135], v[136:137], off offset:64
	buffer_store_dwordx4 v[130:133], v129, s[8:11], 0 offen offset:128 sc1
	v_lshl_add_u32 v129, v142, 8, v192
	s_nop 0
	v_bitop3_b32 v130, v142, v160, 15 bitop3:0x6c
	v_lshl_or_b32 v130, v130, 4, v129
	v_lshl_or_b32 v132, v128, 4, v129
	ds_read_b128 v[128:131], v130
	s_waitcnt lgkmcnt(0)
	v_and_b32_e32 v135, s34, v129
	v_cvt_f32_f16_e32 v134, v128
	v_cvt_f32_f16_e32 v129, v129
	v_and_b32_e32 v133, s34, v131
	v_cvt_f32_f16_e32 v136, v130
	v_cvt_f32_f16_e32 v131, v131
	v_cvt_u32_f32_e32 v134, v134
	v_cvt_u32_f32_e32 v129, v129
	v_cvt_u32_f32_sdwa v136, v136 dst_sel:WORD_1 dst_unused:UNUSED_PAD src0_sel:DWORD
	v_cvt_u32_f32_sdwa v131, v131 dst_sel:BYTE_3 dst_unused:UNUSED_PAD src0_sel:DWORD
	v_or_b32_sdwa v128, v135, v128 dst_sel:DWORD dst_unused:UNUSED_PAD src0_sel:DWORD src1_sel:WORD_1
	v_lshl_or_b32 v129, v129, 8, v134
	v_or3_b32 v134, v129, v136, v131
	v_or_b32_sdwa v129, v133, v130 dst_sel:DWORD dst_unused:UNUSED_PAD src0_sel:DWORD src1_sel:WORD_1
	ds_read_b128 v[130:133], v132
	s_waitcnt lgkmcnt(0)
	v_and_b32_e32 v137, s34, v131
	v_cvt_f32_f16_e32 v135, v130
	v_cvt_f32_f16_e32 v131, v131
	v_and_b32_e32 v136, s34, v133
	v_cvt_f32_f16_e32 v138, v132
	v_cvt_f32_f16_e32 v133, v133
	v_cvt_u32_f32_e32 v135, v135
	v_cvt_u32_f32_e32 v131, v131
	v_cvt_u32_f32_sdwa v138, v138 dst_sel:WORD_1 dst_unused:UNUSED_PAD src0_sel:DWORD
	v_cvt_u32_f32_sdwa v133, v133 dst_sel:BYTE_3 dst_unused:UNUSED_PAD src0_sel:DWORD
	v_or_b32_sdwa v130, v137, v130 dst_sel:DWORD dst_unused:UNUSED_PAD src0_sel:DWORD src1_sel:WORD_1
	v_lshl_or_b32 v131, v131, 8, v135
	v_or3_b32 v135, v131, v138, v133
	v_or_b32_sdwa v131, v136, v132 dst_sel:DWORD dst_unused:UNUSED_PAD src0_sel:DWORD src1_sel:WORD_1
	v_lshlrev_b64 v[132:133], 10, v[142:143]
	v_lshl_add_u64 v[132:133], s[12:13], 0, v[132:133]
	v_lshl_add_u64 v[132:133], v[132:133], 0, v[140:141]
	global_store_dwordx2 v[132:133], v[134:135], off offset:64
	v_lshl_or_b32 v132, v142, 11, v159
	buffer_store_dwordx4 v[128:131], v132, s[8:11], 0 offen offset:128 sc1

; #define NT_LOAD(p) __builtin_nontemporal_load(p)
; __device__ __forceinline__ int opaque_tid() { int t = threadIdx.x; asm volatile("" : "+v"(t)); return t; }
; __device__ __forceinline__ void row_load_bf(const bf16* __restrict__ p, int lane, float (&v)[16]) {
; #pragma unroll
;   for (int i = 0; i < 4; ++i) { u32x2_nt t = NT_LOAD((const u32x2_nt*)p + (lane + 64 * i)); v[i * 4] = bflo(t[0]); v[i * 4 + 1] = bfhi(t[0]); v[i * 4 + 2] = bflo(t[1]); v[i * 4 + 3] = bfhi(t[1]); }
; template <bool WITH_H>
; __device__ void rows_resid(const bf16* __restrict__ Y, const float* __restrict__ xsrc, float* __restrict__ xdst, const float* __restrict__ gpost,
;                            bf16* __restrict__ Hout, const float* __restrict__ gpre, int nrows) {
;   const int tid_ = opaque_tid(); const int lane = tid_ & 63, wid = tid_ >> 6;
;   const int stride = gridDim.x * 8;
;   int r = blockIdx.x * 8 + wid;
;   float y[16], x[16];
;   if (r < nrows) { row_load_bf(Y + (size_t)r * D, lane, y); row_load(xsrc + (size_t)r * D, lane, x); }
;   while (r < nrows) {
;     const int rn = r + stride;
;     float yn[16], xn[16];
;     if (rn < nrows) { row_load_bf(Y + (size_t)rn * D, lane, yn); row_load(xsrc + (size_t)rn * D, lane, xn); }
;     float rs = row_rs(y, lane);
; #pragma unroll
;     for (int i = 0; i < 4; ++i) { float4 gg = ((const float4*)gpost)[lane + 64 * i];
;       x[i * 4] += y[i * 4] * rs * gg.x; x[i * 4 + 1] += y[i * 4 + 1] * rs * gg.y; x[i * 4 + 2] += y[i * 4 + 2] * rs * gg.z; x[i * 4 + 3] += y[i * 4 + 3] * rs * gg.w;
.LBB0_513:
	s_mov_b32 s100, 0xffff0000
	s_movk_i32 s12, 0x4000
	v_ashrrev_i32_e32 v32, 6, v163
	v_add_u32_e32 v48, s88, v32
	v_cmp_gt_i32_e32 vcc, s12, v48
	s_and_saveexec_b64 s[2:3], vcc
	s_cbranch_execz .LBB0_518
	s_load_dwordx2 s[2:3], s[0:1], 0xa0
	s_load_dwordx4 s[8:11], s[0:1], 0xb8
	v_ashrrev_i32_e32 v49, 31, v48
	v_and_b32_e32 v33, 63, v163
	v_lshlrev_b64 v[0:1], 11, v[48:49]
	v_lshlrev_b32_e32 v34, 3, v33
	s_waitcnt lgkmcnt(0)
	v_lshl_add_u64 v[0:1], s[10:11], 0, v[0:1]
	v_mov_b32_e32 v35, 0
	s_add_u32 s0, s2, 0x3000
	v_lshl_add_u64 v[0:1], v[0:1], 0, v[34:35]
	s_mov_b64 s[4:5], 0x9a00000
	s_mov_b32 s1, 0x9a00000
	v_lshl_add_u64 v[2:3], v[0:1], 0, s[4:5]
	v_add_co_u32_e32 v0, vcc, s1, v0
	s_addc_u32 s1, s3, 0
	s_nop 0
	v_addc_co_u32_e32 v1, vcc, 0, v1, vcc
	s_add_u32 s4, s8, 0xc000000
	global_load_dwordx2 v[36:37], v[0:1], off nt
	global_load_dwordx2 v[38:39], v[2:3], off offset:512 nt
	global_load_dwordx2 v[40:41], v[2:3], off offset:1024 nt
	global_load_dwordx2 v[42:43], v[2:3], off offset:1536 nt
	s_addc_u32 s5, s9, 0
	v_lshlrev_b64 v[0:1], 12, v[48:49]
	v_lshl_add_u64 v[0:1], s[4:5], 0, v[0:1]
	v_lshlrev_b32_e32 v50, 4, v33
	v_mov_b32_e32 v51, v35
	v_lshl_add_u64 v[44:45], v[0:1], 0, v[50:51]
	v_or_b32_e32 v16, 0x400, v50
	v_or_b32_e32 v17, 0x800, v50
	global_load_dwordx4 v[0:3], v[44:45], off nt
	global_load_dwordx4 v[4:7], v[44:45], off offset:1024 nt
	global_load_dwordx4 v[8:11], v16, s[0:1]
	global_load_dwordx4 v[12:15], v17, s[0:1]
	v_or_b32_e32 v46, 0xc00, v50
	global_load_dwordx4 v[16:19], v50, s[0:1]
	global_load_dwordx4 v[20:23], v46, s[0:1]
	global_load_dwordx4 v[24:27], v[44:45], off offset:2048 nt
	global_load_dwordx4 v[28:31], v[44:45], off offset:3072 nt
	v_readlane_b32 s0, v224, 33
	v_lshlrev_b32_e32 v44, 2, v33
	v_xor_b32_e32 v49, 0x80, v44
	v_lshl_add_u32 v52, v32, 12, s0
	v_add_u32_e32 v32, s24, v48
	v_ashrrev_i32_e32 v33, 31, v32
	v_xor_b32_e32 v90, 64, v44
	v_xor_b32_e32 v91, 32, v44
	v_xor_b32_e32 v92, 16, v44
	v_xor_b32_e32 v93, 8, v44
	v_xor_b32_e32 v94, 4, v44
	v_lshlrev_b64 v[44:45], 12, v[32:33]
	v_lshlrev_b64 v[32:33], 11, v[32:33]
	v_or_b32_e32 v32, v32, v34
	s_mov_b64 s[0:1], 0x9a00600
	v_lshl_add_u64 v[32:33], s[10:11], 0, v[32:33]
	s_mov_b32 s7, 0x27000
	s_brev_b32 s6, -2
	s_mov_b64 s[2:3], 0
	v_mov_b32_e32 v53, v35
	v_lshl_add_u64 v[54:55], s[8:9], 0, v[44:45]
	v_lshl_add_u64 v[56:57], v[32:33], 0, s[0:1]
	s_and_b32 s5, s5, 0xffff
	s_movk_i32 s10, 0x3fff
	s_brev_b32 s11, 48
	v_mov_b32_e32 v95, 0x358637bd
	s_waitcnt vmcnt(11)
	v_lshlrev_b32_e32 v70, 16, v36
	v_and_b32_e32 v71, s100, v36
	v_lshlrev_b32_e32 v72, 16, v37
	s_waitcnt vmcnt(8)
	v_and_b32_e32 v58, s100, v43
	v_lshlrev_b32_e32 v59, 16, v43
	v_and_b32_e32 v73, s100, v37
	v_lshlrev_b32_e32 v66, 16, v38
	v_and_b32_e32 v67, s100, v38
	v_lshlrev_b32_e32 v68, 16, v39
	v_and_b32_e32 v69, s100, v39
	v_lshlrev_b32_e32 v62, 16, v40
	v_and_b32_e32 v63, s100, v40
	v_lshlrev_b32_e32 v64, 16, v41
	v_and_b32_e32 v65, s100, v41
	v_lshlrev_b32_e32 v60, 16, v42
	v_and_b32_e32 v61, s100, v42
	s_branch .LBB0_516

; #define NT_LOAD(p) __builtin_nontemporal_load(p)
; __device__ __forceinline__ void row_load_bf(const bf16* __restrict__ p, int lane, float (&v)[16]) {
; #pragma unroll
;   for (int i = 0; i < 4; ++i) { u32x2_nt t = NT_LOAD((const u32x2_nt*)p + (lane + 64 * i)); v[i * 4] = bflo(t[0]); v[i * 4 + 1] = bfhi(t[0]); v[i * 4 + 2] = bflo(t[1]); v[i * 4 + 3] = bfhi(t[1]); }
; template <bool WITH_H>
; __device__ void rows_resid(const bf16* __restrict__ Y, const float* __restrict__ xsrc, float* __restrict__ xdst, const float* __restrict__ gpost,
;                            bf16* __restrict__ Hout, const float* __restrict__ gpre, int nrows) {
;     ...
;   while (r < nrows) {
;     const int rn = r + stride;
;     float yn[16], xn[16];
;     if (rn < nrows) { row_load_bf(Y + (size_t)rn * D, lane, yn); row_load(xsrc + (size_t)rn * D, lane, xn); }
.LBB0_516:
	s_mov_b32 s100, 0xffff0000
	v_add_u32_e32 v48, s24, v48
	v_cmp_gt_i32_e64 s[0:1], s12, v48
	v_cmp_lt_i32_e32 vcc, s10, v48
	s_and_saveexec_b64 s[8:9], s[0:1]
	s_cbranch_execz .LBB0_515
	v_lshl_add_u64 v[32:33], v[54:55], 0, v[50:51]
	v_add_co_u32_e64 v74, s[0:1], s11, v32
	global_load_dwordx2 v[76:77], v[56:57], off offset:-1536 nt
	global_load_dwordx2 v[80:81], v[56:57], off offset:-1024 nt
	global_load_dwordx2 v[82:83], v[56:57], off offset:-512 nt
	global_load_dwordx2 v[96:97], v[56:57], off nt
	v_addc_co_u32_e64 v75, s[0:1], 0, v33, s[0:1]
	global_load_dwordx4 v[32:35], v[74:75], off nt
	global_load_dwordx4 v[36:39], v[74:75], off offset:1024 nt
	global_load_dwordx4 v[40:43], v[74:75], off offset:2048 nt
	global_load_dwordx4 v[44:47], v[74:75], off offset:3072 nt
	s_waitcnt vmcnt(7)
	v_lshlrev_b32_e32 v74, 16, v76
	v_and_b32_e32 v75, s100, v76
	v_lshlrev_b32_e32 v76, 16, v77
	v_and_b32_e32 v77, s100, v77
	s_waitcnt vmcnt(6)
	v_lshlrev_b32_e32 v78, 16, v80
	v_and_b32_e32 v79, s100, v80
	v_lshlrev_b32_e32 v80, 16, v81
	v_and_b32_e32 v81, s100, v81
	s_waitcnt vmcnt(5)
	v_lshlrev_b32_e32 v84, 16, v82
	v_and_b32_e32 v85, s100, v82
	v_lshlrev_b32_e32 v86, 16, v83
	v_and_b32_e32 v87, s100, v83
	s_waitcnt vmcnt(4)
	v_lshlrev_b32_e32 v88, 16, v96
	v_and_b32_e32 v89, s100, v96
	v_and_b32_e32 v82, s100, v97
	v_lshlrev_b32_e32 v83, 16, v97
	s_branch .LBB0_515
